# GEMM K-loops: s_setprio flips moved outside the barrier-to-first-MFMA handoff (setprio 1 before the barrier, setprio 0 after the closing barrier), plus redundant lgkmcnt(0) removed
# baseline (speedup 1.0000x reference)
; #define PG8_STAGE(bufoff, gbase, voff) do { _Pragma("unroll") for (int _i = 0; _i < 2; ++_i) \
;         __builtin_amdgcn_global_load_lds((const unsigned*)((const char*)(gbase) + (voff)[_i]), (PG8_LAS unsigned*)(lds + (bufoff) + ldsw + _i * 8192), 16, 0, 0); } while (0)
; #define PG8_LDA(dst, b, h) do { _Pragma("unroll") for (int m = 0; m < 4; ++m) _Pragma("unroll") for (int k = 0; k < 2; ++k) dst[m][k] = *(const PG8_LAS bf16x8*)(lds + PG8_SA(b, h) + aoff + m * 2048 + k * 1024); } while (0)
; #define PG8_LDB(dst, b, h) do { _Pragma("unroll") for (int n = 0; n < 2; ++n) _Pragma("unroll") for (int k = 0; k < 2; ++k) dst[n][k] = *(const PG8_LAS bf16x8*)(lds + PG8_SB(b, h) + boff + n * 2048 + k * 1024); } while (0)
; #define PG8_MMA(ai, bj, At, Bt) do { __builtin_amdgcn_s_setprio(1); _Pragma("unroll") for (int m = 0; m < 4; ++m) _Pragma("unroll") for (int n = 0; n < 2; ++n) _Pragma("unroll") for (int k = 0; k < 2; ++k) \
;         acc[ai][bj][m][n] = __builtin_amdgcn_mfma_f32_16x16x32_bf16(Bt[n][k], At[m][k], acc[ai][bj][m][n], 0, 0, 0); __builtin_amdgcn_s_setprio(0); } while (0)
; #define PG8_WAIT_V(n) asm volatile("s_waitcnt vmcnt(" #n ")" ::: "memory")
; #define PG8_BAR __builtin_amdgcn_s_barrier()
; template <class Epi, class Sched, bool ALIGN_EPI = false, bool SP2 = false>
; __device__ __forceinline__ void gemm_phase(PG8_LAS unsigned char* lds, const Gemm g, const Sched& S, const Epi& E, int tid_in) {
;     ...
;         for (int t = 0; t < nt; t += 2) {
;             const bool last = (t == nt - 2);
;             const char* a1 = cA + (size_t)(t + 1) * kstep;
;             const char* a2 = last ? nA : cA + (size_t)(t + 2) * kstep; const char* b2 = last ? nB : cB + (size_t)(t + 2) * kstep;
;             const char* a3 = a2 + kstep; const char* b3 = b2 + kstep;
;             if (last && has_next) S.a_ready(nxt);
;             if constexpr (SP2) {
;             PG8_LDB(B0, 0, 0); PG8_LDB(B1, 0, 1); PG8_SCHED; PG8_LDA(At, 0, 0); PG8_STAGE(PG8_SA(1, 1), a1 + hstep, voffA);
;             PG8_WAIT_V(8); PG8_WAIT_L(0); PG8_BAR; PG8_MMA(0, 0, At, B0); PG8_MMA(0, 1, At, B1); PG8_BAR; PG8_SCHED;
;             PG8_LDA(At, 0, 1); PG8_STAGE(PG8_SB(0, 0), b2, voffB); PG8_STAGE(PG8_SB(0, 1), b2 + hstep, voffB); PG8_STAGE(PG8_SA(0, 0), a2, voffA);
;             PG8_WAIT_V(8); PG8_WAIT_L(0); PG8_BAR; PG8_MMA(1, 0, At, B0); PG8_MMA(1, 1, At, B1); PG8_BAR; PG8_SCHED;
.LBB0_135:
	s_add_u32 s62, s64, 0xfff80080
	s_addc_u32 s63, s65, -1
	s_add_i32 s76, 0, 0x10000
	s_cmp_eq_u32 s75, 28
	s_cselect_b32 s95, s17, s63
	s_cselect_b32 s94, s43, s62
	v_add_u32_e32 v96, s76, v205
	s_cselect_b32 s93, s41, s74
	s_cselect_b32 s92, s72, s73
	s_add_i32 s77, 0, 0x14000
	ds_read_b128 v[130:133], v96
	ds_read_b128 v[134:137], v96 offset:1024
	ds_read_b128 v[138:141], v96 offset:2048
	ds_read_b128 v[142:145], v96 offset:3072
	v_add_u32_e32 v96, s77, v205
	ds_read_b128 v[146:149], v96
	ds_read_b128 v[150:153], v96 offset:1024
	ds_read_b128 v[154:157], v96 offset:2048
	ds_read_b128 v[158:161], v96 offset:3072
	v_lshl_add_u64 v[196:197], s[64:65], 0, v[180:181]
	s_add_i32 m0, s37, 0xc000
	ds_read_b128 v[162:165], v216
	ds_read_b128 v[184:187], v216 offset:1024
	ds_read_b128 v[188:191], v216 offset:2048
	ds_read_b128 v[192:195], v216 offset:3072
	ds_read_b128 v[218:221], v216 offset:4096
	ds_read_b128 v[222:225], v216 offset:5120
	ds_read_b128 v[226:229], v216 offset:6144
	ds_read_b128 v[230:233], v216 offset:7168
	global_load_lds_dwordx4 v[196:197], off
	v_lshl_add_u64 v[196:197], s[64:65], 0, v[182:183]
	s_add_i32 m0, s37, 0xe000
	s_nop 0
	global_load_lds_dwordx4 v[196:197], off
	s_waitcnt vmcnt(8)
	s_waitcnt lgkmcnt(0)
	s_setprio 1
	s_barrier
	v_mfma_f32_16x16x32_bf16 v[126:129], v[130:133], v[162:165], v[126:129]
	v_mfma_f32_16x16x32_bf16 v[122:125], v[138:141], v[162:165], v[122:125]
	v_mfma_f32_16x16x32_bf16 v[118:121], v[130:133], v[188:191], v[118:121]
	v_mfma_f32_16x16x32_bf16 v[114:117], v[138:141], v[188:191], v[114:117]
	v_mfma_f32_16x16x32_bf16 v[102:105], v[130:133], v[218:221], v[102:105]
	v_mfma_f32_16x16x32_bf16 v[98:101], v[138:141], v[218:221], v[98:101]
	v_mfma_f32_16x16x32_bf16 v[84:87], v[130:133], v[226:229], v[84:87]
	v_mfma_f32_16x16x32_bf16 v[80:83], v[138:141], v[226:229], v[80:83]
	v_mfma_f32_16x16x32_bf16 v[126:129], v[134:137], v[184:187], v[126:129]
	v_mfma_f32_16x16x32_bf16 v[122:125], v[142:145], v[184:187], v[122:125]
	v_mfma_f32_16x16x32_bf16 v[118:121], v[134:137], v[192:195], v[118:121]
	v_mfma_f32_16x16x32_bf16 v[114:117], v[142:145], v[192:195], v[114:117]
	v_mfma_f32_16x16x32_bf16 v[102:105], v[134:137], v[222:225], v[102:105]
	v_mfma_f32_16x16x32_bf16 v[98:101], v[142:145], v[222:225], v[98:101]
	v_mfma_f32_16x16x32_bf16 v[84:87], v[134:137], v[230:233], v[84:87]
	v_mfma_f32_16x16x32_bf16 v[80:83], v[142:145], v[230:233], v[80:83]
	s_setprio 0
	s_setprio 1
	v_mfma_f32_16x16x32_bf16 v[110:113], v[146:149], v[162:165], v[110:113]
	v_mfma_f32_16x16x32_bf16 v[106:109], v[154:157], v[162:165], v[106:109]
	v_mfma_f32_16x16x32_bf16 v[92:95], v[146:149], v[188:191], v[92:95]
	v_mfma_f32_16x16x32_bf16 v[88:91], v[154:157], v[188:191], v[88:91]
	v_mfma_f32_16x16x32_bf16 v[76:79], v[146:149], v[218:221], v[76:79]
	v_mfma_f32_16x16x32_bf16 v[72:75], v[154:157], v[218:221], v[72:75]
	v_mfma_f32_16x16x32_bf16 v[68:71], v[146:149], v[226:229], v[68:71]
	v_mfma_f32_16x16x32_bf16 v[64:67], v[154:157], v[226:229], v[64:67]
	v_mfma_f32_16x16x32_bf16 v[110:113], v[150:153], v[184:187], v[110:113]
	v_mfma_f32_16x16x32_bf16 v[106:109], v[158:161], v[184:187], v[106:109]
	v_mfma_f32_16x16x32_bf16 v[92:95], v[150:153], v[192:195], v[92:95]
	v_mfma_f32_16x16x32_bf16 v[88:91], v[158:161], v[192:195], v[88:91]
	v_mfma_f32_16x16x32_bf16 v[76:79], v[150:153], v[222:225], v[76:79]
	v_mfma_f32_16x16x32_bf16 v[72:75], v[158:161], v[222:225], v[72:75]
	v_mfma_f32_16x16x32_bf16 v[68:71], v[150:153], v[230:233], v[68:71]
	v_mfma_f32_16x16x32_bf16 v[64:67], v[158:161], v[230:233], v[64:67]
	s_barrier
	s_setprio 0
	s_add_i32 s62, s76, s70
	v_lshl_add_u64 v[196:197], s[92:93], 0, v[174:175]
	s_mov_b32 m0, s62
	ds_read_b128 v[162:165], v216 offset:16384
	ds_read_b128 v[184:187], v216 offset:17408
	ds_read_b128 v[188:191], v216 offset:18432
	ds_read_b128 v[192:195], v216 offset:19456
	ds_read_b128 v[218:221], v216 offset:20480
	ds_read_b128 v[222:225], v216 offset:21504
	ds_read_b128 v[226:229], v216 offset:22528
	ds_read_b128 v[230:233], v216 offset:23552
	global_load_lds_dwordx4 v[196:197], off
	s_add_i32 m0, s62, 0x2000
	s_add_u32 s62, s92, 0x80000
	v_lshl_add_u64 v[198:199], s[92:93], 0, v[178:179]
	s_addc_u32 s63, s93, 0
	s_add_i32 s76, s77, s70
	global_load_lds_dwordx4 v[198:199], off
	v_lshl_add_u64 v[200:201], s[62:63], 0, v[174:175]
	s_mov_b32 m0, s76
	v_lshl_add_u64 v[234:235], s[94:95], 0, v[176:177]
	global_load_lds_dwordx4 v[200:201], off
	v_lshl_add_u64 v[200:201], s[62:63], 0, v[178:179]
	s_add_i32 m0, s76, 0x2000
	s_nop 0
	global_load_lds_dwordx4 v[200:201], off
	v_lshl_add_u64 v[200:201], s[94:95], 0, v[172:173]
	s_mov_b32 m0, s37
	s_nop 0
	global_load_lds_dwordx4 v[200:201], off
	s_mov_b32 m0, s71
	s_nop 0
	global_load_lds_dwordx4 v[234:235], off
	s_waitcnt vmcnt(8)
	s_waitcnt lgkmcnt(0)
	s_setprio 1
	s_barrier
; #define PG8_STAGE(bufoff, gbase, voff) do { _Pragma("unroll") for (int _i = 0; _i < 2; ++_i) \
;         __builtin_amdgcn_global_load_lds((const unsigned*)((const char*)(gbase) + (voff)[_i]), (PG8_LAS unsigned*)(lds + (bufoff) + ldsw + _i * 8192), 16, 0, 0); } while (0)
; #define PG8_LDA(dst, b, h) do { _Pragma("unroll") for (int m = 0; m < 4; ++m) _Pragma("unroll") for (int k = 0; k < 2; ++k) dst[m][k] = *(const PG8_LAS bf16x8*)(lds + PG8_SA(b, h) + aoff + m * 2048 + k * 1024); } while (0)
; #define PG8_LDB(dst, b, h) do { _Pragma("unroll") for (int n = 0; n < 2; ++n) _Pragma("unroll") for (int k = 0; k < 2; ++k) dst[n][k] = *(const PG8_LAS bf16x8*)(lds + PG8_SB(b, h) + boff + n * 2048 + k * 1024); } while (0)
; #define PG8_MMA(ai, bj, At, Bt) do { __builtin_amdgcn_s_setprio(1); _Pragma("unroll") for (int m = 0; m < 4; ++m) _Pragma("unroll") for (int n = 0; n < 2; ++n) _Pragma("unroll") for (int k = 0; k < 2; ++k) \
;         acc[ai][bj][m][n] = __builtin_amdgcn_mfma_f32_16x16x32_bf16(Bt[n][k], At[m][k], acc[ai][bj][m][n], 0, 0, 0); __builtin_amdgcn_s_setprio(0); } while (0)
; #define PG8_WAIT_V(n) asm volatile("s_waitcnt vmcnt(" #n ")" ::: "memory")
; #define PG8_WAIT_L(n) asm volatile("s_waitcnt lgkmcnt(" #n ")" ::: "memory")
; #define PG8_BAR __builtin_amdgcn_s_barrier()
; #define PG8_SCHED __builtin_amdgcn_sched_barrier(0)
; template <class Epi, class Sched, bool ALIGN_EPI = false, bool SP2 = false>
; __device__ __forceinline__ void gemm_phase(PG8_LAS unsigned char* lds, const Gemm g, const Sched& S, const Epi& E, int tid_in) {
;     ...
;             PG8_WAIT_V(8); PG8_WAIT_L(0); PG8_BAR; PG8_MMA(1, 0, At, B0); PG8_MMA(1, 1, At, B1); PG8_BAR; PG8_SCHED;
;             PG8_LDB(B0, 1, 0); PG8_LDB(B1, 1, 1); PG8_SCHED; PG8_LDA(At, 1, 0); PG8_STAGE(PG8_SA(0, 1), a2 + hstep, voffA);
;             PG8_WAIT_V(8); PG8_WAIT_L(0); PG8_BAR; PG8_MMA(0, 0, At, B0); PG8_MMA(0, 1, At, B1); PG8_BAR; PG8_SCHED;
	v_mfma_f32_16x16x32_bf16 v[60:63], v[130:133], v[162:165], v[60:63]
	v_mfma_f32_16x16x32_bf16 v[56:59], v[138:141], v[162:165], v[56:59]
	v_mfma_f32_16x16x32_bf16 v[52:55], v[130:133], v[188:191], v[52:55]
	v_mfma_f32_16x16x32_bf16 v[48:51], v[138:141], v[188:191], v[48:51]
	v_mfma_f32_16x16x32_bf16 v[36:39], v[130:133], v[218:221], v[36:39]
	v_mfma_f32_16x16x32_bf16 v[32:35], v[138:141], v[218:221], v[32:35]
	v_mfma_f32_16x16x32_bf16 v[20:23], v[130:133], v[226:229], v[20:23]
	v_mfma_f32_16x16x32_bf16 v[16:19], v[138:141], v[226:229], v[16:19]
	v_mfma_f32_16x16x32_bf16 v[60:63], v[134:137], v[184:187], v[60:63]
	v_mfma_f32_16x16x32_bf16 v[56:59], v[142:145], v[184:187], v[56:59]
	v_mfma_f32_16x16x32_bf16 v[52:55], v[134:137], v[192:195], v[52:55]
	v_mfma_f32_16x16x32_bf16 v[48:51], v[142:145], v[192:195], v[48:51]
	v_mfma_f32_16x16x32_bf16 v[36:39], v[134:137], v[222:225], v[36:39]
	v_mfma_f32_16x16x32_bf16 v[32:35], v[142:145], v[222:225], v[32:35]
	v_mfma_f32_16x16x32_bf16 v[20:23], v[134:137], v[230:233], v[20:23]
	v_mfma_f32_16x16x32_bf16 v[16:19], v[142:145], v[230:233], v[16:19]
	s_setprio 0
	s_setprio 1
	v_mfma_f32_16x16x32_bf16 v[44:47], v[146:149], v[162:165], v[44:47]
	v_mfma_f32_16x16x32_bf16 v[40:43], v[154:157], v[162:165], v[40:43]
	v_mfma_f32_16x16x32_bf16 v[28:31], v[146:149], v[188:191], v[28:31]
	v_mfma_f32_16x16x32_bf16 v[24:27], v[154:157], v[188:191], v[24:27]
	v_mfma_f32_16x16x32_bf16 v[12:15], v[146:149], v[218:221], v[12:15]
	v_mfma_f32_16x16x32_bf16 v[8:11], v[154:157], v[218:221], v[8:11]
	v_mfma_f32_16x16x32_bf16 v[4:7], v[146:149], v[226:229], v[4:7]
	v_mfma_f32_16x16x32_bf16 v[0:3], v[154:157], v[226:229], v[0:3]
	v_mfma_f32_16x16x32_bf16 v[44:47], v[150:153], v[184:187], v[44:47]
	v_mfma_f32_16x16x32_bf16 v[40:43], v[158:161], v[184:187], v[40:43]
	v_mfma_f32_16x16x32_bf16 v[28:31], v[150:153], v[192:195], v[28:31]
	v_mfma_f32_16x16x32_bf16 v[24:27], v[158:161], v[192:195], v[24:27]
	v_mfma_f32_16x16x32_bf16 v[12:15], v[150:153], v[222:225], v[12:15]
	v_mfma_f32_16x16x32_bf16 v[8:11], v[158:161], v[222:225], v[8:11]
	v_mfma_f32_16x16x32_bf16 v[4:7], v[150:153], v[230:233], v[4:7]
	v_mfma_f32_16x16x32_bf16 v[0:3], v[158:161], v[230:233], v[0:3]
	s_barrier
	s_setprio 0
	s_add_i32 s76, 0, 0x18000
	v_add_u32_e32 v96, s76, v205
	s_add_i32 s77, 0, 0x1c000
	ds_read_b128 v[130:133], v96
	ds_read_b128 v[134:137], v96 offset:1024
	ds_read_b128 v[138:141], v96 offset:2048
	ds_read_b128 v[142:145], v96 offset:3072
	v_add_u32_e32 v96, s77, v205
	ds_read_b128 v[146:149], v96
	ds_read_b128 v[150:153], v96 offset:1024
	ds_read_b128 v[154:157], v96 offset:2048
	ds_read_b128 v[158:161], v96 offset:3072
	s_add_u32 s62, s94, 0x80000
	s_addc_u32 s63, s95, 0
	s_mov_b32 m0, s91
	v_lshl_add_u64 v[236:237], s[62:63], 0, v[172:173]
	ds_read_b128 v[162:165], v216 offset:32768
	ds_read_b128 v[184:187], v216 offset:33792
	ds_read_b128 v[188:191], v216 offset:34816
	ds_read_b128 v[192:195], v216 offset:35840
	ds_read_b128 v[218:221], v216 offset:36864
	ds_read_b128 v[222:225], v216 offset:37888
	ds_read_b128 v[226:229], v216 offset:38912
	ds_read_b128 v[230:233], v216 offset:39936
	global_load_lds_dwordx4 v[236:237], off
	v_lshl_add_u64 v[236:237], s[62:63], 0, v[176:177]
	s_mov_b32 m0, s96
	s_nop 0
	global_load_lds_dwordx4 v[236:237], off
	s_waitcnt vmcnt(8)
	s_waitcnt lgkmcnt(0)
	s_setprio 1
	s_barrier
	v_mfma_f32_16x16x32_bf16 v[126:129], v[130:133], v[162:165], v[126:129]
	v_mfma_f32_16x16x32_bf16 v[122:125], v[138:141], v[162:165], v[122:125]
	v_mfma_f32_16x16x32_bf16 v[118:121], v[130:133], v[188:191], v[118:121]
	v_mfma_f32_16x16x32_bf16 v[114:117], v[138:141], v[188:191], v[114:117]
	v_mfma_f32_16x16x32_bf16 v[102:105], v[130:133], v[218:221], v[102:105]
	v_mfma_f32_16x16x32_bf16 v[98:101], v[138:141], v[218:221], v[98:101]
	v_mfma_f32_16x16x32_bf16 v[84:87], v[130:133], v[226:229], v[84:87]
	v_mfma_f32_16x16x32_bf16 v[80:83], v[138:141], v[226:229], v[80:83]
	v_mfma_f32_16x16x32_bf16 v[126:129], v[134:137], v[184:187], v[126:129]
	v_mfma_f32_16x16x32_bf16 v[122:125], v[142:145], v[184:187], v[122:125]
	v_mfma_f32_16x16x32_bf16 v[118:121], v[134:137], v[192:195], v[118:121]
	v_mfma_f32_16x16x32_bf16 v[114:117], v[142:145], v[192:195], v[114:117]
	v_mfma_f32_16x16x32_bf16 v[102:105], v[134:137], v[222:225], v[102:105]
	v_mfma_f32_16x16x32_bf16 v[98:101], v[142:145], v[222:225], v[98:101]
	v_mfma_f32_16x16x32_bf16 v[84:87], v[134:137], v[230:233], v[84:87]
	v_mfma_f32_16x16x32_bf16 v[80:83], v[142:145], v[230:233], v[80:83]
	s_setprio 0
	s_setprio 1
	v_mfma_f32_16x16x32_bf16 v[110:113], v[146:149], v[162:165], v[110:113]
	v_mfma_f32_16x16x32_bf16 v[106:109], v[154:157], v[162:165], v[106:109]
	v_mfma_f32_16x16x32_bf16 v[92:95], v[146:149], v[188:191], v[92:95]
	v_mfma_f32_16x16x32_bf16 v[88:91], v[154:157], v[188:191], v[88:91]
	v_mfma_f32_16x16x32_bf16 v[76:79], v[146:149], v[218:221], v[76:79]
	v_mfma_f32_16x16x32_bf16 v[72:75], v[154:157], v[218:221], v[72:75]
	v_mfma_f32_16x16x32_bf16 v[68:71], v[146:149], v[226:229], v[68:71]
	v_mfma_f32_16x16x32_bf16 v[64:67], v[154:157], v[226:229], v[64:67]
	v_mfma_f32_16x16x32_bf16 v[110:113], v[150:153], v[184:187], v[110:113]
	v_mfma_f32_16x16x32_bf16 v[106:109], v[158:161], v[184:187], v[106:109]
	v_mfma_f32_16x16x32_bf16 v[92:95], v[150:153], v[192:195], v[92:95]
	v_mfma_f32_16x16x32_bf16 v[88:91], v[158:161], v[192:195], v[88:91]
	v_mfma_f32_16x16x32_bf16 v[76:79], v[150:153], v[222:225], v[76:79]
	v_mfma_f32_16x16x32_bf16 v[72:75], v[158:161], v[222:225], v[72:75]
	v_mfma_f32_16x16x32_bf16 v[68:71], v[150:153], v[230:233], v[68:71]
	v_mfma_f32_16x16x32_bf16 v[64:67], v[158:161], v[230:233], v[64:67]
	s_barrier
; #define PG8_STAGE(bufoff, gbase, voff) do { _Pragma("unroll") for (int _i = 0; _i < 2; ++_i) \
;         __builtin_amdgcn_global_load_lds((const unsigned*)((const char*)(gbase) + (voff)[_i]), (PG8_LAS unsigned*)(lds + (bufoff) + ldsw + _i * 8192), 16, 0, 0); } while (0)
; #define PG8_LDA(dst, b, h) do { _Pragma("unroll") for (int m = 0; m < 4; ++m) _Pragma("unroll") for (int k = 0; k < 2; ++k) dst[m][k] = *(const PG8_LAS bf16x8*)(lds + PG8_SA(b, h) + aoff + m * 2048 + k * 1024); } while (0)
; #define PG8_MMA(ai, bj, At, Bt) do { __builtin_amdgcn_s_setprio(1); _Pragma("unroll") for (int m = 0; m < 4; ++m) _Pragma("unroll") for (int n = 0; n < 2; ++n) _Pragma("unroll") for (int k = 0; k < 2; ++k) \
;         acc[ai][bj][m][n] = __builtin_amdgcn_mfma_f32_16x16x32_bf16(Bt[n][k], At[m][k], acc[ai][bj][m][n], 0, 0, 0); __builtin_amdgcn_s_setprio(0); } while (0)
; #define PG8_WAIT_V(n) asm volatile("s_waitcnt vmcnt(" #n ")" ::: "memory")
; #define PG8_WAIT_L(n) asm volatile("s_waitcnt lgkmcnt(" #n ")" ::: "memory")
; #define PG8_BAR __builtin_amdgcn_s_barrier()
; #define PG8_SCHED __builtin_amdgcn_sched_barrier(0)
; template <class Epi, class Sched, bool ALIGN_EPI = false, bool SP2 = false>
; __device__ __forceinline__ void gemm_phase(PG8_LAS unsigned char* lds, const Gemm g, const Sched& S, const Epi& E, int tid_in) {
;     ...
;             PG8_LDA(At, 1, 1); PG8_STAGE(PG8_SB(1, 0), b3, voffB); PG8_STAGE(PG8_SB(1, 1), b3 + hstep, voffB); PG8_STAGE(PG8_SA(1, 0), a3, voffA);
;             PG8_WAIT_V(8); PG8_WAIT_L(0); PG8_BAR; PG8_MMA(1, 0, At, B0); PG8_MMA(1, 1, At, B1); PG8_BAR; PG8_SCHED;
;     ...
;         if constexpr (ALIGN_EPI) { if (wr == 0) PG8_BAR; }
	s_setprio 0
	s_add_i32 s62, s76, s70
	v_lshl_add_u64 v[196:197], v[196:197], 0, s[88:89]
	s_mov_b32 m0, s62
	ds_read_b128 v[162:165], v216 offset:49152
	ds_read_b128 v[184:187], v216 offset:50176
	ds_read_b128 v[188:191], v216 offset:51200
	ds_read_b128 v[192:195], v216 offset:52224
	ds_read_b128 v[218:221], v216 offset:53248
	ds_read_b128 v[222:225], v216 offset:54272
	ds_read_b128 v[226:229], v216 offset:55296
	ds_read_b128 v[230:233], v216 offset:56320
	global_load_lds_dwordx4 v[196:197], off
	s_add_i32 m0, s62, 0x2000
	s_add_u32 s62, s92, 0x80080
	v_lshl_add_u64 v[196:197], v[198:199], 0, s[88:89]
	s_addc_u32 s63, s93, 0
	s_add_i32 s76, s77, s70
	global_load_lds_dwordx4 v[196:197], off
	v_lshl_add_u64 v[196:197], s[62:63], 0, v[174:175]
	s_mov_b32 m0, s76
	s_nop 0
	global_load_lds_dwordx4 v[196:197], off
	v_lshl_add_u64 v[196:197], s[62:63], 0, v[178:179]
	s_add_i32 m0, s76, 0x2000
	s_nop 0
	global_load_lds_dwordx4 v[196:197], off
	v_lshl_add_u64 v[196:197], v[200:201], 0, s[88:89]
	s_mov_b32 m0, s97
	s_nop 0
	global_load_lds_dwordx4 v[196:197], off
	v_lshl_add_u64 v[196:197], v[234:235], 0, s[88:89]
	s_mov_b32 m0, s2
	s_nop 0
	global_load_lds_dwordx4 v[196:197], off
	s_waitcnt vmcnt(8)
	s_waitcnt lgkmcnt(0)
	s_setprio 1
	s_barrier
	v_mfma_f32_16x16x32_bf16 v[60:63], v[130:133], v[162:165], v[60:63]
	v_mfma_f32_16x16x32_bf16 v[56:59], v[138:141], v[162:165], v[56:59]
	v_mfma_f32_16x16x32_bf16 v[52:55], v[130:133], v[188:191], v[52:55]
	v_mfma_f32_16x16x32_bf16 v[48:51], v[138:141], v[188:191], v[48:51]
	v_mfma_f32_16x16x32_bf16 v[36:39], v[130:133], v[218:221], v[36:39]
	v_mfma_f32_16x16x32_bf16 v[32:35], v[138:141], v[218:221], v[32:35]
	v_mfma_f32_16x16x32_bf16 v[20:23], v[130:133], v[226:229], v[20:23]
	v_mfma_f32_16x16x32_bf16 v[16:19], v[138:141], v[226:229], v[16:19]
	v_mfma_f32_16x16x32_bf16 v[60:63], v[134:137], v[184:187], v[60:63]
	v_mfma_f32_16x16x32_bf16 v[56:59], v[142:145], v[184:187], v[56:59]
	v_mfma_f32_16x16x32_bf16 v[52:55], v[134:137], v[192:195], v[52:55]
	v_mfma_f32_16x16x32_bf16 v[48:51], v[142:145], v[192:195], v[48:51]
	v_mfma_f32_16x16x32_bf16 v[36:39], v[134:137], v[222:225], v[36:39]
	v_mfma_f32_16x16x32_bf16 v[32:35], v[142:145], v[222:225], v[32:35]
	v_mfma_f32_16x16x32_bf16 v[20:23], v[134:137], v[230:233], v[20:23]
	v_mfma_f32_16x16x32_bf16 v[16:19], v[142:145], v[230:233], v[16:19]
	s_setprio 0
	s_setprio 1
	v_mfma_f32_16x16x32_bf16 v[44:47], v[146:149], v[162:165], v[44:47]
	v_mfma_f32_16x16x32_bf16 v[40:43], v[154:157], v[162:165], v[40:43]
	v_mfma_f32_16x16x32_bf16 v[28:31], v[146:149], v[188:191], v[28:31]
	v_mfma_f32_16x16x32_bf16 v[24:27], v[154:157], v[188:191], v[24:27]
	v_mfma_f32_16x16x32_bf16 v[12:15], v[146:149], v[218:221], v[12:15]
	v_mfma_f32_16x16x32_bf16 v[8:11], v[154:157], v[218:221], v[8:11]
	v_mfma_f32_16x16x32_bf16 v[4:7], v[146:149], v[226:229], v[4:7]
	v_mfma_f32_16x16x32_bf16 v[0:3], v[154:157], v[226:229], v[0:3]
	v_mfma_f32_16x16x32_bf16 v[44:47], v[150:153], v[184:187], v[44:47]
	v_mfma_f32_16x16x32_bf16 v[40:43], v[158:161], v[184:187], v[40:43]
	v_mfma_f32_16x16x32_bf16 v[28:31], v[150:153], v[192:195], v[28:31]
	v_mfma_f32_16x16x32_bf16 v[24:27], v[158:161], v[192:195], v[24:27]
	v_mfma_f32_16x16x32_bf16 v[12:15], v[150:153], v[222:225], v[12:15]
	v_mfma_f32_16x16x32_bf16 v[8:11], v[158:161], v[222:225], v[8:11]
	v_mfma_f32_16x16x32_bf16 v[4:7], v[150:153], v[230:233], v[4:7]
	v_mfma_f32_16x16x32_bf16 v[0:3], v[158:161], v[230:233], v[0:3]
	s_barrier
	s_setprio 0
	s_add_i32 s75, s75, 2
	s_add_u32 s64, s64, 0x100
	s_addc_u32 s65, s65, 0
	s_add_u32 s73, s73, 0x100
	s_addc_u32 s74, s74, 0
	s_cmp_gt_u32 s75, 29
	s_cbranch_scc0 .LBB0_135
	s_and_b64 vcc, exec, s[38:39]
	s_cbranch_vccz .LBB0_138
	s_barrier

; #define PG8_STAGE(bufoff, gbase, voff) do { _Pragma("unroll") for (int _i = 0; _i < 2; ++_i) \
;         __builtin_amdgcn_global_load_lds((const unsigned*)((const char*)(gbase) + (voff)[_i]), (PG8_LAS unsigned*)(lds + (bufoff) + ldsw + _i * 8192), 16, 0, 0); } while (0)
; #define PG8_LDA(dst, b, h) do { _Pragma("unroll") for (int m = 0; m < 4; ++m) _Pragma("unroll") for (int k = 0; k < 2; ++k) dst[m][k] = *(const PG8_LAS bf16x8*)(lds + PG8_SA(b, h) + aoff + m * 2048 + k * 1024); } while (0)
; #define PG8_LDB(dst, b, h) do { _Pragma("unroll") for (int n = 0; n < 2; ++n) _Pragma("unroll") for (int k = 0; k < 2; ++k) dst[n][k] = *(const PG8_LAS bf16x8*)(lds + PG8_SB(b, h) + boff + n * 2048 + k * 1024); } while (0)
; #define PG8_MMA(ai, bj, At, Bt) do { __builtin_amdgcn_s_setprio(1); _Pragma("unroll") for (int m = 0; m < 4; ++m) _Pragma("unroll") for (int n = 0; n < 2; ++n) _Pragma("unroll") for (int k = 0; k < 2; ++k) \
;         acc[ai][bj][m][n] = __builtin_amdgcn_mfma_f32_16x16x32_bf16(Bt[n][k], At[m][k], acc[ai][bj][m][n], 0, 0, 0); __builtin_amdgcn_s_setprio(0); } while (0)
; #define PG8_WAIT_V(n) asm volatile("s_waitcnt vmcnt(" #n ")" ::: "memory")
; #define PG8_BAR __builtin_amdgcn_s_barrier()
; template <class Epi, class Sched, bool ALIGN_EPI = false, bool SP2 = false>
; __device__ __forceinline__ void gemm_phase(PG8_LAS unsigned char* lds, const Gemm g, const Sched& S, const Epi& E, int tid_in) {
;     ...
;         for (int t = 0; t < nt; t += 2) {
;             const bool last = (t == nt - 2);
;             const char* a1 = cA + (size_t)(t + 1) * kstep;
;             const char* a2 = last ? nA : cA + (size_t)(t + 2) * kstep; const char* b2 = last ? nB : cB + (size_t)(t + 2) * kstep;
;             const char* a3 = a2 + kstep; const char* b3 = b2 + kstep;
;             if (last && has_next) S.a_ready(nxt);
;             if constexpr (SP2) {
;             PG8_LDB(B0, 0, 0); PG8_LDB(B1, 0, 1); PG8_SCHED; PG8_LDA(At, 0, 0); PG8_STAGE(PG8_SA(1, 1), a1 + hstep, voffA);
;             PG8_WAIT_V(8); PG8_WAIT_L(0); PG8_BAR; PG8_MMA(0, 0, At, B0); PG8_MMA(0, 1, At, B1); PG8_BAR; PG8_SCHED;
;             PG8_LDA(At, 0, 1); PG8_STAGE(PG8_SB(0, 0), b2, voffB); PG8_STAGE(PG8_SB(0, 1), b2 + hstep, voffB); PG8_STAGE(PG8_SA(0, 0), a2, voffA);
;             PG8_WAIT_V(8); PG8_WAIT_L(0); PG8_BAR; PG8_MMA(1, 0, At, B0); PG8_MMA(1, 1, At, B1); PG8_BAR; PG8_SCHED;
.LBB0_403:
	s_add_u32 s46, s44, 0xfff80080
	s_addc_u32 s47, s45, -1
	s_add_i32 s62, 0, 0x10000
	s_cmp_eq_u32 s75, 28
	s_cselect_b32 s65, s35, s47
	s_cselect_b32 s64, s43, s46
	v_add_u32_e32 v96, s62, v205
	s_cselect_b32 s47, s37, s74
	s_cselect_b32 s46, s72, s73
	s_add_i32 s76, 0, 0x14000
	ds_read_b128 v[130:133], v96
	ds_read_b128 v[134:137], v96 offset:1024
	ds_read_b128 v[138:141], v96 offset:2048
	ds_read_b128 v[142:145], v96 offset:3072
	v_add_u32_e32 v96, s76, v205
	ds_read_b128 v[146:149], v96
	ds_read_b128 v[150:153], v96 offset:1024
	ds_read_b128 v[154:157], v96 offset:2048
	ds_read_b128 v[158:161], v96 offset:3072
	v_lshl_add_u64 v[200:201], s[44:45], 0, v[180:181]
	s_add_i32 m0, s29, 0xc000
	ds_read_b128 v[162:165], v216
	ds_read_b128 v[184:187], v216 offset:1024
	ds_read_b128 v[188:191], v216 offset:2048
	ds_read_b128 v[192:195], v216 offset:3072
	ds_read_b128 v[196:199], v216 offset:4096
	ds_read_b128 v[218:221], v216 offset:5120
	ds_read_b128 v[222:225], v216 offset:6144
	ds_read_b128 v[226:229], v216 offset:7168
	global_load_lds_dwordx4 v[200:201], off
	v_lshl_add_u64 v[200:201], s[44:45], 0, v[182:183]
	s_add_i32 m0, s29, 0xe000
	s_nop 0
	global_load_lds_dwordx4 v[200:201], off
	s_waitcnt vmcnt(8)
	s_waitcnt lgkmcnt(0)
	s_setprio 1
	s_barrier
	v_mfma_f32_16x16x32_bf16 v[126:129], v[130:133], v[162:165], v[126:129]
	v_mfma_f32_16x16x32_bf16 v[122:125], v[138:141], v[162:165], v[122:125]
	v_mfma_f32_16x16x32_bf16 v[118:121], v[130:133], v[188:191], v[118:121]
	v_mfma_f32_16x16x32_bf16 v[114:117], v[138:141], v[188:191], v[114:117]
	v_mfma_f32_16x16x32_bf16 v[102:105], v[130:133], v[196:199], v[102:105]
	v_mfma_f32_16x16x32_bf16 v[98:101], v[138:141], v[196:199], v[98:101]
	v_mfma_f32_16x16x32_bf16 v[84:87], v[130:133], v[222:225], v[84:87]
	v_mfma_f32_16x16x32_bf16 v[80:83], v[138:141], v[222:225], v[80:83]
	v_mfma_f32_16x16x32_bf16 v[126:129], v[134:137], v[184:187], v[126:129]
	v_mfma_f32_16x16x32_bf16 v[122:125], v[142:145], v[184:187], v[122:125]
	v_mfma_f32_16x16x32_bf16 v[118:121], v[134:137], v[192:195], v[118:121]
	v_mfma_f32_16x16x32_bf16 v[114:117], v[142:145], v[192:195], v[114:117]
	v_mfma_f32_16x16x32_bf16 v[102:105], v[134:137], v[218:221], v[102:105]
	v_mfma_f32_16x16x32_bf16 v[98:101], v[142:145], v[218:221], v[98:101]
	v_mfma_f32_16x16x32_bf16 v[84:87], v[134:137], v[226:229], v[84:87]
	v_mfma_f32_16x16x32_bf16 v[80:83], v[142:145], v[226:229], v[80:83]
	s_setprio 0
	s_setprio 1
	v_mfma_f32_16x16x32_bf16 v[110:113], v[146:149], v[162:165], v[110:113]
	v_mfma_f32_16x16x32_bf16 v[106:109], v[154:157], v[162:165], v[106:109]
	v_mfma_f32_16x16x32_bf16 v[92:95], v[146:149], v[188:191], v[92:95]
	v_mfma_f32_16x16x32_bf16 v[88:91], v[154:157], v[188:191], v[88:91]
	v_mfma_f32_16x16x32_bf16 v[76:79], v[146:149], v[196:199], v[76:79]
	v_mfma_f32_16x16x32_bf16 v[72:75], v[154:157], v[196:199], v[72:75]
	v_mfma_f32_16x16x32_bf16 v[68:71], v[146:149], v[222:225], v[68:71]
	v_mfma_f32_16x16x32_bf16 v[64:67], v[154:157], v[222:225], v[64:67]
	v_mfma_f32_16x16x32_bf16 v[110:113], v[150:153], v[184:187], v[110:113]
	v_mfma_f32_16x16x32_bf16 v[106:109], v[158:161], v[184:187], v[106:109]
	v_mfma_f32_16x16x32_bf16 v[92:95], v[150:153], v[192:195], v[92:95]
	v_mfma_f32_16x16x32_bf16 v[88:91], v[158:161], v[192:195], v[88:91]
	v_mfma_f32_16x16x32_bf16 v[76:79], v[150:153], v[218:221], v[76:79]
	v_mfma_f32_16x16x32_bf16 v[72:75], v[158:161], v[218:221], v[72:75]
	v_mfma_f32_16x16x32_bf16 v[68:71], v[150:153], v[226:229], v[68:71]
	v_mfma_f32_16x16x32_bf16 v[64:67], v[158:161], v[226:229], v[64:67]
	s_barrier
	s_setprio 0
	s_add_i32 s62, s62, s96
	v_lshl_add_u64 v[200:201], s[46:47], 0, v[174:175]
	s_mov_b32 m0, s62
	ds_read_b128 v[162:165], v216 offset:16384
	ds_read_b128 v[184:187], v216 offset:17408
	ds_read_b128 v[188:191], v216 offset:18432
	ds_read_b128 v[192:195], v216 offset:19456
	ds_read_b128 v[196:199], v216 offset:20480
	ds_read_b128 v[218:221], v216 offset:21504
	ds_read_b128 v[222:225], v216 offset:22528
	ds_read_b128 v[226:229], v216 offset:23552
	global_load_lds_dwordx4 v[200:201], off
	s_add_i32 m0, s62, 0x2000
	s_add_u32 s62, s46, 0x80000
	v_lshl_add_u64 v[230:231], s[46:47], 0, v[178:179]
	s_addc_u32 s63, s47, 0
	s_add_i32 s76, s76, s96
	global_load_lds_dwordx4 v[230:231], off
	v_lshl_add_u64 v[232:233], s[62:63], 0, v[174:175]
	s_mov_b32 m0, s76
	v_lshl_add_u64 v[234:235], s[64:65], 0, v[176:177]
	global_load_lds_dwordx4 v[232:233], off
	v_lshl_add_u64 v[232:233], s[62:63], 0, v[178:179]
	s_add_i32 m0, s76, 0x2000
	s_nop 0
	global_load_lds_dwordx4 v[232:233], off
	v_lshl_add_u64 v[232:233], s[64:65], 0, v[172:173]
	s_mov_b32 m0, s29
	s_nop 0
	global_load_lds_dwordx4 v[232:233], off
	s_mov_b32 m0, s97
	s_nop 0
	global_load_lds_dwordx4 v[234:235], off
	s_waitcnt vmcnt(8)
	s_waitcnt lgkmcnt(0)
	s_setprio 1
	s_barrier
; #define PG8_STAGE(bufoff, gbase, voff) do { _Pragma("unroll") for (int _i = 0; _i < 2; ++_i) \
;         __builtin_amdgcn_global_load_lds((const unsigned*)((const char*)(gbase) + (voff)[_i]), (PG8_LAS unsigned*)(lds + (bufoff) + ldsw + _i * 8192), 16, 0, 0); } while (0)
; #define PG8_LDA(dst, b, h) do { _Pragma("unroll") for (int m = 0; m < 4; ++m) _Pragma("unroll") for (int k = 0; k < 2; ++k) dst[m][k] = *(const PG8_LAS bf16x8*)(lds + PG8_SA(b, h) + aoff + m * 2048 + k * 1024); } while (0)
; #define PG8_LDB(dst, b, h) do { _Pragma("unroll") for (int n = 0; n < 2; ++n) _Pragma("unroll") for (int k = 0; k < 2; ++k) dst[n][k] = *(const PG8_LAS bf16x8*)(lds + PG8_SB(b, h) + boff + n * 2048 + k * 1024); } while (0)
; #define PG8_MMA(ai, bj, At, Bt) do { __builtin_amdgcn_s_setprio(1); _Pragma("unroll") for (int m = 0; m < 4; ++m) _Pragma("unroll") for (int n = 0; n < 2; ++n) _Pragma("unroll") for (int k = 0; k < 2; ++k) \
;         acc[ai][bj][m][n] = __builtin_amdgcn_mfma_f32_16x16x32_bf16(Bt[n][k], At[m][k], acc[ai][bj][m][n], 0, 0, 0); __builtin_amdgcn_s_setprio(0); } while (0)
; #define PG8_WAIT_V(n) asm volatile("s_waitcnt vmcnt(" #n ")" ::: "memory")
; #define PG8_WAIT_L(n) asm volatile("s_waitcnt lgkmcnt(" #n ")" ::: "memory")
; #define PG8_BAR __builtin_amdgcn_s_barrier()
; #define PG8_SCHED __builtin_amdgcn_sched_barrier(0)
; template <class Epi, class Sched, bool ALIGN_EPI = false, bool SP2 = false>
; __device__ __forceinline__ void gemm_phase(PG8_LAS unsigned char* lds, const Gemm g, const Sched& S, const Epi& E, int tid_in) {
;     ...
;             PG8_WAIT_V(8); PG8_WAIT_L(0); PG8_BAR; PG8_MMA(1, 0, At, B0); PG8_MMA(1, 1, At, B1); PG8_BAR; PG8_SCHED;
;             PG8_LDB(B0, 1, 0); PG8_LDB(B1, 1, 1); PG8_SCHED; PG8_LDA(At, 1, 0); PG8_STAGE(PG8_SA(0, 1), a2 + hstep, voffA);
;             PG8_WAIT_V(8); PG8_WAIT_L(0); PG8_BAR; PG8_MMA(0, 0, At, B0); PG8_MMA(0, 1, At, B1); PG8_BAR; PG8_SCHED;
	v_mfma_f32_16x16x32_bf16 v[60:63], v[130:133], v[162:165], v[60:63]
	v_mfma_f32_16x16x32_bf16 v[56:59], v[138:141], v[162:165], v[56:59]
	v_mfma_f32_16x16x32_bf16 v[52:55], v[130:133], v[188:191], v[52:55]
	v_mfma_f32_16x16x32_bf16 v[48:51], v[138:141], v[188:191], v[48:51]
	v_mfma_f32_16x16x32_bf16 v[36:39], v[130:133], v[196:199], v[36:39]
	v_mfma_f32_16x16x32_bf16 v[32:35], v[138:141], v[196:199], v[32:35]
	v_mfma_f32_16x16x32_bf16 v[20:23], v[130:133], v[222:225], v[20:23]
	v_mfma_f32_16x16x32_bf16 v[16:19], v[138:141], v[222:225], v[16:19]
	v_mfma_f32_16x16x32_bf16 v[60:63], v[134:137], v[184:187], v[60:63]
	v_mfma_f32_16x16x32_bf16 v[56:59], v[142:145], v[184:187], v[56:59]
	v_mfma_f32_16x16x32_bf16 v[52:55], v[134:137], v[192:195], v[52:55]
	v_mfma_f32_16x16x32_bf16 v[48:51], v[142:145], v[192:195], v[48:51]
	v_mfma_f32_16x16x32_bf16 v[36:39], v[134:137], v[218:221], v[36:39]
	v_mfma_f32_16x16x32_bf16 v[32:35], v[142:145], v[218:221], v[32:35]
	v_mfma_f32_16x16x32_bf16 v[20:23], v[134:137], v[226:229], v[20:23]
	v_mfma_f32_16x16x32_bf16 v[16:19], v[142:145], v[226:229], v[16:19]
	s_setprio 0
	s_setprio 1
	v_mfma_f32_16x16x32_bf16 v[44:47], v[146:149], v[162:165], v[44:47]
	v_mfma_f32_16x16x32_bf16 v[40:43], v[154:157], v[162:165], v[40:43]
	v_mfma_f32_16x16x32_bf16 v[28:31], v[146:149], v[188:191], v[28:31]
	v_mfma_f32_16x16x32_bf16 v[24:27], v[154:157], v[188:191], v[24:27]
	v_mfma_f32_16x16x32_bf16 v[12:15], v[146:149], v[196:199], v[12:15]
	v_mfma_f32_16x16x32_bf16 v[8:11], v[154:157], v[196:199], v[8:11]
	v_mfma_f32_16x16x32_bf16 v[4:7], v[146:149], v[222:225], v[4:7]
	v_mfma_f32_16x16x32_bf16 v[0:3], v[154:157], v[222:225], v[0:3]
	v_mfma_f32_16x16x32_bf16 v[44:47], v[150:153], v[184:187], v[44:47]
	v_mfma_f32_16x16x32_bf16 v[40:43], v[158:161], v[184:187], v[40:43]
	v_mfma_f32_16x16x32_bf16 v[28:31], v[150:153], v[192:195], v[28:31]
	v_mfma_f32_16x16x32_bf16 v[24:27], v[158:161], v[192:195], v[24:27]
	v_mfma_f32_16x16x32_bf16 v[12:15], v[150:153], v[218:221], v[12:15]
	v_mfma_f32_16x16x32_bf16 v[8:11], v[158:161], v[218:221], v[8:11]
	v_mfma_f32_16x16x32_bf16 v[4:7], v[150:153], v[226:229], v[4:7]
	v_mfma_f32_16x16x32_bf16 v[0:3], v[158:161], v[226:229], v[0:3]
	s_barrier
	s_setprio 0
	s_add_i32 s76, 0, 0x18000
	v_add_u32_e32 v96, s76, v205
	s_add_i32 s77, 0, 0x1c000
	ds_read_b128 v[130:133], v96
	ds_read_b128 v[134:137], v96 offset:1024
	ds_read_b128 v[138:141], v96 offset:2048
	ds_read_b128 v[142:145], v96 offset:3072
	v_add_u32_e32 v96, s77, v205
	ds_read_b128 v[146:149], v96
	ds_read_b128 v[150:153], v96 offset:1024
	ds_read_b128 v[154:157], v96 offset:2048
	ds_read_b128 v[158:161], v96 offset:3072
	s_add_u32 s62, s64, 0x80000
	s_addc_u32 s63, s65, 0
	s_mov_b32 m0, s20
	v_lshl_add_u64 v[236:237], s[62:63], 0, v[172:173]
	ds_read_b128 v[162:165], v216 offset:32768
	ds_read_b128 v[184:187], v216 offset:33792
	ds_read_b128 v[188:191], v216 offset:34816
	ds_read_b128 v[192:195], v216 offset:35840
	ds_read_b128 v[196:199], v216 offset:36864
	ds_read_b128 v[218:221], v216 offset:37888
	ds_read_b128 v[222:225], v216 offset:38912
	ds_read_b128 v[226:229], v216 offset:39936
	global_load_lds_dwordx4 v[236:237], off
	v_lshl_add_u64 v[236:237], s[62:63], 0, v[176:177]
	s_mov_b32 m0, s21
	s_nop 0
	global_load_lds_dwordx4 v[236:237], off
	s_waitcnt vmcnt(8)
	s_waitcnt lgkmcnt(0)
	s_setprio 1
	s_barrier
	v_mfma_f32_16x16x32_bf16 v[126:129], v[130:133], v[162:165], v[126:129]
	v_mfma_f32_16x16x32_bf16 v[122:125], v[138:141], v[162:165], v[122:125]
	v_mfma_f32_16x16x32_bf16 v[118:121], v[130:133], v[188:191], v[118:121]
	v_mfma_f32_16x16x32_bf16 v[114:117], v[138:141], v[188:191], v[114:117]
	v_mfma_f32_16x16x32_bf16 v[102:105], v[130:133], v[196:199], v[102:105]
	v_mfma_f32_16x16x32_bf16 v[98:101], v[138:141], v[196:199], v[98:101]
	v_mfma_f32_16x16x32_bf16 v[84:87], v[130:133], v[222:225], v[84:87]
	v_mfma_f32_16x16x32_bf16 v[80:83], v[138:141], v[222:225], v[80:83]
	v_mfma_f32_16x16x32_bf16 v[126:129], v[134:137], v[184:187], v[126:129]
	v_mfma_f32_16x16x32_bf16 v[122:125], v[142:145], v[184:187], v[122:125]
	v_mfma_f32_16x16x32_bf16 v[118:121], v[134:137], v[192:195], v[118:121]
	v_mfma_f32_16x16x32_bf16 v[114:117], v[142:145], v[192:195], v[114:117]
	v_mfma_f32_16x16x32_bf16 v[102:105], v[134:137], v[218:221], v[102:105]
	v_mfma_f32_16x16x32_bf16 v[98:101], v[142:145], v[218:221], v[98:101]
	v_mfma_f32_16x16x32_bf16 v[84:87], v[134:137], v[226:229], v[84:87]
	v_mfma_f32_16x16x32_bf16 v[80:83], v[142:145], v[226:229], v[80:83]
	s_setprio 0
	s_setprio 1
	v_mfma_f32_16x16x32_bf16 v[110:113], v[146:149], v[162:165], v[110:113]
	v_mfma_f32_16x16x32_bf16 v[106:109], v[154:157], v[162:165], v[106:109]
	v_mfma_f32_16x16x32_bf16 v[92:95], v[146:149], v[188:191], v[92:95]
	v_mfma_f32_16x16x32_bf16 v[88:91], v[154:157], v[188:191], v[88:91]
	v_mfma_f32_16x16x32_bf16 v[76:79], v[146:149], v[196:199], v[76:79]
	v_mfma_f32_16x16x32_bf16 v[72:75], v[154:157], v[196:199], v[72:75]
	v_mfma_f32_16x16x32_bf16 v[68:71], v[146:149], v[222:225], v[68:71]
	v_mfma_f32_16x16x32_bf16 v[64:67], v[154:157], v[222:225], v[64:67]
	v_mfma_f32_16x16x32_bf16 v[110:113], v[150:153], v[184:187], v[110:113]
	v_mfma_f32_16x16x32_bf16 v[106:109], v[158:161], v[184:187], v[106:109]
	v_mfma_f32_16x16x32_bf16 v[92:95], v[150:153], v[192:195], v[92:95]
	v_mfma_f32_16x16x32_bf16 v[88:91], v[158:161], v[192:195], v[88:91]
	v_mfma_f32_16x16x32_bf16 v[76:79], v[150:153], v[218:221], v[76:79]
	v_mfma_f32_16x16x32_bf16 v[72:75], v[158:161], v[218:221], v[72:75]
	v_mfma_f32_16x16x32_bf16 v[68:71], v[150:153], v[226:229], v[68:71]
	v_mfma_f32_16x16x32_bf16 v[64:67], v[158:161], v[226:229], v[64:67]
	s_barrier
; #define PG8_STAGE(bufoff, gbase, voff) do { _Pragma("unroll") for (int _i = 0; _i < 2; ++_i) \
;         __builtin_amdgcn_global_load_lds((const unsigned*)((const char*)(gbase) + (voff)[_i]), (PG8_LAS unsigned*)(lds + (bufoff) + ldsw + _i * 8192), 16, 0, 0); } while (0)
; #define PG8_LDA(dst, b, h) do { _Pragma("unroll") for (int m = 0; m < 4; ++m) _Pragma("unroll") for (int k = 0; k < 2; ++k) dst[m][k] = *(const PG8_LAS bf16x8*)(lds + PG8_SA(b, h) + aoff + m * 2048 + k * 1024); } while (0)
; #define PG8_MMA(ai, bj, At, Bt) do { __builtin_amdgcn_s_setprio(1); _Pragma("unroll") for (int m = 0; m < 4; ++m) _Pragma("unroll") for (int n = 0; n < 2; ++n) _Pragma("unroll") for (int k = 0; k < 2; ++k) \
;         acc[ai][bj][m][n] = __builtin_amdgcn_mfma_f32_16x16x32_bf16(Bt[n][k], At[m][k], acc[ai][bj][m][n], 0, 0, 0); __builtin_amdgcn_s_setprio(0); } while (0)
; #define PG8_WAIT_V(n) asm volatile("s_waitcnt vmcnt(" #n ")" ::: "memory")
; #define PG8_WAIT_L(n) asm volatile("s_waitcnt lgkmcnt(" #n ")" ::: "memory")
; #define PG8_BAR __builtin_amdgcn_s_barrier()
; #define PG8_SCHED __builtin_amdgcn_sched_barrier(0)
; template <class Epi, class Sched, bool ALIGN_EPI = false, bool SP2 = false>
; __device__ __forceinline__ void gemm_phase(PG8_LAS unsigned char* lds, const Gemm g, const Sched& S, const Epi& E, int tid_in) {
;     ...
;             PG8_LDA(At, 1, 1); PG8_STAGE(PG8_SB(1, 0), b3, voffB); PG8_STAGE(PG8_SB(1, 1), b3 + hstep, voffB); PG8_STAGE(PG8_SA(1, 0), a3, voffA);
;             PG8_WAIT_V(8); PG8_WAIT_L(0); PG8_BAR; PG8_MMA(1, 0, At, B0); PG8_MMA(1, 1, At, B1); PG8_BAR; PG8_SCHED;
;     ...
;         if constexpr (ALIGN_EPI) { if (wr == 0) PG8_BAR; }
;         if constexpr (!Epi::AFTER_DRAIN) { E(acc, cur, wr, wc, fr, fq); S.done(cur); }
	s_setprio 0
	s_add_i32 s62, s76, s96
	v_lshl_add_u64 v[200:201], v[200:201], 0, s[88:89]
	s_mov_b32 m0, s62
	ds_read_b128 v[162:165], v216 offset:49152
	ds_read_b128 v[184:187], v216 offset:50176
	ds_read_b128 v[188:191], v216 offset:51200
	ds_read_b128 v[192:195], v216 offset:52224
	ds_read_b128 v[196:199], v216 offset:53248
	ds_read_b128 v[218:221], v216 offset:54272
	ds_read_b128 v[222:225], v216 offset:55296
	ds_read_b128 v[226:229], v216 offset:56320
	global_load_lds_dwordx4 v[200:201], off
	s_add_i32 m0, s62, 0x2000
	s_add_u32 s46, s46, 0x80080
	v_lshl_add_u64 v[200:201], v[230:231], 0, s[88:89]
	s_addc_u32 s47, s47, 0
	s_add_i32 s62, s77, s96
	global_load_lds_dwordx4 v[200:201], off
	v_lshl_add_u64 v[200:201], s[46:47], 0, v[174:175]
	s_mov_b32 m0, s62
	s_nop 0
	global_load_lds_dwordx4 v[200:201], off
	v_lshl_add_u64 v[200:201], s[46:47], 0, v[178:179]
	s_add_i32 m0, s62, 0x2000
	s_nop 0
	global_load_lds_dwordx4 v[200:201], off
	v_lshl_add_u64 v[200:201], v[232:233], 0, s[88:89]
	s_mov_b32 m0, s22
	s_nop 0
	global_load_lds_dwordx4 v[200:201], off
	v_lshl_add_u64 v[200:201], v[234:235], 0, s[88:89]
	s_mov_b32 m0, s23
	s_nop 0
	global_load_lds_dwordx4 v[200:201], off
	s_waitcnt vmcnt(8)
	s_waitcnt lgkmcnt(0)
	s_setprio 1
	s_barrier
	v_mfma_f32_16x16x32_bf16 v[60:63], v[130:133], v[162:165], v[60:63]
	v_mfma_f32_16x16x32_bf16 v[56:59], v[138:141], v[162:165], v[56:59]
	v_mfma_f32_16x16x32_bf16 v[52:55], v[130:133], v[188:191], v[52:55]
	v_mfma_f32_16x16x32_bf16 v[48:51], v[138:141], v[188:191], v[48:51]
	v_mfma_f32_16x16x32_bf16 v[36:39], v[130:133], v[196:199], v[36:39]
	v_mfma_f32_16x16x32_bf16 v[32:35], v[138:141], v[196:199], v[32:35]
	v_mfma_f32_16x16x32_bf16 v[20:23], v[130:133], v[222:225], v[20:23]
	v_mfma_f32_16x16x32_bf16 v[16:19], v[138:141], v[222:225], v[16:19]
	v_mfma_f32_16x16x32_bf16 v[60:63], v[134:137], v[184:187], v[60:63]
	v_mfma_f32_16x16x32_bf16 v[56:59], v[142:145], v[184:187], v[56:59]
	v_mfma_f32_16x16x32_bf16 v[52:55], v[134:137], v[192:195], v[52:55]
	v_mfma_f32_16x16x32_bf16 v[48:51], v[142:145], v[192:195], v[48:51]
	v_mfma_f32_16x16x32_bf16 v[36:39], v[134:137], v[218:221], v[36:39]
	v_mfma_f32_16x16x32_bf16 v[32:35], v[142:145], v[218:221], v[32:35]
	v_mfma_f32_16x16x32_bf16 v[20:23], v[134:137], v[226:229], v[20:23]
	v_mfma_f32_16x16x32_bf16 v[16:19], v[142:145], v[226:229], v[16:19]
	s_setprio 0
	s_setprio 1
	v_mfma_f32_16x16x32_bf16 v[44:47], v[146:149], v[162:165], v[44:47]
	v_mfma_f32_16x16x32_bf16 v[40:43], v[154:157], v[162:165], v[40:43]
	v_mfma_f32_16x16x32_bf16 v[28:31], v[146:149], v[188:191], v[28:31]
	v_mfma_f32_16x16x32_bf16 v[24:27], v[154:157], v[188:191], v[24:27]
	v_mfma_f32_16x16x32_bf16 v[12:15], v[146:149], v[196:199], v[12:15]
	v_mfma_f32_16x16x32_bf16 v[8:11], v[154:157], v[196:199], v[8:11]
	v_mfma_f32_16x16x32_bf16 v[4:7], v[146:149], v[222:225], v[4:7]
	v_mfma_f32_16x16x32_bf16 v[0:3], v[154:157], v[222:225], v[0:3]
	v_mfma_f32_16x16x32_bf16 v[44:47], v[150:153], v[184:187], v[44:47]
	v_mfma_f32_16x16x32_bf16 v[40:43], v[158:161], v[184:187], v[40:43]
	v_mfma_f32_16x16x32_bf16 v[28:31], v[150:153], v[192:195], v[28:31]
	v_mfma_f32_16x16x32_bf16 v[24:27], v[158:161], v[192:195], v[24:27]
	v_mfma_f32_16x16x32_bf16 v[12:15], v[150:153], v[218:221], v[12:15]
	v_mfma_f32_16x16x32_bf16 v[8:11], v[158:161], v[218:221], v[8:11]
	v_mfma_f32_16x16x32_bf16 v[4:7], v[150:153], v[226:229], v[4:7]
	v_mfma_f32_16x16x32_bf16 v[0:3], v[158:161], v[226:229], v[0:3]
	s_barrier
	s_setprio 0
	s_add_i32 s75, s75, 2
	s_add_u32 s44, s44, 0x100
	s_addc_u32 s45, s45, 0
	s_add_u32 s73, s73, 0x100
	s_addc_u32 s74, s74, 0
	s_cmp_gt_u32 s75, 29
	s_cbranch_scc0 .LBB0_403
	s_and_b64 vcc, exec, s[30:31]
	s_cbranch_vccnz .LBB0_408
	v_lshl_add_u32 v184, s42, 8, v204
	s_cmp_gt_i32 s28, 3
	s_mov_b64 s[42:43], -1
	s_cbranch_scc1 .LBB0_409

; #define PG8_STAGE(bufoff, gbase, voff) do { _Pragma("unroll") for (int _i = 0; _i < 2; ++_i) \
;         __builtin_amdgcn_global_load_lds((const unsigned*)((const char*)(gbase) + (voff)[_i]), (PG8_LAS unsigned*)(lds + (bufoff) + ldsw + _i * 8192), 16, 0, 0); } while (0)
; #define PG8_LDA(dst, b, h) do { _Pragma("unroll") for (int m = 0; m < 4; ++m) _Pragma("unroll") for (int k = 0; k < 2; ++k) dst[m][k] = *(const PG8_LAS bf16x8*)(lds + PG8_SA(b, h) + aoff + m * 2048 + k * 1024); } while (0)
; #define PG8_LDB(dst, b, h) do { _Pragma("unroll") for (int n = 0; n < 2; ++n) _Pragma("unroll") for (int k = 0; k < 2; ++k) dst[n][k] = *(const PG8_LAS bf16x8*)(lds + PG8_SB(b, h) + boff + n * 2048 + k * 1024); } while (0)
; #define PG8_MMA(ai, bj, At, Bt) do { __builtin_amdgcn_s_setprio(1); _Pragma("unroll") for (int m = 0; m < 4; ++m) _Pragma("unroll") for (int n = 0; n < 2; ++n) _Pragma("unroll") for (int k = 0; k < 2; ++k) \
;         acc[ai][bj][m][n] = __builtin_amdgcn_mfma_f32_16x16x32_bf16(Bt[n][k], At[m][k], acc[ai][bj][m][n], 0, 0, 0); __builtin_amdgcn_s_setprio(0); } while (0)
; #define PG8_WAIT_V(n) asm volatile("s_waitcnt vmcnt(" #n ")" ::: "memory")
; #define PG8_BAR __builtin_amdgcn_s_barrier()
; template <class Epi, class Sched, bool ALIGN_EPI = false, bool SP2 = false>
; __device__ __forceinline__ void gemm_phase(PG8_LAS unsigned char* lds, const Gemm g, const Sched& S, const Epi& E, int tid_in) {
;     ...
;         for (int t = 0; t < nt; t += 2) {
;             const bool last = (t == nt - 2);
;             const char* a1 = cA + (size_t)(t + 1) * kstep;
;             const char* a2 = last ? nA : cA + (size_t)(t + 2) * kstep; const char* b2 = last ? nB : cB + (size_t)(t + 2) * kstep;
;             const char* a3 = a2 + kstep; const char* b3 = b2 + kstep;
;             if (last && has_next) S.a_ready(nxt);
;             if constexpr (SP2) {
;             PG8_LDB(B0, 0, 0); PG8_LDB(B1, 0, 1); PG8_SCHED; PG8_LDA(At, 0, 0); PG8_STAGE(PG8_SA(1, 1), a1 + hstep, voffA);
;             PG8_WAIT_V(8); PG8_WAIT_L(0); PG8_BAR; PG8_MMA(0, 0, At, B0); PG8_MMA(0, 1, At, B1); PG8_BAR; PG8_SCHED;
;             PG8_LDA(At, 0, 1); PG8_STAGE(PG8_SB(0, 0), b2, voffB); PG8_STAGE(PG8_SB(0, 1), b2 + hstep, voffB); PG8_STAGE(PG8_SA(0, 0), a2, voffA);
;             PG8_WAIT_V(8); PG8_WAIT_L(0); PG8_BAR; PG8_MMA(1, 0, At, B0); PG8_MMA(1, 1, At, B1); PG8_BAR; PG8_SCHED;
.LBB0_455:
	s_add_u32 s42, s40, 0xfff80080
	s_addc_u32 s43, s41, -1
	s_add_i32 s62, 0, 0x10000
	s_cmp_eq_u32 s77, 28
	s_cselect_b32 s45, s39, s43
	s_cselect_b32 s44, s73, s42
	v_add_u32_e32 v96, s62, v203
	s_cselect_b32 s43, s37, s76
	s_cselect_b32 s42, s74, s75
	s_add_i32 s78, 0, 0x14000
	ds_read_b128 v[130:133], v96
	ds_read_b128 v[134:137], v96 offset:1024
	ds_read_b128 v[138:141], v96 offset:2048
	ds_read_b128 v[142:145], v96 offset:3072
	v_add_u32_e32 v96, s78, v203
	ds_read_b128 v[146:149], v96
	ds_read_b128 v[150:153], v96 offset:1024
	ds_read_b128 v[154:157], v96 offset:2048
	ds_read_b128 v[158:161], v96 offset:3072
	v_lshl_add_u64 v[196:197], s[40:41], 0, v[180:181]
	s_add_i32 m0, s1, 0xc000
	ds_read_b128 v[162:165], v215
	ds_read_b128 v[184:187], v215 offset:1024
	ds_read_b128 v[188:191], v215 offset:2048
	ds_read_b128 v[192:195], v215 offset:3072
	ds_read_b128 v[216:219], v215 offset:4096
	ds_read_b128 v[220:223], v215 offset:5120
	ds_read_b128 v[224:227], v215 offset:6144
	ds_read_b128 v[228:231], v215 offset:7168
	global_load_lds_dwordx4 v[196:197], off
	v_lshl_add_u64 v[196:197], s[40:41], 0, v[182:183]
	s_add_i32 m0, s1, 0xe000
	s_nop 0
	global_load_lds_dwordx4 v[196:197], off
	s_waitcnt vmcnt(8)
	s_waitcnt lgkmcnt(0)
	s_setprio 1
	s_barrier
	v_mfma_f32_16x16x32_bf16 v[126:129], v[130:133], v[162:165], v[126:129]
	v_mfma_f32_16x16x32_bf16 v[122:125], v[138:141], v[162:165], v[122:125]
	v_mfma_f32_16x16x32_bf16 v[118:121], v[130:133], v[188:191], v[118:121]
	v_mfma_f32_16x16x32_bf16 v[114:117], v[138:141], v[188:191], v[114:117]
	v_mfma_f32_16x16x32_bf16 v[102:105], v[130:133], v[216:219], v[102:105]
	v_mfma_f32_16x16x32_bf16 v[98:101], v[138:141], v[216:219], v[98:101]
	v_mfma_f32_16x16x32_bf16 v[84:87], v[130:133], v[224:227], v[84:87]
	v_mfma_f32_16x16x32_bf16 v[80:83], v[138:141], v[224:227], v[80:83]
	v_mfma_f32_16x16x32_bf16 v[126:129], v[134:137], v[184:187], v[126:129]
	v_mfma_f32_16x16x32_bf16 v[122:125], v[142:145], v[184:187], v[122:125]
	v_mfma_f32_16x16x32_bf16 v[118:121], v[134:137], v[192:195], v[118:121]
	v_mfma_f32_16x16x32_bf16 v[114:117], v[142:145], v[192:195], v[114:117]
	v_mfma_f32_16x16x32_bf16 v[102:105], v[134:137], v[220:223], v[102:105]
	v_mfma_f32_16x16x32_bf16 v[98:101], v[142:145], v[220:223], v[98:101]
	v_mfma_f32_16x16x32_bf16 v[84:87], v[134:137], v[228:231], v[84:87]
	v_mfma_f32_16x16x32_bf16 v[80:83], v[142:145], v[228:231], v[80:83]
	s_setprio 0
	s_setprio 1
	v_mfma_f32_16x16x32_bf16 v[110:113], v[146:149], v[162:165], v[110:113]
	v_mfma_f32_16x16x32_bf16 v[106:109], v[154:157], v[162:165], v[106:109]
	v_mfma_f32_16x16x32_bf16 v[92:95], v[146:149], v[188:191], v[92:95]
	v_mfma_f32_16x16x32_bf16 v[88:91], v[154:157], v[188:191], v[88:91]
	v_mfma_f32_16x16x32_bf16 v[76:79], v[146:149], v[216:219], v[76:79]
	v_mfma_f32_16x16x32_bf16 v[72:75], v[154:157], v[216:219], v[72:75]
	v_mfma_f32_16x16x32_bf16 v[68:71], v[146:149], v[224:227], v[68:71]
	v_mfma_f32_16x16x32_bf16 v[64:67], v[154:157], v[224:227], v[64:67]
	v_mfma_f32_16x16x32_bf16 v[110:113], v[150:153], v[184:187], v[110:113]
	v_mfma_f32_16x16x32_bf16 v[106:109], v[158:161], v[184:187], v[106:109]
	v_mfma_f32_16x16x32_bf16 v[92:95], v[150:153], v[192:195], v[92:95]
	v_mfma_f32_16x16x32_bf16 v[88:91], v[158:161], v[192:195], v[88:91]
	v_mfma_f32_16x16x32_bf16 v[76:79], v[150:153], v[220:223], v[76:79]
	v_mfma_f32_16x16x32_bf16 v[72:75], v[158:161], v[220:223], v[72:75]
	v_mfma_f32_16x16x32_bf16 v[68:71], v[150:153], v[228:231], v[68:71]
	v_mfma_f32_16x16x32_bf16 v[64:67], v[158:161], v[228:231], v[64:67]
	s_barrier
	s_setprio 0
	s_add_i32 s62, s62, s64
	v_lshl_add_u64 v[196:197], s[42:43], 0, v[176:177]
	s_mov_b32 m0, s62
	ds_read_b128 v[162:165], v215 offset:16384
	ds_read_b128 v[184:187], v215 offset:17408
	ds_read_b128 v[188:191], v215 offset:18432
	ds_read_b128 v[192:195], v215 offset:19456
	ds_read_b128 v[216:219], v215 offset:20480
	ds_read_b128 v[220:223], v215 offset:21504
	ds_read_b128 v[224:227], v215 offset:22528
	ds_read_b128 v[228:231], v215 offset:23552
	global_load_lds_dwordx4 v[196:197], off
	s_add_i32 m0, s62, 0x2000
	s_add_u32 s62, s42, 0x80000
	v_lshl_add_u64 v[198:199], s[42:43], 0, v[172:173]
	s_addc_u32 s63, s43, 0
	s_add_i32 s78, s78, s64
	global_load_lds_dwordx4 v[198:199], off
	v_lshl_add_u64 v[200:201], s[62:63], 0, v[176:177]
	s_mov_b32 m0, s78
	v_lshl_add_u64 v[232:233], s[44:45], 0, v[174:175]
	global_load_lds_dwordx4 v[200:201], off
	v_lshl_add_u64 v[200:201], s[62:63], 0, v[172:173]
	s_add_i32 m0, s78, 0x2000
	s_nop 0
	global_load_lds_dwordx4 v[200:201], off
	v_lshl_add_u64 v[200:201], s[44:45], 0, v[178:179]
	s_mov_b32 m0, s1
	s_nop 0
	global_load_lds_dwordx4 v[200:201], off
	s_mov_b32 m0, s3
	s_nop 0
	global_load_lds_dwordx4 v[232:233], off
	s_waitcnt vmcnt(8)
	s_waitcnt lgkmcnt(0)
	s_setprio 1
	s_barrier
; #define PG8_STAGE(bufoff, gbase, voff) do { _Pragma("unroll") for (int _i = 0; _i < 2; ++_i) \
;         __builtin_amdgcn_global_load_lds((const unsigned*)((const char*)(gbase) + (voff)[_i]), (PG8_LAS unsigned*)(lds + (bufoff) + ldsw + _i * 8192), 16, 0, 0); } while (0)
; #define PG8_LDA(dst, b, h) do { _Pragma("unroll") for (int m = 0; m < 4; ++m) _Pragma("unroll") for (int k = 0; k < 2; ++k) dst[m][k] = *(const PG8_LAS bf16x8*)(lds + PG8_SA(b, h) + aoff + m * 2048 + k * 1024); } while (0)
; #define PG8_LDB(dst, b, h) do { _Pragma("unroll") for (int n = 0; n < 2; ++n) _Pragma("unroll") for (int k = 0; k < 2; ++k) dst[n][k] = *(const PG8_LAS bf16x8*)(lds + PG8_SB(b, h) + boff + n * 2048 + k * 1024); } while (0)
; #define PG8_MMA(ai, bj, At, Bt) do { __builtin_amdgcn_s_setprio(1); _Pragma("unroll") for (int m = 0; m < 4; ++m) _Pragma("unroll") for (int n = 0; n < 2; ++n) _Pragma("unroll") for (int k = 0; k < 2; ++k) \
;         acc[ai][bj][m][n] = __builtin_amdgcn_mfma_f32_16x16x32_bf16(Bt[n][k], At[m][k], acc[ai][bj][m][n], 0, 0, 0); __builtin_amdgcn_s_setprio(0); } while (0)
; #define PG8_WAIT_V(n) asm volatile("s_waitcnt vmcnt(" #n ")" ::: "memory")
; #define PG8_WAIT_L(n) asm volatile("s_waitcnt lgkmcnt(" #n ")" ::: "memory")
; #define PG8_BAR __builtin_amdgcn_s_barrier()
; #define PG8_SCHED __builtin_amdgcn_sched_barrier(0)
; template <class Epi, class Sched, bool ALIGN_EPI = false, bool SP2 = false>
; __device__ __forceinline__ void gemm_phase(PG8_LAS unsigned char* lds, const Gemm g, const Sched& S, const Epi& E, int tid_in) {
;     ...
;             PG8_WAIT_V(8); PG8_WAIT_L(0); PG8_BAR; PG8_MMA(1, 0, At, B0); PG8_MMA(1, 1, At, B1); PG8_BAR; PG8_SCHED;
;             PG8_LDB(B0, 1, 0); PG8_LDB(B1, 1, 1); PG8_SCHED; PG8_LDA(At, 1, 0); PG8_STAGE(PG8_SA(0, 1), a2 + hstep, voffA);
;             PG8_WAIT_V(8); PG8_WAIT_L(0); PG8_BAR; PG8_MMA(0, 0, At, B0); PG8_MMA(0, 1, At, B1); PG8_BAR; PG8_SCHED;
	v_mfma_f32_16x16x32_bf16 v[60:63], v[130:133], v[162:165], v[60:63]
	v_mfma_f32_16x16x32_bf16 v[56:59], v[138:141], v[162:165], v[56:59]
	v_mfma_f32_16x16x32_bf16 v[52:55], v[130:133], v[188:191], v[52:55]
	v_mfma_f32_16x16x32_bf16 v[48:51], v[138:141], v[188:191], v[48:51]
	v_mfma_f32_16x16x32_bf16 v[36:39], v[130:133], v[216:219], v[36:39]
	v_mfma_f32_16x16x32_bf16 v[32:35], v[138:141], v[216:219], v[32:35]
	v_mfma_f32_16x16x32_bf16 v[20:23], v[130:133], v[224:227], v[20:23]
	v_mfma_f32_16x16x32_bf16 v[16:19], v[138:141], v[224:227], v[16:19]
	v_mfma_f32_16x16x32_bf16 v[60:63], v[134:137], v[184:187], v[60:63]
	v_mfma_f32_16x16x32_bf16 v[56:59], v[142:145], v[184:187], v[56:59]
	v_mfma_f32_16x16x32_bf16 v[52:55], v[134:137], v[192:195], v[52:55]
	v_mfma_f32_16x16x32_bf16 v[48:51], v[142:145], v[192:195], v[48:51]
	v_mfma_f32_16x16x32_bf16 v[36:39], v[134:137], v[220:223], v[36:39]
	v_mfma_f32_16x16x32_bf16 v[32:35], v[142:145], v[220:223], v[32:35]
	v_mfma_f32_16x16x32_bf16 v[20:23], v[134:137], v[228:231], v[20:23]
	v_mfma_f32_16x16x32_bf16 v[16:19], v[142:145], v[228:231], v[16:19]
	s_setprio 0
	s_setprio 1
	v_mfma_f32_16x16x32_bf16 v[44:47], v[146:149], v[162:165], v[44:47]
	v_mfma_f32_16x16x32_bf16 v[40:43], v[154:157], v[162:165], v[40:43]
	v_mfma_f32_16x16x32_bf16 v[28:31], v[146:149], v[188:191], v[28:31]
	v_mfma_f32_16x16x32_bf16 v[24:27], v[154:157], v[188:191], v[24:27]
	v_mfma_f32_16x16x32_bf16 v[12:15], v[146:149], v[216:219], v[12:15]
	v_mfma_f32_16x16x32_bf16 v[8:11], v[154:157], v[216:219], v[8:11]
	v_mfma_f32_16x16x32_bf16 v[4:7], v[146:149], v[224:227], v[4:7]
	v_mfma_f32_16x16x32_bf16 v[0:3], v[154:157], v[224:227], v[0:3]
	v_mfma_f32_16x16x32_bf16 v[44:47], v[150:153], v[184:187], v[44:47]
	v_mfma_f32_16x16x32_bf16 v[40:43], v[158:161], v[184:187], v[40:43]
	v_mfma_f32_16x16x32_bf16 v[28:31], v[150:153], v[192:195], v[28:31]
	v_mfma_f32_16x16x32_bf16 v[24:27], v[158:161], v[192:195], v[24:27]
	v_mfma_f32_16x16x32_bf16 v[12:15], v[150:153], v[220:223], v[12:15]
	v_mfma_f32_16x16x32_bf16 v[8:11], v[158:161], v[220:223], v[8:11]
	v_mfma_f32_16x16x32_bf16 v[4:7], v[150:153], v[228:231], v[4:7]
	v_mfma_f32_16x16x32_bf16 v[0:3], v[158:161], v[228:231], v[0:3]
	s_barrier
	s_setprio 0
	s_add_i32 s62, 0, 0x18000
	v_add_u32_e32 v96, s62, v203
	s_add_i32 s63, 0, 0x1c000
	ds_read_b128 v[130:133], v96
	ds_read_b128 v[134:137], v96 offset:1024
	ds_read_b128 v[138:141], v96 offset:2048
	ds_read_b128 v[142:145], v96 offset:3072
	v_add_u32_e32 v96, s63, v203
	ds_read_b128 v[146:149], v96
	ds_read_b128 v[150:153], v96 offset:1024
	ds_read_b128 v[154:157], v96 offset:2048
	ds_read_b128 v[158:161], v96 offset:3072
	s_add_u32 s44, s44, 0x80000
	s_addc_u32 s45, s45, 0
	s_mov_b32 m0, s65
	v_lshl_add_u64 v[234:235], s[44:45], 0, v[178:179]
	ds_read_b128 v[162:165], v215 offset:32768
	ds_read_b128 v[184:187], v215 offset:33792
	ds_read_b128 v[188:191], v215 offset:34816
	ds_read_b128 v[192:195], v215 offset:35840
	ds_read_b128 v[216:219], v215 offset:36864
	ds_read_b128 v[220:223], v215 offset:37888
	ds_read_b128 v[224:227], v215 offset:38912
	ds_read_b128 v[228:231], v215 offset:39936
	global_load_lds_dwordx4 v[234:235], off
	v_lshl_add_u64 v[234:235], s[44:45], 0, v[174:175]
	s_mov_b32 m0, s66
	s_nop 0
	global_load_lds_dwordx4 v[234:235], off
	s_waitcnt vmcnt(8)
	s_waitcnt lgkmcnt(0)
	s_setprio 1
	s_barrier
	v_mfma_f32_16x16x32_bf16 v[126:129], v[130:133], v[162:165], v[126:129]
	v_mfma_f32_16x16x32_bf16 v[122:125], v[138:141], v[162:165], v[122:125]
	v_mfma_f32_16x16x32_bf16 v[118:121], v[130:133], v[188:191], v[118:121]
	v_mfma_f32_16x16x32_bf16 v[114:117], v[138:141], v[188:191], v[114:117]
	v_mfma_f32_16x16x32_bf16 v[102:105], v[130:133], v[216:219], v[102:105]
	v_mfma_f32_16x16x32_bf16 v[98:101], v[138:141], v[216:219], v[98:101]
	v_mfma_f32_16x16x32_bf16 v[84:87], v[130:133], v[224:227], v[84:87]
	v_mfma_f32_16x16x32_bf16 v[80:83], v[138:141], v[224:227], v[80:83]
	v_mfma_f32_16x16x32_bf16 v[126:129], v[134:137], v[184:187], v[126:129]
	v_mfma_f32_16x16x32_bf16 v[122:125], v[142:145], v[184:187], v[122:125]
	v_mfma_f32_16x16x32_bf16 v[118:121], v[134:137], v[192:195], v[118:121]
	v_mfma_f32_16x16x32_bf16 v[114:117], v[142:145], v[192:195], v[114:117]
	v_mfma_f32_16x16x32_bf16 v[102:105], v[134:137], v[220:223], v[102:105]
	v_mfma_f32_16x16x32_bf16 v[98:101], v[142:145], v[220:223], v[98:101]
	v_mfma_f32_16x16x32_bf16 v[84:87], v[134:137], v[228:231], v[84:87]
	v_mfma_f32_16x16x32_bf16 v[80:83], v[142:145], v[228:231], v[80:83]
	s_setprio 0
	s_setprio 1
	v_mfma_f32_16x16x32_bf16 v[110:113], v[146:149], v[162:165], v[110:113]
	v_mfma_f32_16x16x32_bf16 v[106:109], v[154:157], v[162:165], v[106:109]
	v_mfma_f32_16x16x32_bf16 v[92:95], v[146:149], v[188:191], v[92:95]
	v_mfma_f32_16x16x32_bf16 v[88:91], v[154:157], v[188:191], v[88:91]
	v_mfma_f32_16x16x32_bf16 v[76:79], v[146:149], v[216:219], v[76:79]
	v_mfma_f32_16x16x32_bf16 v[72:75], v[154:157], v[216:219], v[72:75]
	v_mfma_f32_16x16x32_bf16 v[68:71], v[146:149], v[224:227], v[68:71]
	v_mfma_f32_16x16x32_bf16 v[64:67], v[154:157], v[224:227], v[64:67]
	v_mfma_f32_16x16x32_bf16 v[110:113], v[150:153], v[184:187], v[110:113]
	v_mfma_f32_16x16x32_bf16 v[106:109], v[158:161], v[184:187], v[106:109]
	v_mfma_f32_16x16x32_bf16 v[92:95], v[150:153], v[192:195], v[92:95]
	v_mfma_f32_16x16x32_bf16 v[88:91], v[158:161], v[192:195], v[88:91]
	v_mfma_f32_16x16x32_bf16 v[76:79], v[150:153], v[220:223], v[76:79]
	v_mfma_f32_16x16x32_bf16 v[72:75], v[158:161], v[220:223], v[72:75]
	v_mfma_f32_16x16x32_bf16 v[68:71], v[150:153], v[228:231], v[68:71]
	v_mfma_f32_16x16x32_bf16 v[64:67], v[158:161], v[228:231], v[64:67]
	s_barrier
; #define PG8_STAGE(bufoff, gbase, voff) do { _Pragma("unroll") for (int _i = 0; _i < 2; ++_i) \
;         __builtin_amdgcn_global_load_lds((const unsigned*)((const char*)(gbase) + (voff)[_i]), (PG8_LAS unsigned*)(lds + (bufoff) + ldsw + _i * 8192), 16, 0, 0); } while (0)
; #define PG8_LDA(dst, b, h) do { _Pragma("unroll") for (int m = 0; m < 4; ++m) _Pragma("unroll") for (int k = 0; k < 2; ++k) dst[m][k] = *(const PG8_LAS bf16x8*)(lds + PG8_SA(b, h) + aoff + m * 2048 + k * 1024); } while (0)
; #define PG8_MMA(ai, bj, At, Bt) do { __builtin_amdgcn_s_setprio(1); _Pragma("unroll") for (int m = 0; m < 4; ++m) _Pragma("unroll") for (int n = 0; n < 2; ++n) _Pragma("unroll") for (int k = 0; k < 2; ++k) \
;         acc[ai][bj][m][n] = __builtin_amdgcn_mfma_f32_16x16x32_bf16(Bt[n][k], At[m][k], acc[ai][bj][m][n], 0, 0, 0); __builtin_amdgcn_s_setprio(0); } while (0)
; #define PG8_WAIT_V(n) asm volatile("s_waitcnt vmcnt(" #n ")" ::: "memory")
; #define PG8_WAIT_L(n) asm volatile("s_waitcnt lgkmcnt(" #n ")" ::: "memory")
; #define PG8_BAR __builtin_amdgcn_s_barrier()
; #define PG8_SCHED __builtin_amdgcn_sched_barrier(0)
; template <class Epi, class Sched, bool ALIGN_EPI = false, bool SP2 = false>
; __device__ __forceinline__ void gemm_phase(PG8_LAS unsigned char* lds, const Gemm g, const Sched& S, const Epi& E, int tid_in) {
;     ...
;             PG8_LDA(At, 1, 1); PG8_STAGE(PG8_SB(1, 0), b3, voffB); PG8_STAGE(PG8_SB(1, 1), b3 + hstep, voffB); PG8_STAGE(PG8_SA(1, 0), a3, voffA);
;             PG8_WAIT_V(8); PG8_WAIT_L(0); PG8_BAR; PG8_MMA(1, 0, At, B0); PG8_MMA(1, 1, At, B1); PG8_BAR; PG8_SCHED;
;     ...
;         if constexpr (ALIGN_EPI) { if (wr == 0) PG8_BAR; }
	s_setprio 0
	s_add_i32 s44, s62, s64
	v_lshl_add_u64 v[196:197], v[196:197], 0, s[88:89]
	s_mov_b32 m0, s44
	ds_read_b128 v[162:165], v215 offset:49152
	ds_read_b128 v[184:187], v215 offset:50176
	ds_read_b128 v[188:191], v215 offset:51200
	ds_read_b128 v[192:195], v215 offset:52224
	ds_read_b128 v[216:219], v215 offset:53248
	ds_read_b128 v[220:223], v215 offset:54272
	ds_read_b128 v[224:227], v215 offset:55296
	ds_read_b128 v[228:231], v215 offset:56320
	global_load_lds_dwordx4 v[196:197], off
	s_add_i32 m0, s44, 0x2000
	s_add_u32 s42, s42, 0x80080
	v_lshl_add_u64 v[196:197], v[198:199], 0, s[88:89]
	s_addc_u32 s43, s43, 0
	s_add_i32 s44, s63, s64
	global_load_lds_dwordx4 v[196:197], off
	v_lshl_add_u64 v[196:197], s[42:43], 0, v[176:177]
	s_mov_b32 m0, s44
	s_nop 0
	global_load_lds_dwordx4 v[196:197], off
	v_lshl_add_u64 v[196:197], s[42:43], 0, v[172:173]
	s_add_i32 m0, s44, 0x2000
	s_nop 0
	global_load_lds_dwordx4 v[196:197], off
	v_lshl_add_u64 v[196:197], v[200:201], 0, s[88:89]
	s_mov_b32 m0, s67
	s_nop 0
	global_load_lds_dwordx4 v[196:197], off
	v_lshl_add_u64 v[196:197], v[232:233], 0, s[88:89]
	s_mov_b32 m0, s71
	s_nop 0
	global_load_lds_dwordx4 v[196:197], off
	s_waitcnt vmcnt(8)
	s_waitcnt lgkmcnt(0)
	s_setprio 1
	s_barrier
	v_mfma_f32_16x16x32_bf16 v[60:63], v[130:133], v[162:165], v[60:63]
	v_mfma_f32_16x16x32_bf16 v[56:59], v[138:141], v[162:165], v[56:59]
	v_mfma_f32_16x16x32_bf16 v[52:55], v[130:133], v[188:191], v[52:55]
	v_mfma_f32_16x16x32_bf16 v[48:51], v[138:141], v[188:191], v[48:51]
	v_mfma_f32_16x16x32_bf16 v[36:39], v[130:133], v[216:219], v[36:39]
	v_mfma_f32_16x16x32_bf16 v[32:35], v[138:141], v[216:219], v[32:35]
	v_mfma_f32_16x16x32_bf16 v[20:23], v[130:133], v[224:227], v[20:23]
	v_mfma_f32_16x16x32_bf16 v[16:19], v[138:141], v[224:227], v[16:19]
	v_mfma_f32_16x16x32_bf16 v[60:63], v[134:137], v[184:187], v[60:63]
	v_mfma_f32_16x16x32_bf16 v[56:59], v[142:145], v[184:187], v[56:59]
	v_mfma_f32_16x16x32_bf16 v[52:55], v[134:137], v[192:195], v[52:55]
	v_mfma_f32_16x16x32_bf16 v[48:51], v[142:145], v[192:195], v[48:51]
	v_mfma_f32_16x16x32_bf16 v[36:39], v[134:137], v[220:223], v[36:39]
	v_mfma_f32_16x16x32_bf16 v[32:35], v[142:145], v[220:223], v[32:35]
	v_mfma_f32_16x16x32_bf16 v[20:23], v[134:137], v[228:231], v[20:23]
	v_mfma_f32_16x16x32_bf16 v[16:19], v[142:145], v[228:231], v[16:19]
	s_setprio 0
	s_setprio 1
	v_mfma_f32_16x16x32_bf16 v[44:47], v[146:149], v[162:165], v[44:47]
	v_mfma_f32_16x16x32_bf16 v[40:43], v[154:157], v[162:165], v[40:43]
	v_mfma_f32_16x16x32_bf16 v[28:31], v[146:149], v[188:191], v[28:31]
	v_mfma_f32_16x16x32_bf16 v[24:27], v[154:157], v[188:191], v[24:27]
	v_mfma_f32_16x16x32_bf16 v[12:15], v[146:149], v[216:219], v[12:15]
	v_mfma_f32_16x16x32_bf16 v[8:11], v[154:157], v[216:219], v[8:11]
	v_mfma_f32_16x16x32_bf16 v[4:7], v[146:149], v[224:227], v[4:7]
	v_mfma_f32_16x16x32_bf16 v[0:3], v[154:157], v[224:227], v[0:3]
	v_mfma_f32_16x16x32_bf16 v[44:47], v[150:153], v[184:187], v[44:47]
	v_mfma_f32_16x16x32_bf16 v[40:43], v[158:161], v[184:187], v[40:43]
	v_mfma_f32_16x16x32_bf16 v[28:31], v[150:153], v[192:195], v[28:31]
	v_mfma_f32_16x16x32_bf16 v[24:27], v[158:161], v[192:195], v[24:27]
	v_mfma_f32_16x16x32_bf16 v[12:15], v[150:153], v[220:223], v[12:15]
	v_mfma_f32_16x16x32_bf16 v[8:11], v[158:161], v[220:223], v[8:11]
	v_mfma_f32_16x16x32_bf16 v[4:7], v[150:153], v[228:231], v[4:7]
	v_mfma_f32_16x16x32_bf16 v[0:3], v[158:161], v[228:231], v[0:3]
	s_barrier
	s_setprio 0
	s_add_i32 s77, s77, 2
	s_add_u32 s40, s40, 0x100
	s_addc_u32 s41, s41, 0
	s_add_u32 s75, s75, 0x100
	s_addc_u32 s76, s76, 0
	s_cmp_gt_u32 s77, 29
	s_cbranch_scc0 .LBB0_455
	s_and_b64 vcc, exec, s[34:35]
	s_cbranch_vccz .LBB0_458
	s_barrier

; #define PG8_STAGE(bufoff, gbase, voff) do { _Pragma("unroll") for (int _i = 0; _i < 2; ++_i) \
;         __builtin_amdgcn_global_load_lds((const unsigned*)((const char*)(gbase) + (voff)[_i]), (PG8_LAS unsigned*)(lds + (bufoff) + ldsw + _i * 8192), 16, 0, 0); } while (0)
; #define PG8_LDA(dst, b, h) do { _Pragma("unroll") for (int m = 0; m < 4; ++m) _Pragma("unroll") for (int k = 0; k < 2; ++k) dst[m][k] = *(const PG8_LAS bf16x8*)(lds + PG8_SA(b, h) + aoff + m * 2048 + k * 1024); } while (0)
; #define PG8_LDB(dst, b, h) do { _Pragma("unroll") for (int n = 0; n < 2; ++n) _Pragma("unroll") for (int k = 0; k < 2; ++k) dst[n][k] = *(const PG8_LAS bf16x8*)(lds + PG8_SB(b, h) + boff + n * 2048 + k * 1024); } while (0)
; #define PG8_MMA(ai, bj, At, Bt) do { __builtin_amdgcn_s_setprio(1); _Pragma("unroll") for (int m = 0; m < 4; ++m) _Pragma("unroll") for (int n = 0; n < 2; ++n) _Pragma("unroll") for (int k = 0; k < 2; ++k) \
;         acc[ai][bj][m][n] = __builtin_amdgcn_mfma_f32_16x16x32_bf16(Bt[n][k], At[m][k], acc[ai][bj][m][n], 0, 0, 0); __builtin_amdgcn_s_setprio(0); } while (0)
; #define PG8_WAIT_V(n) asm volatile("s_waitcnt vmcnt(" #n ")" ::: "memory")
; #define PG8_WAIT_L(n) asm volatile("s_waitcnt lgkmcnt(" #n ")" ::: "memory")
; template <class Epi, class Sched, bool ALIGN_EPI = false, bool SP2 = false>
; __device__ __forceinline__ void gemm_phase(PG8_LAS unsigned char* lds, const Gemm g, const Sched& S, const Epi& E, int tid_in) {
;     ...
;             const bool last = (t == nt - 2);
;             const char* a1 = cA + (size_t)(t + 1) * kstep;
;             const char* a2 = last ? nA : cA + (size_t)(t + 2) * kstep; const char* b2 = last ? nB : cB + (size_t)(t + 2) * kstep;
;             const char* a3 = a2 + kstep; const char* b3 = b2 + kstep;
;             if (last && has_next) S.a_ready(nxt);
;             if constexpr (SP2) {
;             PG8_LDB(B0, 0, 0); PG8_LDB(B1, 0, 1); PG8_SCHED; PG8_LDA(At, 0, 0); PG8_STAGE(PG8_SA(1, 1), a1 + hstep, voffA);
;             PG8_WAIT_V(8); PG8_WAIT_L(0); PG8_BAR; PG8_MMA(0, 0, At, B0); PG8_MMA(0, 1, At, B1); PG8_BAR; PG8_SCHED;
;             PG8_LDA(At, 0, 1); PG8_STAGE(PG8_SB(0, 0), b2, voffB); PG8_STAGE(PG8_SB(0, 1), b2 + hstep, voffB); PG8_STAGE(PG8_SA(0, 0), a2, voffA);
;             PG8_WAIT_V(8); PG8_WAIT_L(0); PG8_BAR; PG8_MMA(1, 0, At, B0); PG8_MMA(1, 1, At, B1); PG8_BAR; PG8_SCHED;
.LBB0_567:
	s_add_u32 s28, s26, 0xfff80080
	s_addc_u32 s29, s27, -1
	s_add_i32 s62, 0, 0x10000
	s_cmp_eq_u32 s66, 28
	s_cselect_b32 s31, s19, s29
	s_cselect_b32 s30, s47, s28
	v_add_u32_e32 v144, s62, v148
	s_cselect_b32 s29, s17, s65
	s_cselect_b32 s28, s52, s64
	s_add_i32 s67, 0, 0x14000
	ds_read_b128 v[140:143], v144
	ds_read_b128 v[152:155], v144 offset:1024
	ds_read_b128 v[156:159], v144 offset:2048
	ds_read_b128 v[160:163], v144 offset:3072
	v_add_u32_e32 v144, s67, v148
	ds_read_b128 v[172:175], v144
	ds_read_b128 v[176:179], v144 offset:1024
	ds_read_b128 v[180:183], v144 offset:2048
	ds_read_b128 v[184:187], v144 offset:3072
	v_lshl_add_u64 v[144:145], s[26:27], 0, v[136:137]
	s_add_i32 m0, s40, 0xc000
	ds_read_b128 v[188:191], v150
	ds_read_b128 v[192:195], v150 offset:1024
	ds_read_b128 v[196:199], v150 offset:2048
	ds_read_b128 v[204:207], v150 offset:3072
	ds_read_b128 v[208:211], v150 offset:4096
	ds_read_b128 v[212:215], v150 offset:5120
	ds_read_b128 v[216:219], v150 offset:6144
	ds_read_b128 v[220:223], v150 offset:7168
	global_load_lds_dwordx4 v[144:145], off
	v_lshl_add_u64 v[144:145], s[26:27], 0, v[138:139]
	s_add_i32 m0, s40, 0xe000
	s_nop 0
	global_load_lds_dwordx4 v[144:145], off
	s_waitcnt vmcnt(8)
	s_waitcnt lgkmcnt(0)
	s_setprio 1
	s_barrier
	v_mfma_f32_16x16x32_bf16 v[126:129], v[140:143], v[188:191], v[126:129]
	v_mfma_f32_16x16x32_bf16 v[122:125], v[156:159], v[188:191], v[122:125]
	v_mfma_f32_16x16x32_bf16 v[110:113], v[140:143], v[196:199], v[110:113]
	v_mfma_f32_16x16x32_bf16 v[106:109], v[156:159], v[196:199], v[106:109]
	v_mfma_f32_16x16x32_bf16 v[92:95], v[140:143], v[208:211], v[92:95]
	v_mfma_f32_16x16x32_bf16 v[88:91], v[156:159], v[208:211], v[88:91]
	v_mfma_f32_16x16x32_bf16 v[76:79], v[140:143], v[216:219], v[76:79]
	v_mfma_f32_16x16x32_bf16 v[72:75], v[156:159], v[216:219], v[72:75]
	v_mfma_f32_16x16x32_bf16 v[126:129], v[152:155], v[192:195], v[126:129]
	v_mfma_f32_16x16x32_bf16 v[122:125], v[160:163], v[192:195], v[122:125]
	v_mfma_f32_16x16x32_bf16 v[110:113], v[152:155], v[204:207], v[110:113]
	v_mfma_f32_16x16x32_bf16 v[106:109], v[160:163], v[204:207], v[106:109]
	v_mfma_f32_16x16x32_bf16 v[92:95], v[152:155], v[212:215], v[92:95]
	v_mfma_f32_16x16x32_bf16 v[88:91], v[160:163], v[212:215], v[88:91]
	v_mfma_f32_16x16x32_bf16 v[76:79], v[152:155], v[220:223], v[76:79]
	v_mfma_f32_16x16x32_bf16 v[72:75], v[160:163], v[220:223], v[72:75]
	s_setprio 0
	s_setprio 1
	v_mfma_f32_16x16x32_bf16 v[118:121], v[172:175], v[188:191], v[118:121]
	v_mfma_f32_16x16x32_bf16 v[114:117], v[180:183], v[188:191], v[114:117]
	v_mfma_f32_16x16x32_bf16 v[102:105], v[172:175], v[196:199], v[102:105]
	v_mfma_f32_16x16x32_bf16 v[98:101], v[180:183], v[196:199], v[98:101]
	v_mfma_f32_16x16x32_bf16 v[84:87], v[172:175], v[208:211], v[84:87]
	v_mfma_f32_16x16x32_bf16 v[80:83], v[180:183], v[208:211], v[80:83]
	v_mfma_f32_16x16x32_bf16 v[68:71], v[172:175], v[216:219], v[68:71]
	v_mfma_f32_16x16x32_bf16 v[64:67], v[180:183], v[216:219], v[64:67]
	v_mfma_f32_16x16x32_bf16 v[118:121], v[176:179], v[192:195], v[118:121]
	v_mfma_f32_16x16x32_bf16 v[114:117], v[184:187], v[192:195], v[114:117]
	v_mfma_f32_16x16x32_bf16 v[102:105], v[176:179], v[204:207], v[102:105]
	v_mfma_f32_16x16x32_bf16 v[98:101], v[184:187], v[204:207], v[98:101]
	v_mfma_f32_16x16x32_bf16 v[84:87], v[176:179], v[212:215], v[84:87]
	v_mfma_f32_16x16x32_bf16 v[80:83], v[184:187], v[212:215], v[80:83]
	v_mfma_f32_16x16x32_bf16 v[68:71], v[176:179], v[220:223], v[68:71]
	v_mfma_f32_16x16x32_bf16 v[64:67], v[184:187], v[220:223], v[64:67]
	s_barrier
	s_setprio 0
	s_add_i32 s62, s62, s39
	v_lshl_add_u64 v[144:145], s[28:29], 0, v[96:97]
	s_mov_b32 m0, s62
	ds_read_b128 v[188:191], v150 offset:16384
	ds_read_b128 v[192:195], v150 offset:17408
	ds_read_b128 v[196:199], v150 offset:18432
	ds_read_b128 v[204:207], v150 offset:19456
	ds_read_b128 v[208:211], v150 offset:20480
	ds_read_b128 v[212:215], v150 offset:21504
	ds_read_b128 v[216:219], v150 offset:22528
	ds_read_b128 v[220:223], v150 offset:23552
	global_load_lds_dwordx4 v[144:145], off
	s_add_i32 m0, s62, 0x2000
	s_add_u32 s62, s28, 0x80000
	v_lshl_add_u64 v[164:165], s[28:29], 0, v[134:135]
	s_addc_u32 s63, s29, 0
	s_add_i32 s67, s67, s39
	global_load_lds_dwordx4 v[164:165], off
	v_lshl_add_u64 v[200:201], s[62:63], 0, v[96:97]
	s_mov_b32 m0, s67
	v_lshl_add_u64 v[224:225], s[30:31], 0, v[132:133]
	global_load_lds_dwordx4 v[200:201], off
	v_lshl_add_u64 v[200:201], s[62:63], 0, v[134:135]
	s_add_i32 m0, s67, 0x2000
	s_nop 0
	global_load_lds_dwordx4 v[200:201], off
	v_lshl_add_u64 v[200:201], s[30:31], 0, v[130:131]
	s_mov_b32 m0, s40
	s_nop 0
	global_load_lds_dwordx4 v[200:201], off
	s_mov_b32 m0, s41
	s_nop 0
	global_load_lds_dwordx4 v[224:225], off
	s_waitcnt vmcnt(8)
	s_waitcnt lgkmcnt(0)
	s_setprio 1
	s_barrier
; #define PG8_STAGE(bufoff, gbase, voff) do { _Pragma("unroll") for (int _i = 0; _i < 2; ++_i) \
;         __builtin_amdgcn_global_load_lds((const unsigned*)((const char*)(gbase) + (voff)[_i]), (PG8_LAS unsigned*)(lds + (bufoff) + ldsw + _i * 8192), 16, 0, 0); } while (0)
; #define PG8_LDA(dst, b, h) do { _Pragma("unroll") for (int m = 0; m < 4; ++m) _Pragma("unroll") for (int k = 0; k < 2; ++k) dst[m][k] = *(const PG8_LAS bf16x8*)(lds + PG8_SA(b, h) + aoff + m * 2048 + k * 1024); } while (0)
; #define PG8_LDB(dst, b, h) do { _Pragma("unroll") for (int n = 0; n < 2; ++n) _Pragma("unroll") for (int k = 0; k < 2; ++k) dst[n][k] = *(const PG8_LAS bf16x8*)(lds + PG8_SB(b, h) + boff + n * 2048 + k * 1024); } while (0)
; #define PG8_MMA(ai, bj, At, Bt) do { __builtin_amdgcn_s_setprio(1); _Pragma("unroll") for (int m = 0; m < 4; ++m) _Pragma("unroll") for (int n = 0; n < 2; ++n) _Pragma("unroll") for (int k = 0; k < 2; ++k) \
;         acc[ai][bj][m][n] = __builtin_amdgcn_mfma_f32_16x16x32_bf16(Bt[n][k], At[m][k], acc[ai][bj][m][n], 0, 0, 0); __builtin_amdgcn_s_setprio(0); } while (0)
; #define PG8_WAIT_V(n) asm volatile("s_waitcnt vmcnt(" #n ")" ::: "memory")
; #define PG8_WAIT_L(n) asm volatile("s_waitcnt lgkmcnt(" #n ")" ::: "memory")
; #define PG8_BAR __builtin_amdgcn_s_barrier()
; #define PG8_SCHED __builtin_amdgcn_sched_barrier(0)
; template <class Epi, class Sched, bool ALIGN_EPI = false, bool SP2 = false>
; __device__ __forceinline__ void gemm_phase(PG8_LAS unsigned char* lds, const Gemm g, const Sched& S, const Epi& E, int tid_in) {
;     ...
;             PG8_WAIT_V(8); PG8_WAIT_L(0); PG8_BAR; PG8_MMA(1, 0, At, B0); PG8_MMA(1, 1, At, B1); PG8_BAR; PG8_SCHED;
;             PG8_LDB(B0, 1, 0); PG8_LDB(B1, 1, 1); PG8_SCHED; PG8_LDA(At, 1, 0); PG8_STAGE(PG8_SA(0, 1), a2 + hstep, voffA);
;             PG8_WAIT_V(8); PG8_WAIT_L(0); PG8_BAR; PG8_MMA(0, 0, At, B0); PG8_MMA(0, 1, At, B1); PG8_BAR; PG8_SCHED;
	v_mfma_f32_16x16x32_bf16 v[60:63], v[140:143], v[188:191], v[60:63]
	v_mfma_f32_16x16x32_bf16 v[56:59], v[156:159], v[188:191], v[56:59]
	v_mfma_f32_16x16x32_bf16 v[44:47], v[140:143], v[196:199], v[44:47]
	v_mfma_f32_16x16x32_bf16 v[40:43], v[156:159], v[196:199], v[40:43]
	v_mfma_f32_16x16x32_bf16 v[28:31], v[140:143], v[208:211], v[28:31]
	v_mfma_f32_16x16x32_bf16 v[24:27], v[156:159], v[208:211], v[24:27]
	v_mfma_f32_16x16x32_bf16 v[12:15], v[140:143], v[216:219], v[12:15]
	v_mfma_f32_16x16x32_bf16 v[8:11], v[156:159], v[216:219], v[8:11]
	v_mfma_f32_16x16x32_bf16 v[60:63], v[152:155], v[192:195], v[60:63]
	v_mfma_f32_16x16x32_bf16 v[56:59], v[160:163], v[192:195], v[56:59]
	v_mfma_f32_16x16x32_bf16 v[44:47], v[152:155], v[204:207], v[44:47]
	v_mfma_f32_16x16x32_bf16 v[40:43], v[160:163], v[204:207], v[40:43]
	v_mfma_f32_16x16x32_bf16 v[28:31], v[152:155], v[212:215], v[28:31]
	v_mfma_f32_16x16x32_bf16 v[24:27], v[160:163], v[212:215], v[24:27]
	v_mfma_f32_16x16x32_bf16 v[12:15], v[152:155], v[220:223], v[12:15]
	v_mfma_f32_16x16x32_bf16 v[8:11], v[160:163], v[220:223], v[8:11]
	s_setprio 0
	s_setprio 1
	v_mfma_f32_16x16x32_bf16 v[52:55], v[172:175], v[188:191], v[52:55]
	v_mfma_f32_16x16x32_bf16 v[48:51], v[180:183], v[188:191], v[48:51]
	v_mfma_f32_16x16x32_bf16 v[36:39], v[172:175], v[196:199], v[36:39]
	v_mfma_f32_16x16x32_bf16 v[32:35], v[180:183], v[196:199], v[32:35]
	v_mfma_f32_16x16x32_bf16 v[20:23], v[172:175], v[208:211], v[20:23]
	v_mfma_f32_16x16x32_bf16 v[16:19], v[180:183], v[208:211], v[16:19]
	v_mfma_f32_16x16x32_bf16 v[4:7], v[172:175], v[216:219], v[4:7]
	v_mfma_f32_16x16x32_bf16 v[0:3], v[180:183], v[216:219], v[0:3]
	v_mfma_f32_16x16x32_bf16 v[52:55], v[176:179], v[192:195], v[52:55]
	v_mfma_f32_16x16x32_bf16 v[48:51], v[184:187], v[192:195], v[48:51]
	v_mfma_f32_16x16x32_bf16 v[36:39], v[176:179], v[204:207], v[36:39]
	v_mfma_f32_16x16x32_bf16 v[32:35], v[184:187], v[204:207], v[32:35]
	v_mfma_f32_16x16x32_bf16 v[20:23], v[176:179], v[212:215], v[20:23]
	v_mfma_f32_16x16x32_bf16 v[16:19], v[184:187], v[212:215], v[16:19]
	v_mfma_f32_16x16x32_bf16 v[4:7], v[176:179], v[220:223], v[4:7]
	v_mfma_f32_16x16x32_bf16 v[0:3], v[184:187], v[220:223], v[0:3]
	s_barrier
	s_setprio 0
	s_add_i32 s62, 0, 0x18000
	v_add_u32_e32 v151, s62, v148
	s_add_i32 s63, 0, 0x1c000
	ds_read_b128 v[140:143], v151
	ds_read_b128 v[152:155], v151 offset:1024
	ds_read_b128 v[156:159], v151 offset:2048
	ds_read_b128 v[160:163], v151 offset:3072
	v_add_u32_e32 v151, s63, v148
	ds_read_b128 v[172:175], v151
	ds_read_b128 v[176:179], v151 offset:1024
	ds_read_b128 v[180:183], v151 offset:2048
	ds_read_b128 v[184:187], v151 offset:3072
	s_add_u32 s30, s30, 0x80000
	s_addc_u32 s31, s31, 0
	s_mov_b32 m0, s42
	v_lshl_add_u64 v[226:227], s[30:31], 0, v[130:131]
	ds_read_b128 v[188:191], v150 offset:32768
	ds_read_b128 v[192:195], v150 offset:33792
	ds_read_b128 v[196:199], v150 offset:34816
	ds_read_b128 v[204:207], v150 offset:35840
	ds_read_b128 v[208:211], v150 offset:36864
	ds_read_b128 v[212:215], v150 offset:37888
	ds_read_b128 v[216:219], v150 offset:38912
	ds_read_b128 v[220:223], v150 offset:39936
	global_load_lds_dwordx4 v[226:227], off
	v_lshl_add_u64 v[226:227], s[30:31], 0, v[132:133]
	s_mov_b32 m0, s43
	s_nop 0
	global_load_lds_dwordx4 v[226:227], off
	s_waitcnt vmcnt(8)
	s_waitcnt lgkmcnt(0)
	s_setprio 1
	s_barrier
	v_mfma_f32_16x16x32_bf16 v[126:129], v[140:143], v[188:191], v[126:129]
	v_mfma_f32_16x16x32_bf16 v[122:125], v[156:159], v[188:191], v[122:125]
	v_mfma_f32_16x16x32_bf16 v[110:113], v[140:143], v[196:199], v[110:113]
	v_mfma_f32_16x16x32_bf16 v[106:109], v[156:159], v[196:199], v[106:109]
	v_mfma_f32_16x16x32_bf16 v[92:95], v[140:143], v[208:211], v[92:95]
	v_mfma_f32_16x16x32_bf16 v[88:91], v[156:159], v[208:211], v[88:91]
	v_mfma_f32_16x16x32_bf16 v[76:79], v[140:143], v[216:219], v[76:79]
	v_mfma_f32_16x16x32_bf16 v[72:75], v[156:159], v[216:219], v[72:75]
	v_mfma_f32_16x16x32_bf16 v[126:129], v[152:155], v[192:195], v[126:129]
	v_mfma_f32_16x16x32_bf16 v[122:125], v[160:163], v[192:195], v[122:125]
	v_mfma_f32_16x16x32_bf16 v[110:113], v[152:155], v[204:207], v[110:113]
	v_mfma_f32_16x16x32_bf16 v[106:109], v[160:163], v[204:207], v[106:109]
	v_mfma_f32_16x16x32_bf16 v[92:95], v[152:155], v[212:215], v[92:95]
	v_mfma_f32_16x16x32_bf16 v[88:91], v[160:163], v[212:215], v[88:91]
	v_mfma_f32_16x16x32_bf16 v[76:79], v[152:155], v[220:223], v[76:79]
	v_mfma_f32_16x16x32_bf16 v[72:75], v[160:163], v[220:223], v[72:75]
	s_setprio 0
	s_setprio 1
	v_mfma_f32_16x16x32_bf16 v[118:121], v[172:175], v[188:191], v[118:121]
	v_mfma_f32_16x16x32_bf16 v[114:117], v[180:183], v[188:191], v[114:117]
	v_mfma_f32_16x16x32_bf16 v[102:105], v[172:175], v[196:199], v[102:105]
	v_mfma_f32_16x16x32_bf16 v[98:101], v[180:183], v[196:199], v[98:101]
	v_mfma_f32_16x16x32_bf16 v[84:87], v[172:175], v[208:211], v[84:87]
	v_mfma_f32_16x16x32_bf16 v[80:83], v[180:183], v[208:211], v[80:83]
	v_mfma_f32_16x16x32_bf16 v[68:71], v[172:175], v[216:219], v[68:71]
	v_mfma_f32_16x16x32_bf16 v[64:67], v[180:183], v[216:219], v[64:67]
	v_mfma_f32_16x16x32_bf16 v[118:121], v[176:179], v[192:195], v[118:121]
	v_mfma_f32_16x16x32_bf16 v[114:117], v[184:187], v[192:195], v[114:117]
	v_mfma_f32_16x16x32_bf16 v[102:105], v[176:179], v[204:207], v[102:105]
	v_mfma_f32_16x16x32_bf16 v[98:101], v[184:187], v[204:207], v[98:101]
	v_mfma_f32_16x16x32_bf16 v[84:87], v[176:179], v[212:215], v[84:87]
	v_mfma_f32_16x16x32_bf16 v[80:83], v[184:187], v[212:215], v[80:83]
	v_mfma_f32_16x16x32_bf16 v[68:71], v[176:179], v[220:223], v[68:71]
	v_mfma_f32_16x16x32_bf16 v[64:67], v[184:187], v[220:223], v[64:67]
	s_barrier
; #define PG8_STAGE(bufoff, gbase, voff) do { _Pragma("unroll") for (int _i = 0; _i < 2; ++_i) \
;         __builtin_amdgcn_global_load_lds((const unsigned*)((const char*)(gbase) + (voff)[_i]), (PG8_LAS unsigned*)(lds + (bufoff) + ldsw + _i * 8192), 16, 0, 0); } while (0)
; #define PG8_LDA(dst, b, h) do { _Pragma("unroll") for (int m = 0; m < 4; ++m) _Pragma("unroll") for (int k = 0; k < 2; ++k) dst[m][k] = *(const PG8_LAS bf16x8*)(lds + PG8_SA(b, h) + aoff + m * 2048 + k * 1024); } while (0)
; #define PG8_MMA(ai, bj, At, Bt) do { __builtin_amdgcn_s_setprio(1); _Pragma("unroll") for (int m = 0; m < 4; ++m) _Pragma("unroll") for (int n = 0; n < 2; ++n) _Pragma("unroll") for (int k = 0; k < 2; ++k) \
;         acc[ai][bj][m][n] = __builtin_amdgcn_mfma_f32_16x16x32_bf16(Bt[n][k], At[m][k], acc[ai][bj][m][n], 0, 0, 0); __builtin_amdgcn_s_setprio(0); } while (0)
; #define PG8_WAIT_V(n) asm volatile("s_waitcnt vmcnt(" #n ")" ::: "memory")
; #define PG8_WAIT_L(n) asm volatile("s_waitcnt lgkmcnt(" #n ")" ::: "memory")
; #define PG8_BAR __builtin_amdgcn_s_barrier()
; #define PG8_SCHED __builtin_amdgcn_sched_barrier(0)
; template <class Epi, class Sched, bool ALIGN_EPI = false, bool SP2 = false>
; __device__ __forceinline__ void gemm_phase(PG8_LAS unsigned char* lds, const Gemm g, const Sched& S, const Epi& E, int tid_in) {
;     ...
;             PG8_LDA(At, 1, 1); PG8_STAGE(PG8_SB(1, 0), b3, voffB); PG8_STAGE(PG8_SB(1, 1), b3 + hstep, voffB); PG8_STAGE(PG8_SA(1, 0), a3, voffA);
;             PG8_WAIT_V(8); PG8_WAIT_L(0); PG8_BAR; PG8_MMA(1, 0, At, B0); PG8_MMA(1, 1, At, B1); PG8_BAR; PG8_SCHED;
;     ...
;         if constexpr (ALIGN_EPI) { if (wr == 0) PG8_BAR; }
	s_setprio 0
	s_add_i32 s30, s62, s39
	v_lshl_add_u64 v[144:145], v[144:145], 0, s[88:89]
	s_mov_b32 m0, s30
	ds_read_b128 v[188:191], v150 offset:49152
	ds_read_b128 v[192:195], v150 offset:50176
	ds_read_b128 v[196:199], v150 offset:51200
	ds_read_b128 v[204:207], v150 offset:52224
	ds_read_b128 v[208:211], v150 offset:53248
	ds_read_b128 v[212:215], v150 offset:54272
	ds_read_b128 v[216:219], v150 offset:55296
	ds_read_b128 v[220:223], v150 offset:56320
	global_load_lds_dwordx4 v[144:145], off
	s_add_i32 m0, s30, 0x2000
	s_add_u32 s28, s28, 0x80080
	v_lshl_add_u64 v[144:145], v[164:165], 0, s[88:89]
	s_addc_u32 s29, s29, 0
	s_add_i32 s30, s63, s39
	global_load_lds_dwordx4 v[144:145], off
	v_lshl_add_u64 v[144:145], s[28:29], 0, v[96:97]
	s_mov_b32 m0, s30
	s_nop 0
	global_load_lds_dwordx4 v[144:145], off
	v_lshl_add_u64 v[144:145], s[28:29], 0, v[134:135]
	s_add_i32 m0, s30, 0x2000
	s_nop 0
	global_load_lds_dwordx4 v[144:145], off
	v_lshl_add_u64 v[144:145], v[200:201], 0, s[88:89]
	s_mov_b32 m0, s44
	s_nop 0
	global_load_lds_dwordx4 v[144:145], off
	v_lshl_add_u64 v[144:145], v[224:225], 0, s[88:89]
	s_mov_b32 m0, s45
	s_nop 0
	global_load_lds_dwordx4 v[144:145], off
	s_waitcnt vmcnt(8)
	s_waitcnt lgkmcnt(0)
	s_setprio 1
	s_barrier
	v_mfma_f32_16x16x32_bf16 v[60:63], v[140:143], v[188:191], v[60:63]
	v_mfma_f32_16x16x32_bf16 v[56:59], v[156:159], v[188:191], v[56:59]
	v_mfma_f32_16x16x32_bf16 v[44:47], v[140:143], v[196:199], v[44:47]
	v_mfma_f32_16x16x32_bf16 v[40:43], v[156:159], v[196:199], v[40:43]
	v_mfma_f32_16x16x32_bf16 v[28:31], v[140:143], v[208:211], v[28:31]
	v_mfma_f32_16x16x32_bf16 v[24:27], v[156:159], v[208:211], v[24:27]
	v_mfma_f32_16x16x32_bf16 v[12:15], v[140:143], v[216:219], v[12:15]
	v_mfma_f32_16x16x32_bf16 v[8:11], v[156:159], v[216:219], v[8:11]
	v_mfma_f32_16x16x32_bf16 v[60:63], v[152:155], v[192:195], v[60:63]
	v_mfma_f32_16x16x32_bf16 v[56:59], v[160:163], v[192:195], v[56:59]
	v_mfma_f32_16x16x32_bf16 v[44:47], v[152:155], v[204:207], v[44:47]
	v_mfma_f32_16x16x32_bf16 v[40:43], v[160:163], v[204:207], v[40:43]
	v_mfma_f32_16x16x32_bf16 v[28:31], v[152:155], v[212:215], v[28:31]
	v_mfma_f32_16x16x32_bf16 v[24:27], v[160:163], v[212:215], v[24:27]
	v_mfma_f32_16x16x32_bf16 v[12:15], v[152:155], v[220:223], v[12:15]
	v_mfma_f32_16x16x32_bf16 v[8:11], v[160:163], v[220:223], v[8:11]
	s_setprio 0
	s_setprio 1
	v_mfma_f32_16x16x32_bf16 v[52:55], v[172:175], v[188:191], v[52:55]
	v_mfma_f32_16x16x32_bf16 v[48:51], v[180:183], v[188:191], v[48:51]
	v_mfma_f32_16x16x32_bf16 v[36:39], v[172:175], v[196:199], v[36:39]
	v_mfma_f32_16x16x32_bf16 v[32:35], v[180:183], v[196:199], v[32:35]
	v_mfma_f32_16x16x32_bf16 v[20:23], v[172:175], v[208:211], v[20:23]
	v_mfma_f32_16x16x32_bf16 v[16:19], v[180:183], v[208:211], v[16:19]
	v_mfma_f32_16x16x32_bf16 v[4:7], v[172:175], v[216:219], v[4:7]
	v_mfma_f32_16x16x32_bf16 v[0:3], v[180:183], v[216:219], v[0:3]
	v_mfma_f32_16x16x32_bf16 v[52:55], v[176:179], v[192:195], v[52:55]
	v_mfma_f32_16x16x32_bf16 v[48:51], v[184:187], v[192:195], v[48:51]
	v_mfma_f32_16x16x32_bf16 v[36:39], v[176:179], v[204:207], v[36:39]
	v_mfma_f32_16x16x32_bf16 v[32:35], v[184:187], v[204:207], v[32:35]
	v_mfma_f32_16x16x32_bf16 v[20:23], v[176:179], v[212:215], v[20:23]
	v_mfma_f32_16x16x32_bf16 v[16:19], v[184:187], v[212:215], v[16:19]
	v_mfma_f32_16x16x32_bf16 v[4:7], v[176:179], v[220:223], v[4:7]
	v_mfma_f32_16x16x32_bf16 v[0:3], v[184:187], v[220:223], v[0:3]
	s_barrier
	s_setprio 0
	s_add_i32 s66, s66, 2
	s_add_u32 s26, s26, 0x100
	s_addc_u32 s27, s27, 0
	s_add_u32 s64, s64, 0x100
	s_addc_u32 s65, s65, 0
	s_cmp_gt_u32 s66, 29
	s_cbranch_scc0 .LBB0_567
	s_and_b64 vcc, exec, s[14:15]
	s_cbranch_vccz .LBB0_570
	s_barrier

; #define PG8_STAGE(bufoff, gbase, voff) do { _Pragma("unroll") for (int _i = 0; _i < 2; ++_i) \
;         __builtin_amdgcn_global_load_lds((const unsigned*)((const char*)(gbase) + (voff)[_i]), (PG8_LAS unsigned*)(lds + (bufoff) + ldsw + _i * 8192), 16, 0, 0); } while (0)
; #define PG8_LDA(dst, b, h) do { _Pragma("unroll") for (int m = 0; m < 4; ++m) _Pragma("unroll") for (int k = 0; k < 2; ++k) dst[m][k] = *(const PG8_LAS bf16x8*)(lds + PG8_SA(b, h) + aoff + m * 2048 + k * 1024); } while (0)
; #define PG8_LDB(dst, b, h) do { _Pragma("unroll") for (int n = 0; n < 2; ++n) _Pragma("unroll") for (int k = 0; k < 2; ++k) dst[n][k] = *(const PG8_LAS bf16x8*)(lds + PG8_SB(b, h) + boff + n * 2048 + k * 1024); } while (0)
; #define PG8_MMA(ai, bj, At, Bt) do { __builtin_amdgcn_s_setprio(1); _Pragma("unroll") for (int m = 0; m < 4; ++m) _Pragma("unroll") for (int n = 0; n < 2; ++n) _Pragma("unroll") for (int k = 0; k < 2; ++k) \
;         acc[ai][bj][m][n] = __builtin_amdgcn_mfma_f32_16x16x32_bf16(Bt[n][k], At[m][k], acc[ai][bj][m][n], 0, 0, 0); __builtin_amdgcn_s_setprio(0); } while (0)
; #define PG8_WAIT_V(n) asm volatile("s_waitcnt vmcnt(" #n ")" ::: "memory")
; #define PG8_WAIT_L(n) asm volatile("s_waitcnt lgkmcnt(" #n ")" ::: "memory")
; template <class Epi, class Sched, bool ALIGN_EPI = false, bool SP2 = false>
; __device__ __forceinline__ void gemm_phase(PG8_LAS unsigned char* lds, const Gemm g, const Sched& S, const Epi& E, int tid_in) {
;     ...
;             const bool last = (t == nt - 2);
;             const char* a1 = cA + (size_t)(t + 1) * kstep;
;             const char* a2 = last ? nA : cA + (size_t)(t + 2) * kstep; const char* b2 = last ? nB : cB + (size_t)(t + 2) * kstep;
;             const char* a3 = a2 + kstep; const char* b3 = b2 + kstep;
;             if (last && has_next) S.a_ready(nxt);
;             if constexpr (SP2) {
;             PG8_LDB(B0, 0, 0); PG8_LDB(B1, 0, 1); PG8_SCHED; PG8_LDA(At, 0, 0); PG8_STAGE(PG8_SA(1, 1), a1 + hstep, voffA);
;             PG8_WAIT_V(8); PG8_WAIT_L(0); PG8_BAR; PG8_MMA(0, 0, At, B0); PG8_MMA(0, 1, At, B1); PG8_BAR; PG8_SCHED;
;             PG8_LDA(At, 0, 1); PG8_STAGE(PG8_SB(0, 0), b2, voffB); PG8_STAGE(PG8_SB(0, 1), b2 + hstep, voffB); PG8_STAGE(PG8_SA(0, 0), a2, voffA);
;             PG8_WAIT_V(8); PG8_WAIT_L(0); PG8_BAR; PG8_MMA(1, 0, At, B0); PG8_MMA(1, 1, At, B1); PG8_BAR; PG8_SCHED;
.LBB0_632:
	s_add_u32 s30, s28, 0xfff80080
	s_addc_u32 s31, s29, -1
	s_add_i32 s62, 0, 0x10000
	s_cmp_eq_u32 s72, 28
	s_cselect_b32 s35, s21, s31
	s_cselect_b32 s34, s67, s30
	v_add_u32_e32 v148, s62, v133
	s_cselect_b32 s31, s19, s71
	s_cselect_b32 s30, s69, s70
	s_add_i32 s73, 0, 0x14000
	ds_read_b128 v[144:147], v148
	ds_read_b128 v[158:161], v148 offset:1024
	ds_read_b128 v[162:165], v148 offset:2048
	ds_read_b128 v[172:175], v148 offset:3072
	v_add_u32_e32 v148, s73, v133
	ds_read_b128 v[176:179], v148
	ds_read_b128 v[180:183], v148 offset:1024
	ds_read_b128 v[184:187], v148 offset:2048
	ds_read_b128 v[188:191], v148 offset:3072
	v_lshl_add_u64 v[148:149], s[28:29], 0, v[140:141]
	s_add_i32 m0, s45, 0xc000
	ds_read_b128 v[192:195], v156
	ds_read_b128 v[196:199], v156 offset:1024
	ds_read_b128 v[204:207], v156 offset:2048
	ds_read_b128 v[208:211], v156 offset:3072
	ds_read_b128 v[212:215], v156 offset:4096
	ds_read_b128 v[216:219], v156 offset:5120
	ds_read_b128 v[220:223], v156 offset:6144
	ds_read_b128 v[224:227], v156 offset:7168
	global_load_lds_dwordx4 v[148:149], off
	v_lshl_add_u64 v[148:149], s[28:29], 0, v[142:143]
	s_add_i32 m0, s45, 0xe000
	s_nop 0
	global_load_lds_dwordx4 v[148:149], off
	s_waitcnt vmcnt(8)
	s_waitcnt lgkmcnt(0)
	s_setprio 1
	s_barrier
	v_mfma_f32_16x16x32_bf16 v[126:129], v[144:147], v[192:195], v[126:129]
	v_mfma_f32_16x16x32_bf16 v[122:125], v[162:165], v[192:195], v[122:125]
	v_mfma_f32_16x16x32_bf16 v[110:113], v[144:147], v[204:207], v[110:113]
	v_mfma_f32_16x16x32_bf16 v[106:109], v[162:165], v[204:207], v[106:109]
	v_mfma_f32_16x16x32_bf16 v[92:95], v[144:147], v[212:215], v[92:95]
	v_mfma_f32_16x16x32_bf16 v[88:91], v[162:165], v[212:215], v[88:91]
	v_mfma_f32_16x16x32_bf16 v[76:79], v[144:147], v[220:223], v[76:79]
	v_mfma_f32_16x16x32_bf16 v[72:75], v[162:165], v[220:223], v[72:75]
	v_mfma_f32_16x16x32_bf16 v[126:129], v[158:161], v[196:199], v[126:129]
	v_mfma_f32_16x16x32_bf16 v[122:125], v[172:175], v[196:199], v[122:125]
	v_mfma_f32_16x16x32_bf16 v[110:113], v[158:161], v[208:211], v[110:113]
	v_mfma_f32_16x16x32_bf16 v[106:109], v[172:175], v[208:211], v[106:109]
	v_mfma_f32_16x16x32_bf16 v[92:95], v[158:161], v[216:219], v[92:95]
	v_mfma_f32_16x16x32_bf16 v[88:91], v[172:175], v[216:219], v[88:91]
	v_mfma_f32_16x16x32_bf16 v[76:79], v[158:161], v[224:227], v[76:79]
	v_mfma_f32_16x16x32_bf16 v[72:75], v[172:175], v[224:227], v[72:75]
	s_setprio 0
	s_setprio 1
	v_mfma_f32_16x16x32_bf16 v[118:121], v[176:179], v[192:195], v[118:121]
	v_mfma_f32_16x16x32_bf16 v[114:117], v[184:187], v[192:195], v[114:117]
	v_mfma_f32_16x16x32_bf16 v[102:105], v[176:179], v[204:207], v[102:105]
	v_mfma_f32_16x16x32_bf16 v[98:101], v[184:187], v[204:207], v[98:101]
	v_mfma_f32_16x16x32_bf16 v[84:87], v[176:179], v[212:215], v[84:87]
	v_mfma_f32_16x16x32_bf16 v[80:83], v[184:187], v[212:215], v[80:83]
	v_mfma_f32_16x16x32_bf16 v[68:71], v[176:179], v[220:223], v[68:71]
	v_mfma_f32_16x16x32_bf16 v[64:67], v[184:187], v[220:223], v[64:67]
	v_mfma_f32_16x16x32_bf16 v[118:121], v[180:183], v[196:199], v[118:121]
	v_mfma_f32_16x16x32_bf16 v[114:117], v[188:191], v[196:199], v[114:117]
	v_mfma_f32_16x16x32_bf16 v[102:105], v[180:183], v[208:211], v[102:105]
	v_mfma_f32_16x16x32_bf16 v[98:101], v[188:191], v[208:211], v[98:101]
	v_mfma_f32_16x16x32_bf16 v[84:87], v[180:183], v[216:219], v[84:87]
	v_mfma_f32_16x16x32_bf16 v[80:83], v[188:191], v[216:219], v[80:83]
	v_mfma_f32_16x16x32_bf16 v[68:71], v[180:183], v[224:227], v[68:71]
	v_mfma_f32_16x16x32_bf16 v[64:67], v[188:191], v[224:227], v[64:67]
	s_barrier
	s_setprio 0
	s_add_i32 s62, s62, s44
	v_lshl_add_u64 v[148:149], s[30:31], 0, v[96:97]
	s_mov_b32 m0, s62
	ds_read_b128 v[192:195], v156 offset:16384
	ds_read_b128 v[196:199], v156 offset:17408
	ds_read_b128 v[204:207], v156 offset:18432
	ds_read_b128 v[208:211], v156 offset:19456
	ds_read_b128 v[212:215], v156 offset:20480
	ds_read_b128 v[216:219], v156 offset:21504
	ds_read_b128 v[220:223], v156 offset:22528
	ds_read_b128 v[224:227], v156 offset:23552
	global_load_lds_dwordx4 v[148:149], off
	s_add_i32 m0, s62, 0x2000
	s_add_u32 s62, s30, 0x80000
	v_lshl_add_u64 v[200:201], s[30:31], 0, v[138:139]
	s_addc_u32 s63, s31, 0
	s_add_i32 s73, s73, s44
	global_load_lds_dwordx4 v[200:201], off
	v_lshl_add_u64 v[228:229], s[62:63], 0, v[96:97]
	s_mov_b32 m0, s73
	v_lshl_add_u64 v[230:231], s[34:35], 0, v[136:137]
	global_load_lds_dwordx4 v[228:229], off
	v_lshl_add_u64 v[228:229], s[62:63], 0, v[138:139]
	s_add_i32 m0, s73, 0x2000
	s_nop 0
	global_load_lds_dwordx4 v[228:229], off
	v_lshl_add_u64 v[228:229], s[34:35], 0, v[134:135]
	s_mov_b32 m0, s45
	s_nop 0
	global_load_lds_dwordx4 v[228:229], off
	s_mov_b32 m0, s46
	s_nop 0
	global_load_lds_dwordx4 v[230:231], off
	s_waitcnt vmcnt(8)
	s_waitcnt lgkmcnt(0)
	s_setprio 1
	s_barrier
; #define PG8_STAGE(bufoff, gbase, voff) do { _Pragma("unroll") for (int _i = 0; _i < 2; ++_i) \
;         __builtin_amdgcn_global_load_lds((const unsigned*)((const char*)(gbase) + (voff)[_i]), (PG8_LAS unsigned*)(lds + (bufoff) + ldsw + _i * 8192), 16, 0, 0); } while (0)
; #define PG8_LDA(dst, b, h) do { _Pragma("unroll") for (int m = 0; m < 4; ++m) _Pragma("unroll") for (int k = 0; k < 2; ++k) dst[m][k] = *(const PG8_LAS bf16x8*)(lds + PG8_SA(b, h) + aoff + m * 2048 + k * 1024); } while (0)
; #define PG8_LDB(dst, b, h) do { _Pragma("unroll") for (int n = 0; n < 2; ++n) _Pragma("unroll") for (int k = 0; k < 2; ++k) dst[n][k] = *(const PG8_LAS bf16x8*)(lds + PG8_SB(b, h) + boff + n * 2048 + k * 1024); } while (0)
; #define PG8_MMA(ai, bj, At, Bt) do { __builtin_amdgcn_s_setprio(1); _Pragma("unroll") for (int m = 0; m < 4; ++m) _Pragma("unroll") for (int n = 0; n < 2; ++n) _Pragma("unroll") for (int k = 0; k < 2; ++k) \
;         acc[ai][bj][m][n] = __builtin_amdgcn_mfma_f32_16x16x32_bf16(Bt[n][k], At[m][k], acc[ai][bj][m][n], 0, 0, 0); __builtin_amdgcn_s_setprio(0); } while (0)
; #define PG8_WAIT_V(n) asm volatile("s_waitcnt vmcnt(" #n ")" ::: "memory")
; #define PG8_WAIT_L(n) asm volatile("s_waitcnt lgkmcnt(" #n ")" ::: "memory")
; #define PG8_BAR __builtin_amdgcn_s_barrier()
; #define PG8_SCHED __builtin_amdgcn_sched_barrier(0)
; template <class Epi, class Sched, bool ALIGN_EPI = false, bool SP2 = false>
; __device__ __forceinline__ void gemm_phase(PG8_LAS unsigned char* lds, const Gemm g, const Sched& S, const Epi& E, int tid_in) {
;     ...
;             PG8_WAIT_V(8); PG8_WAIT_L(0); PG8_BAR; PG8_MMA(1, 0, At, B0); PG8_MMA(1, 1, At, B1); PG8_BAR; PG8_SCHED;
;             PG8_LDB(B0, 1, 0); PG8_LDB(B1, 1, 1); PG8_SCHED; PG8_LDA(At, 1, 0); PG8_STAGE(PG8_SA(0, 1), a2 + hstep, voffA);
;             PG8_WAIT_V(8); PG8_WAIT_L(0); PG8_BAR; PG8_MMA(0, 0, At, B0); PG8_MMA(0, 1, At, B1); PG8_BAR; PG8_SCHED;
	v_mfma_f32_16x16x32_bf16 v[60:63], v[144:147], v[192:195], v[60:63]
	v_mfma_f32_16x16x32_bf16 v[56:59], v[162:165], v[192:195], v[56:59]
	v_mfma_f32_16x16x32_bf16 v[44:47], v[144:147], v[204:207], v[44:47]
	v_mfma_f32_16x16x32_bf16 v[40:43], v[162:165], v[204:207], v[40:43]
	v_mfma_f32_16x16x32_bf16 v[28:31], v[144:147], v[212:215], v[28:31]
	v_mfma_f32_16x16x32_bf16 v[24:27], v[162:165], v[212:215], v[24:27]
	v_mfma_f32_16x16x32_bf16 v[12:15], v[144:147], v[220:223], v[12:15]
	v_mfma_f32_16x16x32_bf16 v[8:11], v[162:165], v[220:223], v[8:11]
	v_mfma_f32_16x16x32_bf16 v[60:63], v[158:161], v[196:199], v[60:63]
	v_mfma_f32_16x16x32_bf16 v[56:59], v[172:175], v[196:199], v[56:59]
	v_mfma_f32_16x16x32_bf16 v[44:47], v[158:161], v[208:211], v[44:47]
	v_mfma_f32_16x16x32_bf16 v[40:43], v[172:175], v[208:211], v[40:43]
	v_mfma_f32_16x16x32_bf16 v[28:31], v[158:161], v[216:219], v[28:31]
	v_mfma_f32_16x16x32_bf16 v[24:27], v[172:175], v[216:219], v[24:27]
	v_mfma_f32_16x16x32_bf16 v[12:15], v[158:161], v[224:227], v[12:15]
	v_mfma_f32_16x16x32_bf16 v[8:11], v[172:175], v[224:227], v[8:11]
	s_setprio 0
	s_setprio 1
	v_mfma_f32_16x16x32_bf16 v[52:55], v[176:179], v[192:195], v[52:55]
	v_mfma_f32_16x16x32_bf16 v[48:51], v[184:187], v[192:195], v[48:51]
	v_mfma_f32_16x16x32_bf16 v[36:39], v[176:179], v[204:207], v[36:39]
	v_mfma_f32_16x16x32_bf16 v[32:35], v[184:187], v[204:207], v[32:35]
	v_mfma_f32_16x16x32_bf16 v[20:23], v[176:179], v[212:215], v[20:23]
	v_mfma_f32_16x16x32_bf16 v[16:19], v[184:187], v[212:215], v[16:19]
	v_mfma_f32_16x16x32_bf16 v[4:7], v[176:179], v[220:223], v[4:7]
	v_mfma_f32_16x16x32_bf16 v[0:3], v[184:187], v[220:223], v[0:3]
	v_mfma_f32_16x16x32_bf16 v[52:55], v[180:183], v[196:199], v[52:55]
	v_mfma_f32_16x16x32_bf16 v[48:51], v[188:191], v[196:199], v[48:51]
	v_mfma_f32_16x16x32_bf16 v[36:39], v[180:183], v[208:211], v[36:39]
	v_mfma_f32_16x16x32_bf16 v[32:35], v[188:191], v[208:211], v[32:35]
	v_mfma_f32_16x16x32_bf16 v[20:23], v[180:183], v[216:219], v[20:23]
	v_mfma_f32_16x16x32_bf16 v[16:19], v[188:191], v[216:219], v[16:19]
	v_mfma_f32_16x16x32_bf16 v[4:7], v[180:183], v[224:227], v[4:7]
	v_mfma_f32_16x16x32_bf16 v[0:3], v[188:191], v[224:227], v[0:3]
	s_barrier
	s_setprio 0
	s_add_i32 s62, 0, 0x18000
	v_add_u32_e32 v157, s62, v133
	s_add_i32 s63, 0, 0x1c000
	ds_read_b128 v[144:147], v157
	ds_read_b128 v[158:161], v157 offset:1024
	ds_read_b128 v[162:165], v157 offset:2048
	ds_read_b128 v[172:175], v157 offset:3072
	v_add_u32_e32 v157, s63, v133
	ds_read_b128 v[176:179], v157
	ds_read_b128 v[180:183], v157 offset:1024
	ds_read_b128 v[184:187], v157 offset:2048
	ds_read_b128 v[188:191], v157 offset:3072
	s_add_u32 s34, s34, 0x80000
	s_addc_u32 s35, s35, 0
	s_mov_b32 m0, s47
	v_lshl_add_u64 v[232:233], s[34:35], 0, v[134:135]
	ds_read_b128 v[192:195], v156 offset:32768
	ds_read_b128 v[196:199], v156 offset:33792
	ds_read_b128 v[204:207], v156 offset:34816
	ds_read_b128 v[208:211], v156 offset:35840
	ds_read_b128 v[212:215], v156 offset:36864
	ds_read_b128 v[216:219], v156 offset:37888
	ds_read_b128 v[220:223], v156 offset:38912
	ds_read_b128 v[224:227], v156 offset:39936
	global_load_lds_dwordx4 v[232:233], off
	v_lshl_add_u64 v[232:233], s[34:35], 0, v[136:137]
	s_mov_b32 m0, s52
	s_nop 0
	global_load_lds_dwordx4 v[232:233], off
	s_waitcnt vmcnt(8)
	s_waitcnt lgkmcnt(0)
	s_setprio 1
	s_barrier
	v_mfma_f32_16x16x32_bf16 v[126:129], v[144:147], v[192:195], v[126:129]
	v_mfma_f32_16x16x32_bf16 v[122:125], v[162:165], v[192:195], v[122:125]
	v_mfma_f32_16x16x32_bf16 v[110:113], v[144:147], v[204:207], v[110:113]
	v_mfma_f32_16x16x32_bf16 v[106:109], v[162:165], v[204:207], v[106:109]
	v_mfma_f32_16x16x32_bf16 v[92:95], v[144:147], v[212:215], v[92:95]
	v_mfma_f32_16x16x32_bf16 v[88:91], v[162:165], v[212:215], v[88:91]
	v_mfma_f32_16x16x32_bf16 v[76:79], v[144:147], v[220:223], v[76:79]
	v_mfma_f32_16x16x32_bf16 v[72:75], v[162:165], v[220:223], v[72:75]
	v_mfma_f32_16x16x32_bf16 v[126:129], v[158:161], v[196:199], v[126:129]
	v_mfma_f32_16x16x32_bf16 v[122:125], v[172:175], v[196:199], v[122:125]
	v_mfma_f32_16x16x32_bf16 v[110:113], v[158:161], v[208:211], v[110:113]
	v_mfma_f32_16x16x32_bf16 v[106:109], v[172:175], v[208:211], v[106:109]
	v_mfma_f32_16x16x32_bf16 v[92:95], v[158:161], v[216:219], v[92:95]
	v_mfma_f32_16x16x32_bf16 v[88:91], v[172:175], v[216:219], v[88:91]
	v_mfma_f32_16x16x32_bf16 v[76:79], v[158:161], v[224:227], v[76:79]
	v_mfma_f32_16x16x32_bf16 v[72:75], v[172:175], v[224:227], v[72:75]
	s_setprio 0
	s_setprio 1
	v_mfma_f32_16x16x32_bf16 v[118:121], v[176:179], v[192:195], v[118:121]
	v_mfma_f32_16x16x32_bf16 v[114:117], v[184:187], v[192:195], v[114:117]
	v_mfma_f32_16x16x32_bf16 v[102:105], v[176:179], v[204:207], v[102:105]
	v_mfma_f32_16x16x32_bf16 v[98:101], v[184:187], v[204:207], v[98:101]
	v_mfma_f32_16x16x32_bf16 v[84:87], v[176:179], v[212:215], v[84:87]
	v_mfma_f32_16x16x32_bf16 v[80:83], v[184:187], v[212:215], v[80:83]
	v_mfma_f32_16x16x32_bf16 v[68:71], v[176:179], v[220:223], v[68:71]
	v_mfma_f32_16x16x32_bf16 v[64:67], v[184:187], v[220:223], v[64:67]
	v_mfma_f32_16x16x32_bf16 v[118:121], v[180:183], v[196:199], v[118:121]
	v_mfma_f32_16x16x32_bf16 v[114:117], v[188:191], v[196:199], v[114:117]
	v_mfma_f32_16x16x32_bf16 v[102:105], v[180:183], v[208:211], v[102:105]
	v_mfma_f32_16x16x32_bf16 v[98:101], v[188:191], v[208:211], v[98:101]
	v_mfma_f32_16x16x32_bf16 v[84:87], v[180:183], v[216:219], v[84:87]
	v_mfma_f32_16x16x32_bf16 v[80:83], v[188:191], v[216:219], v[80:83]
	v_mfma_f32_16x16x32_bf16 v[68:71], v[180:183], v[224:227], v[68:71]
	v_mfma_f32_16x16x32_bf16 v[64:67], v[188:191], v[224:227], v[64:67]
	s_barrier
; #define PG8_STAGE(bufoff, gbase, voff) do { _Pragma("unroll") for (int _i = 0; _i < 2; ++_i) \
;         __builtin_amdgcn_global_load_lds((const unsigned*)((const char*)(gbase) + (voff)[_i]), (PG8_LAS unsigned*)(lds + (bufoff) + ldsw + _i * 8192), 16, 0, 0); } while (0)
; #define PG8_LDA(dst, b, h) do { _Pragma("unroll") for (int m = 0; m < 4; ++m) _Pragma("unroll") for (int k = 0; k < 2; ++k) dst[m][k] = *(const PG8_LAS bf16x8*)(lds + PG8_SA(b, h) + aoff + m * 2048 + k * 1024); } while (0)
; #define PG8_MMA(ai, bj, At, Bt) do { __builtin_amdgcn_s_setprio(1); _Pragma("unroll") for (int m = 0; m < 4; ++m) _Pragma("unroll") for (int n = 0; n < 2; ++n) _Pragma("unroll") for (int k = 0; k < 2; ++k) \
;         acc[ai][bj][m][n] = __builtin_amdgcn_mfma_f32_16x16x32_bf16(Bt[n][k], At[m][k], acc[ai][bj][m][n], 0, 0, 0); __builtin_amdgcn_s_setprio(0); } while (0)
; #define PG8_WAIT_V(n) asm volatile("s_waitcnt vmcnt(" #n ")" ::: "memory")
; #define PG8_WAIT_L(n) asm volatile("s_waitcnt lgkmcnt(" #n ")" ::: "memory")
; #define PG8_BAR __builtin_amdgcn_s_barrier()
; #define PG8_SCHED __builtin_amdgcn_sched_barrier(0)
; template <class Epi, class Sched, bool ALIGN_EPI = false, bool SP2 = false>
; __device__ __forceinline__ void gemm_phase(PG8_LAS unsigned char* lds, const Gemm g, const Sched& S, const Epi& E, int tid_in) {
;     ...
;             PG8_LDA(At, 1, 1); PG8_STAGE(PG8_SB(1, 0), b3, voffB); PG8_STAGE(PG8_SB(1, 1), b3 + hstep, voffB); PG8_STAGE(PG8_SA(1, 0), a3, voffA);
;             PG8_WAIT_V(8); PG8_WAIT_L(0); PG8_BAR; PG8_MMA(1, 0, At, B0); PG8_MMA(1, 1, At, B1); PG8_BAR; PG8_SCHED;
;     ...
;         if constexpr (ALIGN_EPI) { if (wr == 0) PG8_BAR; }
	s_setprio 0
	s_add_i32 s34, s62, s44
	v_lshl_add_u64 v[148:149], v[148:149], 0, s[88:89]
	s_mov_b32 m0, s34
	ds_read_b128 v[192:195], v156 offset:49152
	ds_read_b128 v[196:199], v156 offset:50176
	ds_read_b128 v[204:207], v156 offset:51200
	ds_read_b128 v[208:211], v156 offset:52224
	ds_read_b128 v[212:215], v156 offset:53248
	ds_read_b128 v[216:219], v156 offset:54272
	ds_read_b128 v[220:223], v156 offset:55296
	ds_read_b128 v[224:227], v156 offset:56320
	global_load_lds_dwordx4 v[148:149], off
	s_add_i32 m0, s34, 0x2000
	s_add_u32 s30, s30, 0x80080
	v_lshl_add_u64 v[148:149], v[200:201], 0, s[88:89]
	s_addc_u32 s31, s31, 0
	s_add_i32 s34, s63, s44
	global_load_lds_dwordx4 v[148:149], off
	v_lshl_add_u64 v[148:149], s[30:31], 0, v[96:97]
	s_mov_b32 m0, s34
	s_nop 0
	global_load_lds_dwordx4 v[148:149], off
	v_lshl_add_u64 v[148:149], s[30:31], 0, v[138:139]
	s_add_i32 m0, s34, 0x2000
	s_nop 0
	global_load_lds_dwordx4 v[148:149], off
	v_lshl_add_u64 v[148:149], v[228:229], 0, s[88:89]
	s_mov_b32 m0, s64
	s_nop 0
	global_load_lds_dwordx4 v[148:149], off
	v_lshl_add_u64 v[148:149], v[230:231], 0, s[88:89]
	s_mov_b32 m0, s65
	s_nop 0
	global_load_lds_dwordx4 v[148:149], off
	s_waitcnt vmcnt(8)
	s_waitcnt lgkmcnt(0)
	s_setprio 1
	s_barrier
	v_mfma_f32_16x16x32_bf16 v[60:63], v[144:147], v[192:195], v[60:63]
	v_mfma_f32_16x16x32_bf16 v[56:59], v[162:165], v[192:195], v[56:59]
	v_mfma_f32_16x16x32_bf16 v[44:47], v[144:147], v[204:207], v[44:47]
	v_mfma_f32_16x16x32_bf16 v[40:43], v[162:165], v[204:207], v[40:43]
	v_mfma_f32_16x16x32_bf16 v[28:31], v[144:147], v[212:215], v[28:31]
	v_mfma_f32_16x16x32_bf16 v[24:27], v[162:165], v[212:215], v[24:27]
	v_mfma_f32_16x16x32_bf16 v[12:15], v[144:147], v[220:223], v[12:15]
	v_mfma_f32_16x16x32_bf16 v[8:11], v[162:165], v[220:223], v[8:11]
	v_mfma_f32_16x16x32_bf16 v[60:63], v[158:161], v[196:199], v[60:63]
	v_mfma_f32_16x16x32_bf16 v[56:59], v[172:175], v[196:199], v[56:59]
	v_mfma_f32_16x16x32_bf16 v[44:47], v[158:161], v[208:211], v[44:47]
	v_mfma_f32_16x16x32_bf16 v[40:43], v[172:175], v[208:211], v[40:43]
	v_mfma_f32_16x16x32_bf16 v[28:31], v[158:161], v[216:219], v[28:31]
	v_mfma_f32_16x16x32_bf16 v[24:27], v[172:175], v[216:219], v[24:27]
	v_mfma_f32_16x16x32_bf16 v[12:15], v[158:161], v[224:227], v[12:15]
	v_mfma_f32_16x16x32_bf16 v[8:11], v[172:175], v[224:227], v[8:11]
	s_setprio 0
	s_setprio 1
	v_mfma_f32_16x16x32_bf16 v[52:55], v[176:179], v[192:195], v[52:55]
	v_mfma_f32_16x16x32_bf16 v[48:51], v[184:187], v[192:195], v[48:51]
	v_mfma_f32_16x16x32_bf16 v[36:39], v[176:179], v[204:207], v[36:39]
	v_mfma_f32_16x16x32_bf16 v[32:35], v[184:187], v[204:207], v[32:35]
	v_mfma_f32_16x16x32_bf16 v[20:23], v[176:179], v[212:215], v[20:23]
	v_mfma_f32_16x16x32_bf16 v[16:19], v[184:187], v[212:215], v[16:19]
	v_mfma_f32_16x16x32_bf16 v[4:7], v[176:179], v[220:223], v[4:7]
	v_mfma_f32_16x16x32_bf16 v[0:3], v[184:187], v[220:223], v[0:3]
	v_mfma_f32_16x16x32_bf16 v[52:55], v[180:183], v[196:199], v[52:55]
	v_mfma_f32_16x16x32_bf16 v[48:51], v[188:191], v[196:199], v[48:51]
	v_mfma_f32_16x16x32_bf16 v[36:39], v[180:183], v[208:211], v[36:39]
	v_mfma_f32_16x16x32_bf16 v[32:35], v[188:191], v[208:211], v[32:35]
	v_mfma_f32_16x16x32_bf16 v[20:23], v[180:183], v[216:219], v[20:23]
	v_mfma_f32_16x16x32_bf16 v[16:19], v[188:191], v[216:219], v[16:19]
	v_mfma_f32_16x16x32_bf16 v[4:7], v[180:183], v[224:227], v[4:7]
	v_mfma_f32_16x16x32_bf16 v[0:3], v[188:191], v[224:227], v[0:3]
	s_barrier
	s_setprio 0
	s_add_i32 s72, s72, 2
	s_add_u32 s28, s28, 0x100
	s_addc_u32 s29, s29, 0
	s_add_u32 s70, s70, 0x100
	s_addc_u32 s71, s71, 0
	s_cmp_gt_u32 s72, 29
	s_cbranch_scc0 .LBB0_632
	v_readlane_b32 s70, v255, 33
	s_and_b64 vcc, exec, s[16:17]
	v_readlane_b32 s71, v255, 34
	s_cbranch_vccz .LBB0_635
	s_barrier

; #define PG8_STAGE(bufoff, gbase, voff) do { _Pragma("unroll") for (int _i = 0; _i < 2; ++_i) \
;         __builtin_amdgcn_global_load_lds((const unsigned*)((const char*)(gbase) + (voff)[_i]), (PG8_LAS unsigned*)(lds + (bufoff) + ldsw + _i * 8192), 16, 0, 0); } while (0)
; #define PG8_LDA(dst, b, h) do { _Pragma("unroll") for (int m = 0; m < 4; ++m) _Pragma("unroll") for (int k = 0; k < 2; ++k) dst[m][k] = *(const PG8_LAS bf16x8*)(lds + PG8_SA(b, h) + aoff + m * 2048 + k * 1024); } while (0)
; #define PG8_LDB(dst, b, h) do { _Pragma("unroll") for (int n = 0; n < 2; ++n) _Pragma("unroll") for (int k = 0; k < 2; ++k) dst[n][k] = *(const PG8_LAS bf16x8*)(lds + PG8_SB(b, h) + boff + n * 2048 + k * 1024); } while (0)
; #define PG8_MMA(ai, bj, At, Bt) do { __builtin_amdgcn_s_setprio(1); _Pragma("unroll") for (int m = 0; m < 4; ++m) _Pragma("unroll") for (int n = 0; n < 2; ++n) _Pragma("unroll") for (int k = 0; k < 2; ++k) \
;         acc[ai][bj][m][n] = __builtin_amdgcn_mfma_f32_16x16x32_bf16(Bt[n][k], At[m][k], acc[ai][bj][m][n], 0, 0, 0); __builtin_amdgcn_s_setprio(0); } while (0)
; #define PG8_WAIT_V(n) asm volatile("s_waitcnt vmcnt(" #n ")" ::: "memory")
; #define PG8_WAIT_L(n) asm volatile("s_waitcnt lgkmcnt(" #n ")" ::: "memory")
; template <class Epi, class Sched, bool ALIGN_EPI = false, bool SP2 = false>
; __device__ __forceinline__ void gemm_phase(PG8_LAS unsigned char* lds, const Gemm g, const Sched& S, const Epi& E, int tid_in) {
;     ...
;             const bool last = (t == nt - 2);
;             const char* a1 = cA + (size_t)(t + 1) * kstep;
;             const char* a2 = last ? nA : cA + (size_t)(t + 2) * kstep; const char* b2 = last ? nB : cB + (size_t)(t + 2) * kstep;
;             const char* a3 = a2 + kstep; const char* b3 = b2 + kstep;
;             if (last && has_next) S.a_ready(nxt);
;             if constexpr (SP2) {
;             PG8_LDB(B0, 0, 0); PG8_LDB(B1, 0, 1); PG8_SCHED; PG8_LDA(At, 0, 0); PG8_STAGE(PG8_SA(1, 1), a1 + hstep, voffA);
;             PG8_WAIT_V(8); PG8_WAIT_L(0); PG8_BAR; PG8_MMA(0, 0, At, B0); PG8_MMA(0, 1, At, B1); PG8_BAR; PG8_SCHED;
;             PG8_LDA(At, 0, 1); PG8_STAGE(PG8_SB(0, 0), b2, voffB); PG8_STAGE(PG8_SB(0, 1), b2 + hstep, voffB); PG8_STAGE(PG8_SA(0, 0), a2, voffA);
;             PG8_WAIT_V(8); PG8_WAIT_L(0); PG8_BAR; PG8_MMA(1, 0, At, B0); PG8_MMA(1, 1, At, B1); PG8_BAR; PG8_SCHED;
.LBB0_749:
	s_add_u32 s24, s22, 0xfff80080
	s_addc_u32 s25, s23, -1
	s_add_i32 s52, 0, 0x10000
	s_cmp_eq_u32 s47, 28
	s_cselect_b32 s27, s17, s25
	s_cselect_b32 s26, s43, s24
	v_add_u32_e32 v145, s52, v142
	s_cselect_b32 s25, s15, s46
	s_cselect_b32 s24, s44, s45
	s_add_i32 s64, 0, 0x14000
	ds_read_b128 v[146:149], v145
	ds_read_b128 v[150:153], v145 offset:1024
	ds_read_b128 v[154:157], v145 offset:2048
	ds_read_b128 v[158:161], v145 offset:3072
	v_add_u32_e32 v145, s64, v142
	ds_read_b128 v[162:165], v145
	ds_read_b128 v[172:175], v145 offset:1024
	ds_read_b128 v[176:179], v145 offset:2048
	ds_read_b128 v[180:183], v145 offset:3072
	v_lshl_add_u64 v[200:201], s[22:23], 0, v[136:137]
	s_add_i32 m0, s13, 0xc000
	ds_read_b128 v[184:187], v144
	ds_read_b128 v[188:191], v144 offset:1024
	ds_read_b128 v[192:195], v144 offset:2048
	ds_read_b128 v[196:199], v144 offset:3072
	ds_read_b128 v[204:207], v144 offset:4096
	ds_read_b128 v[208:211], v144 offset:5120
	ds_read_b128 v[212:215], v144 offset:6144
	ds_read_b128 v[216:219], v144 offset:7168
	global_load_lds_dwordx4 v[200:201], off
	v_lshl_add_u64 v[200:201], s[22:23], 0, v[138:139]
	s_add_i32 m0, s13, 0xe000
	s_nop 0
	global_load_lds_dwordx4 v[200:201], off
	s_waitcnt vmcnt(8)
	s_waitcnt lgkmcnt(0)
	s_setprio 1
	s_barrier
	v_mfma_f32_16x16x32_bf16 v[126:129], v[146:149], v[184:187], v[126:129]
	v_mfma_f32_16x16x32_bf16 v[122:125], v[154:157], v[184:187], v[122:125]
	v_mfma_f32_16x16x32_bf16 v[118:121], v[146:149], v[192:195], v[118:121]
	v_mfma_f32_16x16x32_bf16 v[114:117], v[154:157], v[192:195], v[114:117]
	v_mfma_f32_16x16x32_bf16 v[102:105], v[146:149], v[204:207], v[102:105]
	v_mfma_f32_16x16x32_bf16 v[98:101], v[154:157], v[204:207], v[98:101]
	v_mfma_f32_16x16x32_bf16 v[84:87], v[146:149], v[212:215], v[84:87]
	v_mfma_f32_16x16x32_bf16 v[80:83], v[154:157], v[212:215], v[80:83]
	v_mfma_f32_16x16x32_bf16 v[126:129], v[150:153], v[188:191], v[126:129]
	v_mfma_f32_16x16x32_bf16 v[122:125], v[158:161], v[188:191], v[122:125]
	v_mfma_f32_16x16x32_bf16 v[118:121], v[150:153], v[196:199], v[118:121]
	v_mfma_f32_16x16x32_bf16 v[114:117], v[158:161], v[196:199], v[114:117]
	v_mfma_f32_16x16x32_bf16 v[102:105], v[150:153], v[208:211], v[102:105]
	v_mfma_f32_16x16x32_bf16 v[98:101], v[158:161], v[208:211], v[98:101]
	v_mfma_f32_16x16x32_bf16 v[84:87], v[150:153], v[216:219], v[84:87]
	v_mfma_f32_16x16x32_bf16 v[80:83], v[158:161], v[216:219], v[80:83]
	s_setprio 0
	s_setprio 1
	v_mfma_f32_16x16x32_bf16 v[110:113], v[162:165], v[184:187], v[110:113]
	v_mfma_f32_16x16x32_bf16 v[106:109], v[176:179], v[184:187], v[106:109]
	v_mfma_f32_16x16x32_bf16 v[92:95], v[162:165], v[192:195], v[92:95]
	v_mfma_f32_16x16x32_bf16 v[88:91], v[176:179], v[192:195], v[88:91]
	v_mfma_f32_16x16x32_bf16 v[76:79], v[162:165], v[204:207], v[76:79]
	v_mfma_f32_16x16x32_bf16 v[72:75], v[176:179], v[204:207], v[72:75]
	v_mfma_f32_16x16x32_bf16 v[68:71], v[162:165], v[212:215], v[68:71]
	v_mfma_f32_16x16x32_bf16 v[64:67], v[176:179], v[212:215], v[64:67]
	v_mfma_f32_16x16x32_bf16 v[110:113], v[172:175], v[188:191], v[110:113]
	v_mfma_f32_16x16x32_bf16 v[106:109], v[180:183], v[188:191], v[106:109]
	v_mfma_f32_16x16x32_bf16 v[92:95], v[172:175], v[196:199], v[92:95]
	v_mfma_f32_16x16x32_bf16 v[88:91], v[180:183], v[196:199], v[88:91]
	v_mfma_f32_16x16x32_bf16 v[76:79], v[172:175], v[208:211], v[76:79]
	v_mfma_f32_16x16x32_bf16 v[72:75], v[180:183], v[208:211], v[72:75]
	v_mfma_f32_16x16x32_bf16 v[68:71], v[172:175], v[216:219], v[68:71]
	v_mfma_f32_16x16x32_bf16 v[64:67], v[180:183], v[216:219], v[64:67]
	s_barrier
	s_setprio 0
	s_add_i32 s52, s52, s35
	v_lshl_add_u64 v[200:201], s[24:25], 0, v[96:97]
	s_mov_b32 m0, s52
	ds_read_b128 v[184:187], v144 offset:16384
	ds_read_b128 v[188:191], v144 offset:17408
	ds_read_b128 v[192:195], v144 offset:18432
	ds_read_b128 v[196:199], v144 offset:19456
	ds_read_b128 v[204:207], v144 offset:20480
	ds_read_b128 v[208:211], v144 offset:21504
	ds_read_b128 v[212:215], v144 offset:22528
	ds_read_b128 v[216:219], v144 offset:23552
	global_load_lds_dwordx4 v[200:201], off
	s_add_i32 m0, s52, 0x2000
	s_add_u32 s62, s24, 0x80000
	v_lshl_add_u64 v[220:221], s[24:25], 0, v[134:135]
	s_addc_u32 s63, s25, 0
	s_add_i32 s52, s64, s35
	global_load_lds_dwordx4 v[220:221], off
	v_lshl_add_u64 v[222:223], s[62:63], 0, v[96:97]
	s_mov_b32 m0, s52
	v_lshl_add_u64 v[224:225], s[26:27], 0, v[132:133]
	global_load_lds_dwordx4 v[222:223], off
	v_lshl_add_u64 v[222:223], s[62:63], 0, v[134:135]
	s_add_i32 m0, s52, 0x2000
	s_nop 0
	global_load_lds_dwordx4 v[222:223], off
	v_lshl_add_u64 v[222:223], s[26:27], 0, v[130:131]
	s_mov_b32 m0, s13
	s_nop 0
	global_load_lds_dwordx4 v[222:223], off
	s_mov_b32 m0, s36
	s_nop 0
	global_load_lds_dwordx4 v[224:225], off
	s_waitcnt vmcnt(8)
	s_waitcnt lgkmcnt(0)
	s_setprio 1
	s_barrier
; #define PG8_STAGE(bufoff, gbase, voff) do { _Pragma("unroll") for (int _i = 0; _i < 2; ++_i) \
;         __builtin_amdgcn_global_load_lds((const unsigned*)((const char*)(gbase) + (voff)[_i]), (PG8_LAS unsigned*)(lds + (bufoff) + ldsw + _i * 8192), 16, 0, 0); } while (0)
; #define PG8_LDA(dst, b, h) do { _Pragma("unroll") for (int m = 0; m < 4; ++m) _Pragma("unroll") for (int k = 0; k < 2; ++k) dst[m][k] = *(const PG8_LAS bf16x8*)(lds + PG8_SA(b, h) + aoff + m * 2048 + k * 1024); } while (0)
; #define PG8_LDB(dst, b, h) do { _Pragma("unroll") for (int n = 0; n < 2; ++n) _Pragma("unroll") for (int k = 0; k < 2; ++k) dst[n][k] = *(const PG8_LAS bf16x8*)(lds + PG8_SB(b, h) + boff + n * 2048 + k * 1024); } while (0)
; #define PG8_MMA(ai, bj, At, Bt) do { __builtin_amdgcn_s_setprio(1); _Pragma("unroll") for (int m = 0; m < 4; ++m) _Pragma("unroll") for (int n = 0; n < 2; ++n) _Pragma("unroll") for (int k = 0; k < 2; ++k) \
;         acc[ai][bj][m][n] = __builtin_amdgcn_mfma_f32_16x16x32_bf16(Bt[n][k], At[m][k], acc[ai][bj][m][n], 0, 0, 0); __builtin_amdgcn_s_setprio(0); } while (0)
; #define PG8_WAIT_V(n) asm volatile("s_waitcnt vmcnt(" #n ")" ::: "memory")
; #define PG8_WAIT_L(n) asm volatile("s_waitcnt lgkmcnt(" #n ")" ::: "memory")
; #define PG8_BAR __builtin_amdgcn_s_barrier()
; #define PG8_SCHED __builtin_amdgcn_sched_barrier(0)
; template <class Epi, class Sched, bool ALIGN_EPI = false, bool SP2 = false>
; __device__ __forceinline__ void gemm_phase(PG8_LAS unsigned char* lds, const Gemm g, const Sched& S, const Epi& E, int tid_in) {
;     ...
;             PG8_WAIT_V(8); PG8_WAIT_L(0); PG8_BAR; PG8_MMA(1, 0, At, B0); PG8_MMA(1, 1, At, B1); PG8_BAR; PG8_SCHED;
;             PG8_LDB(B0, 1, 0); PG8_LDB(B1, 1, 1); PG8_SCHED; PG8_LDA(At, 1, 0); PG8_STAGE(PG8_SA(0, 1), a2 + hstep, voffA);
;             PG8_WAIT_V(8); PG8_WAIT_L(0); PG8_BAR; PG8_MMA(0, 0, At, B0); PG8_MMA(0, 1, At, B1); PG8_BAR; PG8_SCHED;
	v_mfma_f32_16x16x32_bf16 v[60:63], v[146:149], v[184:187], v[60:63]
	v_mfma_f32_16x16x32_bf16 v[56:59], v[154:157], v[184:187], v[56:59]
	v_mfma_f32_16x16x32_bf16 v[52:55], v[146:149], v[192:195], v[52:55]
	v_mfma_f32_16x16x32_bf16 v[48:51], v[154:157], v[192:195], v[48:51]
	v_mfma_f32_16x16x32_bf16 v[36:39], v[146:149], v[204:207], v[36:39]
	v_mfma_f32_16x16x32_bf16 v[32:35], v[154:157], v[204:207], v[32:35]
	v_mfma_f32_16x16x32_bf16 v[20:23], v[146:149], v[212:215], v[20:23]
	v_mfma_f32_16x16x32_bf16 v[16:19], v[154:157], v[212:215], v[16:19]
	v_mfma_f32_16x16x32_bf16 v[60:63], v[150:153], v[188:191], v[60:63]
	v_mfma_f32_16x16x32_bf16 v[56:59], v[158:161], v[188:191], v[56:59]
	v_mfma_f32_16x16x32_bf16 v[52:55], v[150:153], v[196:199], v[52:55]
	v_mfma_f32_16x16x32_bf16 v[48:51], v[158:161], v[196:199], v[48:51]
	v_mfma_f32_16x16x32_bf16 v[36:39], v[150:153], v[208:211], v[36:39]
	v_mfma_f32_16x16x32_bf16 v[32:35], v[158:161], v[208:211], v[32:35]
	v_mfma_f32_16x16x32_bf16 v[20:23], v[150:153], v[216:219], v[20:23]
	v_mfma_f32_16x16x32_bf16 v[16:19], v[158:161], v[216:219], v[16:19]
	s_setprio 0
	s_setprio 1
	v_mfma_f32_16x16x32_bf16 v[44:47], v[162:165], v[184:187], v[44:47]
	v_mfma_f32_16x16x32_bf16 v[40:43], v[176:179], v[184:187], v[40:43]
	v_mfma_f32_16x16x32_bf16 v[28:31], v[162:165], v[192:195], v[28:31]
	v_mfma_f32_16x16x32_bf16 v[24:27], v[176:179], v[192:195], v[24:27]
	v_mfma_f32_16x16x32_bf16 v[12:15], v[162:165], v[204:207], v[12:15]
	v_mfma_f32_16x16x32_bf16 v[8:11], v[176:179], v[204:207], v[8:11]
	v_mfma_f32_16x16x32_bf16 v[4:7], v[162:165], v[212:215], v[4:7]
	v_mfma_f32_16x16x32_bf16 v[0:3], v[176:179], v[212:215], v[0:3]
	v_mfma_f32_16x16x32_bf16 v[44:47], v[172:175], v[188:191], v[44:47]
	v_mfma_f32_16x16x32_bf16 v[40:43], v[180:183], v[188:191], v[40:43]
	v_mfma_f32_16x16x32_bf16 v[28:31], v[172:175], v[196:199], v[28:31]
	v_mfma_f32_16x16x32_bf16 v[24:27], v[180:183], v[196:199], v[24:27]
	v_mfma_f32_16x16x32_bf16 v[12:15], v[172:175], v[208:211], v[12:15]
	v_mfma_f32_16x16x32_bf16 v[8:11], v[180:183], v[208:211], v[8:11]
	v_mfma_f32_16x16x32_bf16 v[4:7], v[172:175], v[216:219], v[4:7]
	v_mfma_f32_16x16x32_bf16 v[0:3], v[180:183], v[216:219], v[0:3]
	s_barrier
	s_setprio 0
	s_add_i32 s52, 0, 0x18000
	v_add_u32_e32 v145, s52, v142
	s_add_i32 s62, 0, 0x1c000
	ds_read_b128 v[146:149], v145
	ds_read_b128 v[150:153], v145 offset:1024
	ds_read_b128 v[154:157], v145 offset:2048
	ds_read_b128 v[158:161], v145 offset:3072
	v_add_u32_e32 v145, s62, v142
	ds_read_b128 v[162:165], v145
	ds_read_b128 v[172:175], v145 offset:1024
	ds_read_b128 v[176:179], v145 offset:2048
	ds_read_b128 v[180:183], v145 offset:3072
	s_add_u32 s26, s26, 0x80000
	s_addc_u32 s27, s27, 0
	s_mov_b32 m0, s37
	v_lshl_add_u64 v[226:227], s[26:27], 0, v[130:131]
	ds_read_b128 v[184:187], v144 offset:32768
	ds_read_b128 v[188:191], v144 offset:33792
	ds_read_b128 v[192:195], v144 offset:34816
	ds_read_b128 v[196:199], v144 offset:35840
	ds_read_b128 v[204:207], v144 offset:36864
	ds_read_b128 v[208:211], v144 offset:37888
	ds_read_b128 v[212:215], v144 offset:38912
	ds_read_b128 v[216:219], v144 offset:39936
	global_load_lds_dwordx4 v[226:227], off
	v_lshl_add_u64 v[226:227], s[26:27], 0, v[132:133]
	s_mov_b32 m0, s38
	s_nop 0
	global_load_lds_dwordx4 v[226:227], off
	s_waitcnt vmcnt(8)
	s_waitcnt lgkmcnt(0)
	s_setprio 1
	s_barrier
	v_mfma_f32_16x16x32_bf16 v[126:129], v[146:149], v[184:187], v[126:129]
	v_mfma_f32_16x16x32_bf16 v[122:125], v[154:157], v[184:187], v[122:125]
	v_mfma_f32_16x16x32_bf16 v[118:121], v[146:149], v[192:195], v[118:121]
	v_mfma_f32_16x16x32_bf16 v[114:117], v[154:157], v[192:195], v[114:117]
	v_mfma_f32_16x16x32_bf16 v[102:105], v[146:149], v[204:207], v[102:105]
	v_mfma_f32_16x16x32_bf16 v[98:101], v[154:157], v[204:207], v[98:101]
	v_mfma_f32_16x16x32_bf16 v[84:87], v[146:149], v[212:215], v[84:87]
	v_mfma_f32_16x16x32_bf16 v[80:83], v[154:157], v[212:215], v[80:83]
	v_mfma_f32_16x16x32_bf16 v[126:129], v[150:153], v[188:191], v[126:129]
	v_mfma_f32_16x16x32_bf16 v[122:125], v[158:161], v[188:191], v[122:125]
	v_mfma_f32_16x16x32_bf16 v[118:121], v[150:153], v[196:199], v[118:121]
	v_mfma_f32_16x16x32_bf16 v[114:117], v[158:161], v[196:199], v[114:117]
	v_mfma_f32_16x16x32_bf16 v[102:105], v[150:153], v[208:211], v[102:105]
	v_mfma_f32_16x16x32_bf16 v[98:101], v[158:161], v[208:211], v[98:101]
	v_mfma_f32_16x16x32_bf16 v[84:87], v[150:153], v[216:219], v[84:87]
	v_mfma_f32_16x16x32_bf16 v[80:83], v[158:161], v[216:219], v[80:83]
	s_setprio 0
	s_setprio 1
	v_mfma_f32_16x16x32_bf16 v[110:113], v[162:165], v[184:187], v[110:113]
	v_mfma_f32_16x16x32_bf16 v[106:109], v[176:179], v[184:187], v[106:109]
	v_mfma_f32_16x16x32_bf16 v[92:95], v[162:165], v[192:195], v[92:95]
	v_mfma_f32_16x16x32_bf16 v[88:91], v[176:179], v[192:195], v[88:91]
	v_mfma_f32_16x16x32_bf16 v[76:79], v[162:165], v[204:207], v[76:79]
	v_mfma_f32_16x16x32_bf16 v[72:75], v[176:179], v[204:207], v[72:75]
	v_mfma_f32_16x16x32_bf16 v[68:71], v[162:165], v[212:215], v[68:71]
	v_mfma_f32_16x16x32_bf16 v[64:67], v[176:179], v[212:215], v[64:67]
	v_mfma_f32_16x16x32_bf16 v[110:113], v[172:175], v[188:191], v[110:113]
	v_mfma_f32_16x16x32_bf16 v[106:109], v[180:183], v[188:191], v[106:109]
	v_mfma_f32_16x16x32_bf16 v[92:95], v[172:175], v[196:199], v[92:95]
	v_mfma_f32_16x16x32_bf16 v[88:91], v[180:183], v[196:199], v[88:91]
	v_mfma_f32_16x16x32_bf16 v[76:79], v[172:175], v[208:211], v[76:79]
	v_mfma_f32_16x16x32_bf16 v[72:75], v[180:183], v[208:211], v[72:75]
	v_mfma_f32_16x16x32_bf16 v[68:71], v[172:175], v[216:219], v[68:71]
	v_mfma_f32_16x16x32_bf16 v[64:67], v[180:183], v[216:219], v[64:67]
	s_barrier
; #define PG8_STAGE(bufoff, gbase, voff) do { _Pragma("unroll") for (int _i = 0; _i < 2; ++_i) \
;         __builtin_amdgcn_global_load_lds((const unsigned*)((const char*)(gbase) + (voff)[_i]), (PG8_LAS unsigned*)(lds + (bufoff) + ldsw + _i * 8192), 16, 0, 0); } while (0)
; #define PG8_LDA(dst, b, h) do { _Pragma("unroll") for (int m = 0; m < 4; ++m) _Pragma("unroll") for (int k = 0; k < 2; ++k) dst[m][k] = *(const PG8_LAS bf16x8*)(lds + PG8_SA(b, h) + aoff + m * 2048 + k * 1024); } while (0)
; #define PG8_MMA(ai, bj, At, Bt) do { __builtin_amdgcn_s_setprio(1); _Pragma("unroll") for (int m = 0; m < 4; ++m) _Pragma("unroll") for (int n = 0; n < 2; ++n) _Pragma("unroll") for (int k = 0; k < 2; ++k) \
;         acc[ai][bj][m][n] = __builtin_amdgcn_mfma_f32_16x16x32_bf16(Bt[n][k], At[m][k], acc[ai][bj][m][n], 0, 0, 0); __builtin_amdgcn_s_setprio(0); } while (0)
; #define PG8_WAIT_V(n) asm volatile("s_waitcnt vmcnt(" #n ")" ::: "memory")
; #define PG8_WAIT_L(n) asm volatile("s_waitcnt lgkmcnt(" #n ")" ::: "memory")
; #define PG8_BAR __builtin_amdgcn_s_barrier()
; #define PG8_SCHED __builtin_amdgcn_sched_barrier(0)
; template <class Epi, class Sched, bool ALIGN_EPI = false, bool SP2 = false>
; __device__ __forceinline__ void gemm_phase(PG8_LAS unsigned char* lds, const Gemm g, const Sched& S, const Epi& E, int tid_in) {
;     ...
;             PG8_LDA(At, 1, 1); PG8_STAGE(PG8_SB(1, 0), b3, voffB); PG8_STAGE(PG8_SB(1, 1), b3 + hstep, voffB); PG8_STAGE(PG8_SA(1, 0), a3, voffA);
;             PG8_WAIT_V(8); PG8_WAIT_L(0); PG8_BAR; PG8_MMA(1, 0, At, B0); PG8_MMA(1, 1, At, B1); PG8_BAR; PG8_SCHED;
;     ...
;         if constexpr (ALIGN_EPI) { if (wr == 0) PG8_BAR; }
	s_setprio 0
	s_add_i32 s26, s52, s35
	v_lshl_add_u64 v[200:201], v[200:201], 0, s[88:89]
	s_mov_b32 m0, s26
	ds_read_b128 v[184:187], v144 offset:49152
	ds_read_b128 v[188:191], v144 offset:50176
	ds_read_b128 v[192:195], v144 offset:51200
	ds_read_b128 v[196:199], v144 offset:52224
	ds_read_b128 v[204:207], v144 offset:53248
	ds_read_b128 v[208:211], v144 offset:54272
	ds_read_b128 v[212:215], v144 offset:55296
	ds_read_b128 v[216:219], v144 offset:56320
	global_load_lds_dwordx4 v[200:201], off
	s_add_i32 m0, s26, 0x2000
	s_add_u32 s24, s24, 0x80080
	v_lshl_add_u64 v[200:201], v[220:221], 0, s[88:89]
	s_addc_u32 s25, s25, 0
	s_add_i32 s26, s62, s35
	global_load_lds_dwordx4 v[200:201], off
	v_lshl_add_u64 v[200:201], s[24:25], 0, v[96:97]
	s_mov_b32 m0, s26
	s_nop 0
	global_load_lds_dwordx4 v[200:201], off
	v_lshl_add_u64 v[200:201], s[24:25], 0, v[134:135]
	s_add_i32 m0, s26, 0x2000
	s_nop 0
	global_load_lds_dwordx4 v[200:201], off
	v_lshl_add_u64 v[200:201], v[222:223], 0, s[88:89]
	s_mov_b32 m0, s39
	s_nop 0
	global_load_lds_dwordx4 v[200:201], off
	v_lshl_add_u64 v[200:201], v[224:225], 0, s[88:89]
	s_mov_b32 m0, s40
	s_nop 0
	global_load_lds_dwordx4 v[200:201], off
	s_waitcnt vmcnt(8)
	s_waitcnt lgkmcnt(0)
	s_setprio 1
	s_barrier
	v_mfma_f32_16x16x32_bf16 v[60:63], v[146:149], v[184:187], v[60:63]
	v_mfma_f32_16x16x32_bf16 v[56:59], v[154:157], v[184:187], v[56:59]
	v_mfma_f32_16x16x32_bf16 v[52:55], v[146:149], v[192:195], v[52:55]
	v_mfma_f32_16x16x32_bf16 v[48:51], v[154:157], v[192:195], v[48:51]
	v_mfma_f32_16x16x32_bf16 v[36:39], v[146:149], v[204:207], v[36:39]
	v_mfma_f32_16x16x32_bf16 v[32:35], v[154:157], v[204:207], v[32:35]
	v_mfma_f32_16x16x32_bf16 v[20:23], v[146:149], v[212:215], v[20:23]
	v_mfma_f32_16x16x32_bf16 v[16:19], v[154:157], v[212:215], v[16:19]
	v_mfma_f32_16x16x32_bf16 v[60:63], v[150:153], v[188:191], v[60:63]
	v_mfma_f32_16x16x32_bf16 v[56:59], v[158:161], v[188:191], v[56:59]
	v_mfma_f32_16x16x32_bf16 v[52:55], v[150:153], v[196:199], v[52:55]
	v_mfma_f32_16x16x32_bf16 v[48:51], v[158:161], v[196:199], v[48:51]
	v_mfma_f32_16x16x32_bf16 v[36:39], v[150:153], v[208:211], v[36:39]
	v_mfma_f32_16x16x32_bf16 v[32:35], v[158:161], v[208:211], v[32:35]
	v_mfma_f32_16x16x32_bf16 v[20:23], v[150:153], v[216:219], v[20:23]
	v_mfma_f32_16x16x32_bf16 v[16:19], v[158:161], v[216:219], v[16:19]
	s_setprio 0
	s_setprio 1
	v_mfma_f32_16x16x32_bf16 v[44:47], v[162:165], v[184:187], v[44:47]
	v_mfma_f32_16x16x32_bf16 v[40:43], v[176:179], v[184:187], v[40:43]
	v_mfma_f32_16x16x32_bf16 v[28:31], v[162:165], v[192:195], v[28:31]
	v_mfma_f32_16x16x32_bf16 v[24:27], v[176:179], v[192:195], v[24:27]
	v_mfma_f32_16x16x32_bf16 v[12:15], v[162:165], v[204:207], v[12:15]
	v_mfma_f32_16x16x32_bf16 v[8:11], v[176:179], v[204:207], v[8:11]
	v_mfma_f32_16x16x32_bf16 v[4:7], v[162:165], v[212:215], v[4:7]
	v_mfma_f32_16x16x32_bf16 v[0:3], v[176:179], v[212:215], v[0:3]
	v_mfma_f32_16x16x32_bf16 v[44:47], v[172:175], v[188:191], v[44:47]
	v_mfma_f32_16x16x32_bf16 v[40:43], v[180:183], v[188:191], v[40:43]
	v_mfma_f32_16x16x32_bf16 v[28:31], v[172:175], v[196:199], v[28:31]
	v_mfma_f32_16x16x32_bf16 v[24:27], v[180:183], v[196:199], v[24:27]
	v_mfma_f32_16x16x32_bf16 v[12:15], v[172:175], v[208:211], v[12:15]
	v_mfma_f32_16x16x32_bf16 v[8:11], v[180:183], v[208:211], v[8:11]
	v_mfma_f32_16x16x32_bf16 v[4:7], v[172:175], v[216:219], v[4:7]
	v_mfma_f32_16x16x32_bf16 v[0:3], v[180:183], v[216:219], v[0:3]
	s_barrier
	s_setprio 0
	s_add_i32 s47, s47, 2
	s_add_u32 s22, s22, 0x100
	s_addc_u32 s23, s23, 0
	s_add_u32 s45, s45, 0x100
	s_addc_u32 s46, s46, 0
	s_cmp_gt_u32 s47, 29
	s_cbranch_scc0 .LBB0_749
	s_and_b64 vcc, exec, s[10:11]
	s_cbranch_vccz .LBB0_752
	s_barrier

; #define PG8_STAGE(bufoff, gbase, voff) do { _Pragma("unroll") for (int _i = 0; _i < 2; ++_i) \
;         __builtin_amdgcn_global_load_lds((const unsigned*)((const char*)(gbase) + (voff)[_i]), (PG8_LAS unsigned*)(lds + (bufoff) + ldsw + _i * 8192), 16, 0, 0); } while (0)
; #define PG8_LDA(dst, b, h) do { _Pragma("unroll") for (int m = 0; m < 4; ++m) _Pragma("unroll") for (int k = 0; k < 2; ++k) dst[m][k] = *(const PG8_LAS bf16x8*)(lds + PG8_SA(b, h) + aoff + m * 2048 + k * 1024); } while (0)
; #define PG8_LDB(dst, b, h) do { _Pragma("unroll") for (int n = 0; n < 2; ++n) _Pragma("unroll") for (int k = 0; k < 2; ++k) dst[n][k] = *(const PG8_LAS bf16x8*)(lds + PG8_SB(b, h) + boff + n * 2048 + k * 1024); } while (0)
; #define PG8_MMA(ai, bj, At, Bt) do { __builtin_amdgcn_s_setprio(1); _Pragma("unroll") for (int m = 0; m < 4; ++m) _Pragma("unroll") for (int n = 0; n < 2; ++n) _Pragma("unroll") for (int k = 0; k < 2; ++k) \
;         acc[ai][bj][m][n] = __builtin_amdgcn_mfma_f32_16x16x32_bf16(Bt[n][k], At[m][k], acc[ai][bj][m][n], 0, 0, 0); __builtin_amdgcn_s_setprio(0); } while (0)
; #define PG8_WAIT_V(n) asm volatile("s_waitcnt vmcnt(" #n ")" ::: "memory")
; #define PG8_WAIT_L(n) asm volatile("s_waitcnt lgkmcnt(" #n ")" ::: "memory")
; template <class Epi, class Sched, bool ALIGN_EPI = false, bool SP2 = false>
; __device__ __forceinline__ void gemm_phase(PG8_LAS unsigned char* lds, const Gemm g, const Sched& S, const Epi& E, int tid_in) {
;     ...
;             const bool last = (t == nt - 2);
;             const char* a1 = cA + (size_t)(t + 1) * kstep;
;             const char* a2 = last ? nA : cA + (size_t)(t + 2) * kstep; const char* b2 = last ? nB : cB + (size_t)(t + 2) * kstep;
;             const char* a3 = a2 + kstep; const char* b3 = b2 + kstep;
;             if (last && has_next) S.a_ready(nxt);
;             if constexpr (SP2) {
;             PG8_LDB(B0, 0, 0); PG8_LDB(B1, 0, 1); PG8_SCHED; PG8_LDA(At, 0, 0); PG8_STAGE(PG8_SA(1, 1), a1 + hstep, voffA);
;             PG8_WAIT_V(8); PG8_WAIT_L(0); PG8_BAR; PG8_MMA(0, 0, At, B0); PG8_MMA(0, 1, At, B1); PG8_BAR; PG8_SCHED;
;             PG8_LDA(At, 0, 1); PG8_STAGE(PG8_SB(0, 0), b2, voffB); PG8_STAGE(PG8_SB(0, 1), b2 + hstep, voffB); PG8_STAGE(PG8_SA(0, 0), a2, voffA);
;             PG8_WAIT_V(8); PG8_WAIT_L(0); PG8_BAR; PG8_MMA(1, 0, At, B0); PG8_MMA(1, 1, At, B1); PG8_BAR; PG8_SCHED;
.LBB0_979:
	s_add_u32 s26, s24, 0xfff80080
	s_addc_u32 s27, s25, -1
	s_add_i32 s62, 0, 0x10000
	s_cmp_eq_u32 s64, 28
	s_cselect_b32 s29, s17, s27
	s_cselect_b32 s28, s45, s26
	v_add_u32_e32 v140, s62, v144
	s_cselect_b32 s27, s15, s52
	s_cselect_b32 s26, s46, s47
	s_add_i32 s65, 0, 0x14000
	ds_read_b128 v[148:151], v140
	ds_read_b128 v[152:155], v140 offset:1024
	ds_read_b128 v[156:159], v140 offset:2048
	ds_read_b128 v[160:163], v140 offset:3072
	v_add_u32_e32 v140, s65, v144
	ds_read_b128 v[172:175], v140
	ds_read_b128 v[176:179], v140 offset:1024
	ds_read_b128 v[180:183], v140 offset:2048
	ds_read_b128 v[184:187], v140 offset:3072
	v_lshl_add_u64 v[140:141], s[24:25], 0, v[136:137]
	s_add_i32 m0, s38, 0xc000
	ds_read_b128 v[188:191], v146
	ds_read_b128 v[192:195], v146 offset:1024
	ds_read_b128 v[196:199], v146 offset:2048
	ds_read_b128 v[204:207], v146 offset:3072
	ds_read_b128 v[208:211], v146 offset:4096
	ds_read_b128 v[212:215], v146 offset:5120
	ds_read_b128 v[216:219], v146 offset:6144
	ds_read_b128 v[220:223], v146 offset:7168
	global_load_lds_dwordx4 v[140:141], off
	v_lshl_add_u64 v[140:141], s[24:25], 0, v[138:139]
	s_add_i32 m0, s38, 0xe000
	s_nop 0
	global_load_lds_dwordx4 v[140:141], off
	s_waitcnt vmcnt(8)
	s_waitcnt lgkmcnt(0)
	s_setprio 1
	s_barrier
	v_mfma_f32_16x16x32_bf16 v[126:129], v[148:151], v[188:191], v[126:129]
	v_mfma_f32_16x16x32_bf16 v[118:121], v[156:159], v[188:191], v[118:121]
	v_mfma_f32_16x16x32_bf16 v[110:113], v[148:151], v[196:199], v[110:113]
	v_mfma_f32_16x16x32_bf16 v[102:105], v[156:159], v[196:199], v[102:105]
	v_mfma_f32_16x16x32_bf16 v[92:95], v[148:151], v[208:211], v[92:95]
	v_mfma_f32_16x16x32_bf16 v[84:87], v[156:159], v[208:211], v[84:87]
	v_mfma_f32_16x16x32_bf16 v[76:79], v[148:151], v[216:219], v[76:79]
	v_mfma_f32_16x16x32_bf16 v[68:71], v[156:159], v[216:219], v[68:71]
	v_mfma_f32_16x16x32_bf16 v[126:129], v[152:155], v[192:195], v[126:129]
	v_mfma_f32_16x16x32_bf16 v[118:121], v[160:163], v[192:195], v[118:121]
	v_mfma_f32_16x16x32_bf16 v[110:113], v[152:155], v[204:207], v[110:113]
	v_mfma_f32_16x16x32_bf16 v[102:105], v[160:163], v[204:207], v[102:105]
	v_mfma_f32_16x16x32_bf16 v[92:95], v[152:155], v[212:215], v[92:95]
	v_mfma_f32_16x16x32_bf16 v[84:87], v[160:163], v[212:215], v[84:87]
	v_mfma_f32_16x16x32_bf16 v[76:79], v[152:155], v[220:223], v[76:79]
	v_mfma_f32_16x16x32_bf16 v[68:71], v[160:163], v[220:223], v[68:71]
	s_setprio 0
	s_setprio 1
	v_mfma_f32_16x16x32_bf16 v[122:125], v[172:175], v[188:191], v[122:125]
	v_mfma_f32_16x16x32_bf16 v[114:117], v[180:183], v[188:191], v[114:117]
	v_mfma_f32_16x16x32_bf16 v[106:109], v[172:175], v[196:199], v[106:109]
	v_mfma_f32_16x16x32_bf16 v[98:101], v[180:183], v[196:199], v[98:101]
	v_mfma_f32_16x16x32_bf16 v[88:91], v[172:175], v[208:211], v[88:91]
	v_mfma_f32_16x16x32_bf16 v[80:83], v[180:183], v[208:211], v[80:83]
	v_mfma_f32_16x16x32_bf16 v[72:75], v[172:175], v[216:219], v[72:75]
	v_mfma_f32_16x16x32_bf16 v[64:67], v[180:183], v[216:219], v[64:67]
	v_mfma_f32_16x16x32_bf16 v[122:125], v[176:179], v[192:195], v[122:125]
	v_mfma_f32_16x16x32_bf16 v[114:117], v[184:187], v[192:195], v[114:117]
	v_mfma_f32_16x16x32_bf16 v[106:109], v[176:179], v[204:207], v[106:109]
	v_mfma_f32_16x16x32_bf16 v[98:101], v[184:187], v[204:207], v[98:101]
	v_mfma_f32_16x16x32_bf16 v[88:91], v[176:179], v[212:215], v[88:91]
	v_mfma_f32_16x16x32_bf16 v[80:83], v[184:187], v[212:215], v[80:83]
	v_mfma_f32_16x16x32_bf16 v[72:75], v[176:179], v[220:223], v[72:75]
	v_mfma_f32_16x16x32_bf16 v[64:67], v[184:187], v[220:223], v[64:67]
	s_barrier
	s_setprio 0
	s_add_i32 s62, s62, s36
	v_lshl_add_u64 v[140:141], s[26:27], 0, v[96:97]
	s_mov_b32 m0, s62
	ds_read_b128 v[188:191], v146 offset:16384
	ds_read_b128 v[192:195], v146 offset:17408
	ds_read_b128 v[196:199], v146 offset:18432
	ds_read_b128 v[204:207], v146 offset:19456
	ds_read_b128 v[208:211], v146 offset:20480
	ds_read_b128 v[212:215], v146 offset:21504
	ds_read_b128 v[216:219], v146 offset:22528
	ds_read_b128 v[220:223], v146 offset:23552
	global_load_lds_dwordx4 v[140:141], off
	s_add_i32 m0, s62, 0x2000
	s_add_u32 s62, s26, 0x80000
	v_lshl_add_u64 v[164:165], s[26:27], 0, v[130:131]
	s_addc_u32 s63, s27, 0
	s_add_i32 s65, s65, s36
	global_load_lds_dwordx4 v[164:165], off
	v_lshl_add_u64 v[200:201], s[62:63], 0, v[96:97]
	s_mov_b32 m0, s65
	v_lshl_add_u64 v[224:225], s[28:29], 0, v[132:133]
	global_load_lds_dwordx4 v[200:201], off
	v_lshl_add_u64 v[200:201], s[62:63], 0, v[130:131]
	s_add_i32 m0, s65, 0x2000
	s_nop 0
	global_load_lds_dwordx4 v[200:201], off
	v_lshl_add_u64 v[200:201], s[28:29], 0, v[134:135]
	s_mov_b32 m0, s38
	s_nop 0
	global_load_lds_dwordx4 v[200:201], off
	s_mov_b32 m0, s39
	s_nop 0
	global_load_lds_dwordx4 v[224:225], off
	s_waitcnt vmcnt(8)
	s_waitcnt lgkmcnt(0)
	s_setprio 1
	s_barrier
; #define PG8_STAGE(bufoff, gbase, voff) do { _Pragma("unroll") for (int _i = 0; _i < 2; ++_i) \
;         __builtin_amdgcn_global_load_lds((const unsigned*)((const char*)(gbase) + (voff)[_i]), (PG8_LAS unsigned*)(lds + (bufoff) + ldsw + _i * 8192), 16, 0, 0); } while (0)
; #define PG8_LDA(dst, b, h) do { _Pragma("unroll") for (int m = 0; m < 4; ++m) _Pragma("unroll") for (int k = 0; k < 2; ++k) dst[m][k] = *(const PG8_LAS bf16x8*)(lds + PG8_SA(b, h) + aoff + m * 2048 + k * 1024); } while (0)
; #define PG8_LDB(dst, b, h) do { _Pragma("unroll") for (int n = 0; n < 2; ++n) _Pragma("unroll") for (int k = 0; k < 2; ++k) dst[n][k] = *(const PG8_LAS bf16x8*)(lds + PG8_SB(b, h) + boff + n * 2048 + k * 1024); } while (0)
; #define PG8_MMA(ai, bj, At, Bt) do { __builtin_amdgcn_s_setprio(1); _Pragma("unroll") for (int m = 0; m < 4; ++m) _Pragma("unroll") for (int n = 0; n < 2; ++n) _Pragma("unroll") for (int k = 0; k < 2; ++k) \
;         acc[ai][bj][m][n] = __builtin_amdgcn_mfma_f32_16x16x32_bf16(Bt[n][k], At[m][k], acc[ai][bj][m][n], 0, 0, 0); __builtin_amdgcn_s_setprio(0); } while (0)
; #define PG8_WAIT_V(n) asm volatile("s_waitcnt vmcnt(" #n ")" ::: "memory")
; #define PG8_WAIT_L(n) asm volatile("s_waitcnt lgkmcnt(" #n ")" ::: "memory")
; #define PG8_BAR __builtin_amdgcn_s_barrier()
; #define PG8_SCHED __builtin_amdgcn_sched_barrier(0)
; template <class Epi, class Sched, bool ALIGN_EPI = false, bool SP2 = false>
; __device__ __forceinline__ void gemm_phase(PG8_LAS unsigned char* lds, const Gemm g, const Sched& S, const Epi& E, int tid_in) {
;     ...
;             PG8_WAIT_V(8); PG8_WAIT_L(0); PG8_BAR; PG8_MMA(1, 0, At, B0); PG8_MMA(1, 1, At, B1); PG8_BAR; PG8_SCHED;
;             PG8_LDB(B0, 1, 0); PG8_LDB(B1, 1, 1); PG8_SCHED; PG8_LDA(At, 1, 0); PG8_STAGE(PG8_SA(0, 1), a2 + hstep, voffA);
;             PG8_WAIT_V(8); PG8_WAIT_L(0); PG8_BAR; PG8_MMA(0, 0, At, B0); PG8_MMA(0, 1, At, B1); PG8_BAR; PG8_SCHED;
	v_mfma_f32_16x16x32_bf16 v[60:63], v[148:151], v[188:191], v[60:63]
	v_mfma_f32_16x16x32_bf16 v[52:55], v[156:159], v[188:191], v[52:55]
	v_mfma_f32_16x16x32_bf16 v[44:47], v[148:151], v[196:199], v[44:47]
	v_mfma_f32_16x16x32_bf16 v[36:39], v[156:159], v[196:199], v[36:39]
	v_mfma_f32_16x16x32_bf16 v[28:31], v[148:151], v[208:211], v[28:31]
	v_mfma_f32_16x16x32_bf16 v[20:23], v[156:159], v[208:211], v[20:23]
	v_mfma_f32_16x16x32_bf16 v[12:15], v[148:151], v[216:219], v[12:15]
	v_mfma_f32_16x16x32_bf16 v[4:7], v[156:159], v[216:219], v[4:7]
	v_mfma_f32_16x16x32_bf16 v[60:63], v[152:155], v[192:195], v[60:63]
	v_mfma_f32_16x16x32_bf16 v[52:55], v[160:163], v[192:195], v[52:55]
	v_mfma_f32_16x16x32_bf16 v[44:47], v[152:155], v[204:207], v[44:47]
	v_mfma_f32_16x16x32_bf16 v[36:39], v[160:163], v[204:207], v[36:39]
	v_mfma_f32_16x16x32_bf16 v[28:31], v[152:155], v[212:215], v[28:31]
	v_mfma_f32_16x16x32_bf16 v[20:23], v[160:163], v[212:215], v[20:23]
	v_mfma_f32_16x16x32_bf16 v[12:15], v[152:155], v[220:223], v[12:15]
	v_mfma_f32_16x16x32_bf16 v[4:7], v[160:163], v[220:223], v[4:7]
	s_setprio 0
	s_setprio 1
	v_mfma_f32_16x16x32_bf16 v[56:59], v[172:175], v[188:191], v[56:59]
	v_mfma_f32_16x16x32_bf16 v[48:51], v[180:183], v[188:191], v[48:51]
	v_mfma_f32_16x16x32_bf16 v[40:43], v[172:175], v[196:199], v[40:43]
	v_mfma_f32_16x16x32_bf16 v[32:35], v[180:183], v[196:199], v[32:35]
	v_mfma_f32_16x16x32_bf16 v[24:27], v[172:175], v[208:211], v[24:27]
	v_mfma_f32_16x16x32_bf16 v[16:19], v[180:183], v[208:211], v[16:19]
	v_mfma_f32_16x16x32_bf16 v[8:11], v[172:175], v[216:219], v[8:11]
	v_mfma_f32_16x16x32_bf16 v[0:3], v[180:183], v[216:219], v[0:3]
	v_mfma_f32_16x16x32_bf16 v[56:59], v[176:179], v[192:195], v[56:59]
	v_mfma_f32_16x16x32_bf16 v[48:51], v[184:187], v[192:195], v[48:51]
	v_mfma_f32_16x16x32_bf16 v[40:43], v[176:179], v[204:207], v[40:43]
	v_mfma_f32_16x16x32_bf16 v[32:35], v[184:187], v[204:207], v[32:35]
	v_mfma_f32_16x16x32_bf16 v[24:27], v[176:179], v[212:215], v[24:27]
	v_mfma_f32_16x16x32_bf16 v[16:19], v[184:187], v[212:215], v[16:19]
	v_mfma_f32_16x16x32_bf16 v[8:11], v[176:179], v[220:223], v[8:11]
	v_mfma_f32_16x16x32_bf16 v[0:3], v[184:187], v[220:223], v[0:3]
	s_barrier
	s_setprio 0
	s_add_i32 s62, 0, 0x18000
	v_add_u32_e32 v147, s62, v144
	s_add_i32 s63, 0, 0x1c000
	ds_read_b128 v[148:151], v147
	ds_read_b128 v[152:155], v147 offset:1024
	ds_read_b128 v[156:159], v147 offset:2048
	ds_read_b128 v[160:163], v147 offset:3072
	v_add_u32_e32 v147, s63, v144
	ds_read_b128 v[172:175], v147
	ds_read_b128 v[176:179], v147 offset:1024
	ds_read_b128 v[180:183], v147 offset:2048
	ds_read_b128 v[184:187], v147 offset:3072
	s_add_u32 s28, s28, 0x80000
	s_addc_u32 s29, s29, 0
	s_mov_b32 m0, s40
	v_lshl_add_u64 v[226:227], s[28:29], 0, v[134:135]
	ds_read_b128 v[188:191], v146 offset:32768
	ds_read_b128 v[192:195], v146 offset:33792
	ds_read_b128 v[196:199], v146 offset:34816
	ds_read_b128 v[204:207], v146 offset:35840
	ds_read_b128 v[208:211], v146 offset:36864
	ds_read_b128 v[212:215], v146 offset:37888
	ds_read_b128 v[216:219], v146 offset:38912
	ds_read_b128 v[220:223], v146 offset:39936
	global_load_lds_dwordx4 v[226:227], off
	v_lshl_add_u64 v[226:227], s[28:29], 0, v[132:133]
	s_mov_b32 m0, s41
	s_nop 0
	global_load_lds_dwordx4 v[226:227], off
	s_waitcnt vmcnt(8)
	s_waitcnt lgkmcnt(0)
	s_setprio 1
	s_barrier
	v_mfma_f32_16x16x32_bf16 v[126:129], v[148:151], v[188:191], v[126:129]
	v_mfma_f32_16x16x32_bf16 v[118:121], v[156:159], v[188:191], v[118:121]
	v_mfma_f32_16x16x32_bf16 v[110:113], v[148:151], v[196:199], v[110:113]
	v_mfma_f32_16x16x32_bf16 v[102:105], v[156:159], v[196:199], v[102:105]
	v_mfma_f32_16x16x32_bf16 v[92:95], v[148:151], v[208:211], v[92:95]
	v_mfma_f32_16x16x32_bf16 v[84:87], v[156:159], v[208:211], v[84:87]
	v_mfma_f32_16x16x32_bf16 v[76:79], v[148:151], v[216:219], v[76:79]
	v_mfma_f32_16x16x32_bf16 v[68:71], v[156:159], v[216:219], v[68:71]
	v_mfma_f32_16x16x32_bf16 v[126:129], v[152:155], v[192:195], v[126:129]
	v_mfma_f32_16x16x32_bf16 v[118:121], v[160:163], v[192:195], v[118:121]
	v_mfma_f32_16x16x32_bf16 v[110:113], v[152:155], v[204:207], v[110:113]
	v_mfma_f32_16x16x32_bf16 v[102:105], v[160:163], v[204:207], v[102:105]
	v_mfma_f32_16x16x32_bf16 v[92:95], v[152:155], v[212:215], v[92:95]
	v_mfma_f32_16x16x32_bf16 v[84:87], v[160:163], v[212:215], v[84:87]
	v_mfma_f32_16x16x32_bf16 v[76:79], v[152:155], v[220:223], v[76:79]
	v_mfma_f32_16x16x32_bf16 v[68:71], v[160:163], v[220:223], v[68:71]
	s_setprio 0
	s_setprio 1
	v_mfma_f32_16x16x32_bf16 v[122:125], v[172:175], v[188:191], v[122:125]
	v_mfma_f32_16x16x32_bf16 v[114:117], v[180:183], v[188:191], v[114:117]
	v_mfma_f32_16x16x32_bf16 v[106:109], v[172:175], v[196:199], v[106:109]
	v_mfma_f32_16x16x32_bf16 v[98:101], v[180:183], v[196:199], v[98:101]
	v_mfma_f32_16x16x32_bf16 v[88:91], v[172:175], v[208:211], v[88:91]
	v_mfma_f32_16x16x32_bf16 v[80:83], v[180:183], v[208:211], v[80:83]
	v_mfma_f32_16x16x32_bf16 v[72:75], v[172:175], v[216:219], v[72:75]
	v_mfma_f32_16x16x32_bf16 v[64:67], v[180:183], v[216:219], v[64:67]
	v_mfma_f32_16x16x32_bf16 v[122:125], v[176:179], v[192:195], v[122:125]
	v_mfma_f32_16x16x32_bf16 v[114:117], v[184:187], v[192:195], v[114:117]
	v_mfma_f32_16x16x32_bf16 v[106:109], v[176:179], v[204:207], v[106:109]
	v_mfma_f32_16x16x32_bf16 v[98:101], v[184:187], v[204:207], v[98:101]
	v_mfma_f32_16x16x32_bf16 v[88:91], v[176:179], v[212:215], v[88:91]
	v_mfma_f32_16x16x32_bf16 v[80:83], v[184:187], v[212:215], v[80:83]
	v_mfma_f32_16x16x32_bf16 v[72:75], v[176:179], v[220:223], v[72:75]
	v_mfma_f32_16x16x32_bf16 v[64:67], v[184:187], v[220:223], v[64:67]
	s_barrier
; #define PG8_STAGE(bufoff, gbase, voff) do { _Pragma("unroll") for (int _i = 0; _i < 2; ++_i) \
;         __builtin_amdgcn_global_load_lds((const unsigned*)((const char*)(gbase) + (voff)[_i]), (PG8_LAS unsigned*)(lds + (bufoff) + ldsw + _i * 8192), 16, 0, 0); } while (0)
; #define PG8_LDA(dst, b, h) do { _Pragma("unroll") for (int m = 0; m < 4; ++m) _Pragma("unroll") for (int k = 0; k < 2; ++k) dst[m][k] = *(const PG8_LAS bf16x8*)(lds + PG8_SA(b, h) + aoff + m * 2048 + k * 1024); } while (0)
; #define PG8_MMA(ai, bj, At, Bt) do { __builtin_amdgcn_s_setprio(1); _Pragma("unroll") for (int m = 0; m < 4; ++m) _Pragma("unroll") for (int n = 0; n < 2; ++n) _Pragma("unroll") for (int k = 0; k < 2; ++k) \
;         acc[ai][bj][m][n] = __builtin_amdgcn_mfma_f32_16x16x32_bf16(Bt[n][k], At[m][k], acc[ai][bj][m][n], 0, 0, 0); __builtin_amdgcn_s_setprio(0); } while (0)
; #define PG8_WAIT_V(n) asm volatile("s_waitcnt vmcnt(" #n ")" ::: "memory")
; #define PG8_WAIT_L(n) asm volatile("s_waitcnt lgkmcnt(" #n ")" ::: "memory")
; #define PG8_BAR __builtin_amdgcn_s_barrier()
; #define PG8_SCHED __builtin_amdgcn_sched_barrier(0)
; template <class Epi, class Sched, bool ALIGN_EPI = false, bool SP2 = false>
; __device__ __forceinline__ void gemm_phase(PG8_LAS unsigned char* lds, const Gemm g, const Sched& S, const Epi& E, int tid_in) {
;     ...
;             PG8_LDA(At, 1, 1); PG8_STAGE(PG8_SB(1, 0), b3, voffB); PG8_STAGE(PG8_SB(1, 1), b3 + hstep, voffB); PG8_STAGE(PG8_SA(1, 0), a3, voffA);
;             PG8_WAIT_V(8); PG8_WAIT_L(0); PG8_BAR; PG8_MMA(1, 0, At, B0); PG8_MMA(1, 1, At, B1); PG8_BAR; PG8_SCHED;
;     ...
;         if constexpr (ALIGN_EPI) { if (wr == 0) PG8_BAR; }
	s_setprio 0
	s_add_i32 s28, s62, s36
	v_lshl_add_u64 v[140:141], v[140:141], 0, s[88:89]
	s_mov_b32 m0, s28
	ds_read_b128 v[188:191], v146 offset:49152
	ds_read_b128 v[192:195], v146 offset:50176
	ds_read_b128 v[196:199], v146 offset:51200
	ds_read_b128 v[204:207], v146 offset:52224
	ds_read_b128 v[208:211], v146 offset:53248
	ds_read_b128 v[212:215], v146 offset:54272
	ds_read_b128 v[216:219], v146 offset:55296
	ds_read_b128 v[220:223], v146 offset:56320
	global_load_lds_dwordx4 v[140:141], off
	s_add_i32 m0, s28, 0x2000
	s_add_u32 s26, s26, 0x80080
	v_lshl_add_u64 v[140:141], v[164:165], 0, s[88:89]
	s_addc_u32 s27, s27, 0
	s_add_i32 s28, s63, s36
	global_load_lds_dwordx4 v[140:141], off
	v_lshl_add_u64 v[140:141], s[26:27], 0, v[96:97]
	s_mov_b32 m0, s28
	s_nop 0
	global_load_lds_dwordx4 v[140:141], off
	v_lshl_add_u64 v[140:141], s[26:27], 0, v[130:131]
	s_add_i32 m0, s28, 0x2000
	s_nop 0
	global_load_lds_dwordx4 v[140:141], off
	v_lshl_add_u64 v[140:141], v[200:201], 0, s[88:89]
	s_mov_b32 m0, s42
	s_nop 0
	global_load_lds_dwordx4 v[140:141], off
	v_lshl_add_u64 v[140:141], v[224:225], 0, s[88:89]
	s_mov_b32 m0, s43
	s_nop 0
	global_load_lds_dwordx4 v[140:141], off
	s_waitcnt vmcnt(8)
	s_waitcnt lgkmcnt(0)
	s_setprio 1
	s_barrier
	v_mfma_f32_16x16x32_bf16 v[60:63], v[148:151], v[188:191], v[60:63]
	v_mfma_f32_16x16x32_bf16 v[52:55], v[156:159], v[188:191], v[52:55]
	v_mfma_f32_16x16x32_bf16 v[44:47], v[148:151], v[196:199], v[44:47]
	v_mfma_f32_16x16x32_bf16 v[36:39], v[156:159], v[196:199], v[36:39]
	v_mfma_f32_16x16x32_bf16 v[28:31], v[148:151], v[208:211], v[28:31]
	v_mfma_f32_16x16x32_bf16 v[20:23], v[156:159], v[208:211], v[20:23]
	v_mfma_f32_16x16x32_bf16 v[12:15], v[148:151], v[216:219], v[12:15]
	v_mfma_f32_16x16x32_bf16 v[4:7], v[156:159], v[216:219], v[4:7]
	v_mfma_f32_16x16x32_bf16 v[60:63], v[152:155], v[192:195], v[60:63]
	v_mfma_f32_16x16x32_bf16 v[52:55], v[160:163], v[192:195], v[52:55]
	v_mfma_f32_16x16x32_bf16 v[44:47], v[152:155], v[204:207], v[44:47]
	v_mfma_f32_16x16x32_bf16 v[36:39], v[160:163], v[204:207], v[36:39]
	v_mfma_f32_16x16x32_bf16 v[28:31], v[152:155], v[212:215], v[28:31]
	v_mfma_f32_16x16x32_bf16 v[20:23], v[160:163], v[212:215], v[20:23]
	v_mfma_f32_16x16x32_bf16 v[12:15], v[152:155], v[220:223], v[12:15]
	v_mfma_f32_16x16x32_bf16 v[4:7], v[160:163], v[220:223], v[4:7]
	s_setprio 0
	s_setprio 1
	v_mfma_f32_16x16x32_bf16 v[56:59], v[172:175], v[188:191], v[56:59]
	v_mfma_f32_16x16x32_bf16 v[48:51], v[180:183], v[188:191], v[48:51]
	v_mfma_f32_16x16x32_bf16 v[40:43], v[172:175], v[196:199], v[40:43]
	v_mfma_f32_16x16x32_bf16 v[32:35], v[180:183], v[196:199], v[32:35]
	v_mfma_f32_16x16x32_bf16 v[24:27], v[172:175], v[208:211], v[24:27]
	v_mfma_f32_16x16x32_bf16 v[16:19], v[180:183], v[208:211], v[16:19]
	v_mfma_f32_16x16x32_bf16 v[8:11], v[172:175], v[216:219], v[8:11]
	v_mfma_f32_16x16x32_bf16 v[0:3], v[180:183], v[216:219], v[0:3]
	v_mfma_f32_16x16x32_bf16 v[56:59], v[176:179], v[192:195], v[56:59]
	v_mfma_f32_16x16x32_bf16 v[48:51], v[184:187], v[192:195], v[48:51]
	v_mfma_f32_16x16x32_bf16 v[40:43], v[176:179], v[204:207], v[40:43]
	v_mfma_f32_16x16x32_bf16 v[32:35], v[184:187], v[204:207], v[32:35]
	v_mfma_f32_16x16x32_bf16 v[24:27], v[176:179], v[212:215], v[24:27]
	v_mfma_f32_16x16x32_bf16 v[16:19], v[184:187], v[212:215], v[16:19]
	v_mfma_f32_16x16x32_bf16 v[8:11], v[176:179], v[220:223], v[8:11]
	v_mfma_f32_16x16x32_bf16 v[0:3], v[184:187], v[220:223], v[0:3]
	s_barrier
	s_setprio 0
	s_add_i32 s64, s64, 2
	s_add_u32 s24, s24, 0x100
	s_addc_u32 s25, s25, 0
	s_add_u32 s47, s47, 0x100
	s_addc_u32 s52, s52, 0
	s_cmp_gt_u32 s64, 29
	s_cbranch_scc0 .LBB0_979
	s_and_b64 vcc, exec, s[12:13]
	s_cbranch_vccz .LBB0_982
	s_barrier

; #define PG8_STAGE(bufoff, gbase, voff) do { _Pragma("unroll") for (int _i = 0; _i < 2; ++_i) \
;         __builtin_amdgcn_global_load_lds((const unsigned*)((const char*)(gbase) + (voff)[_i]), (PG8_LAS unsigned*)(lds + (bufoff) + ldsw + _i * 8192), 16, 0, 0); } while (0)
; #define PG8_LDA(dst, b, h) do { _Pragma("unroll") for (int m = 0; m < 4; ++m) _Pragma("unroll") for (int k = 0; k < 2; ++k) dst[m][k] = *(const PG8_LAS bf16x8*)(lds + PG8_SA(b, h) + aoff + m * 2048 + k * 1024); } while (0)
; #define PG8_LDB(dst, b, h) do { _Pragma("unroll") for (int n = 0; n < 2; ++n) _Pragma("unroll") for (int k = 0; k < 2; ++k) dst[n][k] = *(const PG8_LAS bf16x8*)(lds + PG8_SB(b, h) + boff + n * 2048 + k * 1024); } while (0)
; #define PG8_MMA(ai, bj, At, Bt) do { __builtin_amdgcn_s_setprio(1); _Pragma("unroll") for (int m = 0; m < 4; ++m) _Pragma("unroll") for (int n = 0; n < 2; ++n) _Pragma("unroll") for (int k = 0; k < 2; ++k) \
;         acc[ai][bj][m][n] = __builtin_amdgcn_mfma_f32_16x16x32_bf16(Bt[n][k], At[m][k], acc[ai][bj][m][n], 0, 0, 0); __builtin_amdgcn_s_setprio(0); } while (0)
; #define PG8_WAIT_V(n) asm volatile("s_waitcnt vmcnt(" #n ")" ::: "memory")
; #define PG8_WAIT_L(n) asm volatile("s_waitcnt lgkmcnt(" #n ")" ::: "memory")
; template <class Epi, class Sched, bool ALIGN_EPI = false, bool SP2 = false>
; __device__ __forceinline__ void gemm_phase(PG8_LAS unsigned char* lds, const Gemm g, const Sched& S, const Epi& E, int tid_in) {
;     ...
;             const bool last = (t == nt - 2);
;             const char* a1 = cA + (size_t)(t + 1) * kstep;
;             const char* a2 = last ? nA : cA + (size_t)(t + 2) * kstep; const char* b2 = last ? nB : cB + (size_t)(t + 2) * kstep;
;             const char* a3 = a2 + kstep; const char* b3 = b2 + kstep;
;             if (last && has_next) S.a_ready(nxt);
;             if constexpr (SP2) {
;             PG8_LDB(B0, 0, 0); PG8_LDB(B1, 0, 1); PG8_SCHED; PG8_LDA(At, 0, 0); PG8_STAGE(PG8_SA(1, 1), a1 + hstep, voffA);
;             PG8_WAIT_V(8); PG8_WAIT_L(0); PG8_BAR; PG8_MMA(0, 0, At, B0); PG8_MMA(0, 1, At, B1); PG8_BAR; PG8_SCHED;
;             PG8_LDA(At, 0, 1); PG8_STAGE(PG8_SB(0, 0), b2, voffB); PG8_STAGE(PG8_SB(0, 1), b2 + hstep, voffB); PG8_STAGE(PG8_SA(0, 0), a2, voffA);
;             PG8_WAIT_V(8); PG8_WAIT_L(0); PG8_BAR; PG8_MMA(1, 0, At, B0); PG8_MMA(1, 1, At, B1); PG8_BAR; PG8_SCHED;
.LBB0_1100:
	s_add_u32 s20, s18, 0x100
	s_addc_u32 s21, s19, 0
	s_add_i32 s52, 0, 0x10000
	s_cmpk_eq_i32 s47, 0x54
	s_cselect_b32 s25, s3, s21
	s_cselect_b32 s24, s2, s20
	v_add_u32_e32 v145, s52, v142
	s_cselect_b32 s23, s17, s46
	s_cselect_b32 s22, s16, s45
	s_add_i32 s62, 0, 0x14000
	ds_read_b128 v[146:149], v145
	ds_read_b128 v[150:153], v145 offset:1024
	ds_read_b128 v[154:157], v145 offset:2048
	ds_read_b128 v[158:161], v145 offset:3072
	v_add_u32_e32 v145, s62, v142
	ds_read_b128 v[162:165], v145
	ds_read_b128 v[172:175], v145 offset:1024
	ds_read_b128 v[176:179], v145 offset:2048
	ds_read_b128 v[180:183], v145 offset:3072
	v_lshl_add_u64 v[200:201], s[18:19], 0, v[136:137]
	s_add_i32 m0, s34, 0xc000
	ds_read_b128 v[184:187], v144
	ds_read_b128 v[188:191], v144 offset:1024
	ds_read_b128 v[192:195], v144 offset:2048
	ds_read_b128 v[196:199], v144 offset:3072
	ds_read_b128 v[204:207], v144 offset:4096
	ds_read_b128 v[208:211], v144 offset:5120
	ds_read_b128 v[212:215], v144 offset:6144
	ds_read_b128 v[216:219], v144 offset:7168
	global_load_lds_dwordx4 v[200:201], off
	v_lshl_add_u64 v[200:201], s[18:19], 0, v[138:139]
	s_add_i32 m0, s34, 0xe000
	s_nop 0
	global_load_lds_dwordx4 v[200:201], off
	s_waitcnt vmcnt(8)
	s_waitcnt lgkmcnt(0)
	s_setprio 1
	s_barrier
	v_mfma_f32_16x16x32_bf16 v[126:129], v[146:149], v[184:187], v[126:129]
	v_mfma_f32_16x16x32_bf16 v[122:125], v[154:157], v[184:187], v[122:125]
	v_mfma_f32_16x16x32_bf16 v[118:121], v[146:149], v[192:195], v[118:121]
	v_mfma_f32_16x16x32_bf16 v[114:117], v[154:157], v[192:195], v[114:117]
	v_mfma_f32_16x16x32_bf16 v[102:105], v[146:149], v[204:207], v[102:105]
	v_mfma_f32_16x16x32_bf16 v[98:101], v[154:157], v[204:207], v[98:101]
	v_mfma_f32_16x16x32_bf16 v[84:87], v[146:149], v[212:215], v[84:87]
	v_mfma_f32_16x16x32_bf16 v[80:83], v[154:157], v[212:215], v[80:83]
	v_mfma_f32_16x16x32_bf16 v[126:129], v[150:153], v[188:191], v[126:129]
	v_mfma_f32_16x16x32_bf16 v[122:125], v[158:161], v[188:191], v[122:125]
	v_mfma_f32_16x16x32_bf16 v[118:121], v[150:153], v[196:199], v[118:121]
	v_mfma_f32_16x16x32_bf16 v[114:117], v[158:161], v[196:199], v[114:117]
	v_mfma_f32_16x16x32_bf16 v[102:105], v[150:153], v[208:211], v[102:105]
	v_mfma_f32_16x16x32_bf16 v[98:101], v[158:161], v[208:211], v[98:101]
	v_mfma_f32_16x16x32_bf16 v[84:87], v[150:153], v[216:219], v[84:87]
	v_mfma_f32_16x16x32_bf16 v[80:83], v[158:161], v[216:219], v[80:83]
	s_setprio 0
	s_setprio 1
	v_mfma_f32_16x16x32_bf16 v[110:113], v[162:165], v[184:187], v[110:113]
	v_mfma_f32_16x16x32_bf16 v[106:109], v[176:179], v[184:187], v[106:109]
	v_mfma_f32_16x16x32_bf16 v[92:95], v[162:165], v[192:195], v[92:95]
	v_mfma_f32_16x16x32_bf16 v[88:91], v[176:179], v[192:195], v[88:91]
	v_mfma_f32_16x16x32_bf16 v[76:79], v[162:165], v[204:207], v[76:79]
	v_mfma_f32_16x16x32_bf16 v[72:75], v[176:179], v[204:207], v[72:75]
	v_mfma_f32_16x16x32_bf16 v[68:71], v[162:165], v[212:215], v[68:71]
	v_mfma_f32_16x16x32_bf16 v[64:67], v[176:179], v[212:215], v[64:67]
	v_mfma_f32_16x16x32_bf16 v[110:113], v[172:175], v[188:191], v[110:113]
	v_mfma_f32_16x16x32_bf16 v[106:109], v[180:183], v[188:191], v[106:109]
	v_mfma_f32_16x16x32_bf16 v[92:95], v[172:175], v[196:199], v[92:95]
	v_mfma_f32_16x16x32_bf16 v[88:91], v[180:183], v[196:199], v[88:91]
	v_mfma_f32_16x16x32_bf16 v[76:79], v[172:175], v[208:211], v[76:79]
	v_mfma_f32_16x16x32_bf16 v[72:75], v[180:183], v[208:211], v[72:75]
	v_mfma_f32_16x16x32_bf16 v[68:71], v[172:175], v[216:219], v[68:71]
	v_mfma_f32_16x16x32_bf16 v[64:67], v[180:183], v[216:219], v[64:67]
	s_barrier
	s_setprio 0
	s_add_i32 s18, s52, s31
	v_lshl_add_u64 v[200:201], s[22:23], 0, v[96:97]
	s_mov_b32 m0, s18
	ds_read_b128 v[184:187], v144 offset:16384
	ds_read_b128 v[188:191], v144 offset:17408
	ds_read_b128 v[192:195], v144 offset:18432
	ds_read_b128 v[196:199], v144 offset:19456
	ds_read_b128 v[204:207], v144 offset:20480
	ds_read_b128 v[208:211], v144 offset:21504
	ds_read_b128 v[212:215], v144 offset:22528
	ds_read_b128 v[216:219], v144 offset:23552
	global_load_lds_dwordx4 v[200:201], off
	s_add_i32 m0, s18, 0x2000
	s_add_u32 s18, s22, 0x160000
	v_lshl_add_u64 v[220:221], s[22:23], 0, v[134:135]
	s_addc_u32 s19, s23, 0
	s_add_i32 s52, s62, s31
	global_load_lds_dwordx4 v[220:221], off
	v_lshl_add_u64 v[222:223], s[18:19], 0, v[96:97]
	s_mov_b32 m0, s52
	v_lshl_add_u64 v[224:225], s[24:25], 0, v[132:133]
	global_load_lds_dwordx4 v[222:223], off
	v_lshl_add_u64 v[222:223], s[18:19], 0, v[134:135]
	s_add_i32 m0, s52, 0x2000
	s_nop 0
	global_load_lds_dwordx4 v[222:223], off
	v_lshl_add_u64 v[222:223], s[24:25], 0, v[130:131]
	s_mov_b32 m0, s34
	s_nop 0
	global_load_lds_dwordx4 v[222:223], off
	s_mov_b32 m0, s35
	s_nop 0
	global_load_lds_dwordx4 v[224:225], off
	s_waitcnt vmcnt(8)
	s_waitcnt lgkmcnt(0)
	s_setprio 1
	s_barrier
; #define PG8_STAGE(bufoff, gbase, voff) do { _Pragma("unroll") for (int _i = 0; _i < 2; ++_i) \
;         __builtin_amdgcn_global_load_lds((const unsigned*)((const char*)(gbase) + (voff)[_i]), (PG8_LAS unsigned*)(lds + (bufoff) + ldsw + _i * 8192), 16, 0, 0); } while (0)
; #define PG8_LDA(dst, b, h) do { _Pragma("unroll") for (int m = 0; m < 4; ++m) _Pragma("unroll") for (int k = 0; k < 2; ++k) dst[m][k] = *(const PG8_LAS bf16x8*)(lds + PG8_SA(b, h) + aoff + m * 2048 + k * 1024); } while (0)
; #define PG8_LDB(dst, b, h) do { _Pragma("unroll") for (int n = 0; n < 2; ++n) _Pragma("unroll") for (int k = 0; k < 2; ++k) dst[n][k] = *(const PG8_LAS bf16x8*)(lds + PG8_SB(b, h) + boff + n * 2048 + k * 1024); } while (0)
; #define PG8_MMA(ai, bj, At, Bt) do { __builtin_amdgcn_s_setprio(1); _Pragma("unroll") for (int m = 0; m < 4; ++m) _Pragma("unroll") for (int n = 0; n < 2; ++n) _Pragma("unroll") for (int k = 0; k < 2; ++k) \
;         acc[ai][bj][m][n] = __builtin_amdgcn_mfma_f32_16x16x32_bf16(Bt[n][k], At[m][k], acc[ai][bj][m][n], 0, 0, 0); __builtin_amdgcn_s_setprio(0); } while (0)
; #define PG8_WAIT_V(n) asm volatile("s_waitcnt vmcnt(" #n ")" ::: "memory")
; #define PG8_WAIT_L(n) asm volatile("s_waitcnt lgkmcnt(" #n ")" ::: "memory")
; #define PG8_BAR __builtin_amdgcn_s_barrier()
; #define PG8_SCHED __builtin_amdgcn_sched_barrier(0)
; template <class Epi, class Sched, bool ALIGN_EPI = false, bool SP2 = false>
; __device__ __forceinline__ void gemm_phase(PG8_LAS unsigned char* lds, const Gemm g, const Sched& S, const Epi& E, int tid_in) {
;     ...
;             PG8_WAIT_V(8); PG8_WAIT_L(0); PG8_BAR; PG8_MMA(1, 0, At, B0); PG8_MMA(1, 1, At, B1); PG8_BAR; PG8_SCHED;
;             PG8_LDB(B0, 1, 0); PG8_LDB(B1, 1, 1); PG8_SCHED; PG8_LDA(At, 1, 0); PG8_STAGE(PG8_SA(0, 1), a2 + hstep, voffA);
;             PG8_WAIT_V(8); PG8_WAIT_L(0); PG8_BAR; PG8_MMA(0, 0, At, B0); PG8_MMA(0, 1, At, B1); PG8_BAR; PG8_SCHED;
	v_mfma_f32_16x16x32_bf16 v[60:63], v[146:149], v[184:187], v[60:63]
	v_mfma_f32_16x16x32_bf16 v[56:59], v[154:157], v[184:187], v[56:59]
	v_mfma_f32_16x16x32_bf16 v[52:55], v[146:149], v[192:195], v[52:55]
	v_mfma_f32_16x16x32_bf16 v[48:51], v[154:157], v[192:195], v[48:51]
	v_mfma_f32_16x16x32_bf16 v[36:39], v[146:149], v[204:207], v[36:39]
	v_mfma_f32_16x16x32_bf16 v[32:35], v[154:157], v[204:207], v[32:35]
	v_mfma_f32_16x16x32_bf16 v[20:23], v[146:149], v[212:215], v[20:23]
	v_mfma_f32_16x16x32_bf16 v[16:19], v[154:157], v[212:215], v[16:19]
	v_mfma_f32_16x16x32_bf16 v[60:63], v[150:153], v[188:191], v[60:63]
	v_mfma_f32_16x16x32_bf16 v[56:59], v[158:161], v[188:191], v[56:59]
	v_mfma_f32_16x16x32_bf16 v[52:55], v[150:153], v[196:199], v[52:55]
	v_mfma_f32_16x16x32_bf16 v[48:51], v[158:161], v[196:199], v[48:51]
	v_mfma_f32_16x16x32_bf16 v[36:39], v[150:153], v[208:211], v[36:39]
	v_mfma_f32_16x16x32_bf16 v[32:35], v[158:161], v[208:211], v[32:35]
	v_mfma_f32_16x16x32_bf16 v[20:23], v[150:153], v[216:219], v[20:23]
	v_mfma_f32_16x16x32_bf16 v[16:19], v[158:161], v[216:219], v[16:19]
	s_setprio 0
	s_setprio 1
	v_mfma_f32_16x16x32_bf16 v[44:47], v[162:165], v[184:187], v[44:47]
	v_mfma_f32_16x16x32_bf16 v[40:43], v[176:179], v[184:187], v[40:43]
	v_mfma_f32_16x16x32_bf16 v[28:31], v[162:165], v[192:195], v[28:31]
	v_mfma_f32_16x16x32_bf16 v[24:27], v[176:179], v[192:195], v[24:27]
	v_mfma_f32_16x16x32_bf16 v[12:15], v[162:165], v[204:207], v[12:15]
	v_mfma_f32_16x16x32_bf16 v[8:11], v[176:179], v[204:207], v[8:11]
	v_mfma_f32_16x16x32_bf16 v[4:7], v[162:165], v[212:215], v[4:7]
	v_mfma_f32_16x16x32_bf16 v[0:3], v[176:179], v[212:215], v[0:3]
	v_mfma_f32_16x16x32_bf16 v[44:47], v[172:175], v[188:191], v[44:47]
	v_mfma_f32_16x16x32_bf16 v[40:43], v[180:183], v[188:191], v[40:43]
	v_mfma_f32_16x16x32_bf16 v[28:31], v[172:175], v[196:199], v[28:31]
	v_mfma_f32_16x16x32_bf16 v[24:27], v[180:183], v[196:199], v[24:27]
	v_mfma_f32_16x16x32_bf16 v[12:15], v[172:175], v[208:211], v[12:15]
	v_mfma_f32_16x16x32_bf16 v[8:11], v[180:183], v[208:211], v[8:11]
	v_mfma_f32_16x16x32_bf16 v[4:7], v[172:175], v[216:219], v[4:7]
	v_mfma_f32_16x16x32_bf16 v[0:3], v[180:183], v[216:219], v[0:3]
	s_barrier
	s_setprio 0
	s_add_i32 s52, 0, 0x18000
	v_add_u32_e32 v145, s52, v142
	s_add_i32 s62, 0, 0x1c000
	ds_read_b128 v[146:149], v145
	ds_read_b128 v[150:153], v145 offset:1024
	ds_read_b128 v[154:157], v145 offset:2048
	ds_read_b128 v[158:161], v145 offset:3072
	v_add_u32_e32 v145, s62, v142
	ds_read_b128 v[162:165], v145
	ds_read_b128 v[172:175], v145 offset:1024
	ds_read_b128 v[176:179], v145 offset:2048
	ds_read_b128 v[180:183], v145 offset:3072
	s_add_u32 s18, s24, 0x160000
	s_addc_u32 s19, s25, 0
	s_mov_b32 m0, s36
	v_lshl_add_u64 v[226:227], s[18:19], 0, v[130:131]
	ds_read_b128 v[184:187], v144 offset:32768
	ds_read_b128 v[188:191], v144 offset:33792
	ds_read_b128 v[192:195], v144 offset:34816
	ds_read_b128 v[196:199], v144 offset:35840
	ds_read_b128 v[204:207], v144 offset:36864
	ds_read_b128 v[208:211], v144 offset:37888
	ds_read_b128 v[212:215], v144 offset:38912
	ds_read_b128 v[216:219], v144 offset:39936
	global_load_lds_dwordx4 v[226:227], off
	v_lshl_add_u64 v[226:227], s[18:19], 0, v[132:133]
	s_mov_b32 m0, s37
	s_nop 0
	global_load_lds_dwordx4 v[226:227], off
	s_waitcnt vmcnt(8)
	s_waitcnt lgkmcnt(0)
	s_setprio 1
	s_barrier
	v_mfma_f32_16x16x32_bf16 v[126:129], v[146:149], v[184:187], v[126:129]
	v_mfma_f32_16x16x32_bf16 v[122:125], v[154:157], v[184:187], v[122:125]
	v_mfma_f32_16x16x32_bf16 v[118:121], v[146:149], v[192:195], v[118:121]
	v_mfma_f32_16x16x32_bf16 v[114:117], v[154:157], v[192:195], v[114:117]
	v_mfma_f32_16x16x32_bf16 v[102:105], v[146:149], v[204:207], v[102:105]
	v_mfma_f32_16x16x32_bf16 v[98:101], v[154:157], v[204:207], v[98:101]
	v_mfma_f32_16x16x32_bf16 v[84:87], v[146:149], v[212:215], v[84:87]
	v_mfma_f32_16x16x32_bf16 v[80:83], v[154:157], v[212:215], v[80:83]
	v_mfma_f32_16x16x32_bf16 v[126:129], v[150:153], v[188:191], v[126:129]
	v_mfma_f32_16x16x32_bf16 v[122:125], v[158:161], v[188:191], v[122:125]
	v_mfma_f32_16x16x32_bf16 v[118:121], v[150:153], v[196:199], v[118:121]
	v_mfma_f32_16x16x32_bf16 v[114:117], v[158:161], v[196:199], v[114:117]
	v_mfma_f32_16x16x32_bf16 v[102:105], v[150:153], v[208:211], v[102:105]
	v_mfma_f32_16x16x32_bf16 v[98:101], v[158:161], v[208:211], v[98:101]
	v_mfma_f32_16x16x32_bf16 v[84:87], v[150:153], v[216:219], v[84:87]
	v_mfma_f32_16x16x32_bf16 v[80:83], v[158:161], v[216:219], v[80:83]
	s_setprio 0
	s_setprio 1
	v_mfma_f32_16x16x32_bf16 v[110:113], v[162:165], v[184:187], v[110:113]
	v_mfma_f32_16x16x32_bf16 v[106:109], v[176:179], v[184:187], v[106:109]
	v_mfma_f32_16x16x32_bf16 v[92:95], v[162:165], v[192:195], v[92:95]
	v_mfma_f32_16x16x32_bf16 v[88:91], v[176:179], v[192:195], v[88:91]
	v_mfma_f32_16x16x32_bf16 v[76:79], v[162:165], v[204:207], v[76:79]
	v_mfma_f32_16x16x32_bf16 v[72:75], v[176:179], v[204:207], v[72:75]
	v_mfma_f32_16x16x32_bf16 v[68:71], v[162:165], v[212:215], v[68:71]
	v_mfma_f32_16x16x32_bf16 v[64:67], v[176:179], v[212:215], v[64:67]
	v_mfma_f32_16x16x32_bf16 v[110:113], v[172:175], v[188:191], v[110:113]
	v_mfma_f32_16x16x32_bf16 v[106:109], v[180:183], v[188:191], v[106:109]
	v_mfma_f32_16x16x32_bf16 v[92:95], v[172:175], v[196:199], v[92:95]
	v_mfma_f32_16x16x32_bf16 v[88:91], v[180:183], v[196:199], v[88:91]
	v_mfma_f32_16x16x32_bf16 v[76:79], v[172:175], v[208:211], v[76:79]
	v_mfma_f32_16x16x32_bf16 v[72:75], v[180:183], v[208:211], v[72:75]
	v_mfma_f32_16x16x32_bf16 v[68:71], v[172:175], v[216:219], v[68:71]
	v_mfma_f32_16x16x32_bf16 v[64:67], v[180:183], v[216:219], v[64:67]
	s_barrier
; #define PG8_STAGE(bufoff, gbase, voff) do { _Pragma("unroll") for (int _i = 0; _i < 2; ++_i) \
;         __builtin_amdgcn_global_load_lds((const unsigned*)((const char*)(gbase) + (voff)[_i]), (PG8_LAS unsigned*)(lds + (bufoff) + ldsw + _i * 8192), 16, 0, 0); } while (0)
; #define PG8_LDA(dst, b, h) do { _Pragma("unroll") for (int m = 0; m < 4; ++m) _Pragma("unroll") for (int k = 0; k < 2; ++k) dst[m][k] = *(const PG8_LAS bf16x8*)(lds + PG8_SA(b, h) + aoff + m * 2048 + k * 1024); } while (0)
; #define PG8_MMA(ai, bj, At, Bt) do { __builtin_amdgcn_s_setprio(1); _Pragma("unroll") for (int m = 0; m < 4; ++m) _Pragma("unroll") for (int n = 0; n < 2; ++n) _Pragma("unroll") for (int k = 0; k < 2; ++k) \
;         acc[ai][bj][m][n] = __builtin_amdgcn_mfma_f32_16x16x32_bf16(Bt[n][k], At[m][k], acc[ai][bj][m][n], 0, 0, 0); __builtin_amdgcn_s_setprio(0); } while (0)
; #define PG8_WAIT_V(n) asm volatile("s_waitcnt vmcnt(" #n ")" ::: "memory")
; #define PG8_WAIT_L(n) asm volatile("s_waitcnt lgkmcnt(" #n ")" ::: "memory")
; #define PG8_BAR __builtin_amdgcn_s_barrier()
; #define PG8_SCHED __builtin_amdgcn_sched_barrier(0)
; template <class Epi, class Sched, bool ALIGN_EPI = false, bool SP2 = false>
; __device__ __forceinline__ void gemm_phase(PG8_LAS unsigned char* lds, const Gemm g, const Sched& S, const Epi& E, int tid_in) {
;     ...
;             PG8_LDA(At, 1, 1); PG8_STAGE(PG8_SB(1, 0), b3, voffB); PG8_STAGE(PG8_SB(1, 1), b3 + hstep, voffB); PG8_STAGE(PG8_SA(1, 0), a3, voffA);
;             PG8_WAIT_V(8); PG8_WAIT_L(0); PG8_BAR; PG8_MMA(1, 0, At, B0); PG8_MMA(1, 1, At, B1); PG8_BAR; PG8_SCHED;
;     ...
;         if constexpr (ALIGN_EPI) { if (wr == 0) PG8_BAR; }
	s_setprio 0
	s_add_i32 s18, s52, s31
	v_lshl_add_u64 v[200:201], v[200:201], 0, s[88:89]
	s_mov_b32 m0, s18
	ds_read_b128 v[184:187], v144 offset:49152
	ds_read_b128 v[188:191], v144 offset:50176
	ds_read_b128 v[192:195], v144 offset:51200
	ds_read_b128 v[196:199], v144 offset:52224
	ds_read_b128 v[204:207], v144 offset:53248
	ds_read_b128 v[208:211], v144 offset:54272
	ds_read_b128 v[212:215], v144 offset:55296
	ds_read_b128 v[216:219], v144 offset:56320
	global_load_lds_dwordx4 v[200:201], off
	s_add_i32 m0, s18, 0x2000
	s_add_u32 s18, s22, 0x160080
	v_lshl_add_u64 v[200:201], v[220:221], 0, s[88:89]
	s_addc_u32 s19, s23, 0
	s_add_i32 s22, s62, s31
	global_load_lds_dwordx4 v[200:201], off
	v_lshl_add_u64 v[200:201], s[18:19], 0, v[96:97]
	s_mov_b32 m0, s22
	s_nop 0
	global_load_lds_dwordx4 v[200:201], off
	v_lshl_add_u64 v[200:201], s[18:19], 0, v[134:135]
	s_add_i32 m0, s22, 0x2000
	s_nop 0
	global_load_lds_dwordx4 v[200:201], off
	v_lshl_add_u64 v[200:201], v[222:223], 0, s[88:89]
	s_mov_b32 m0, s38
	s_nop 0
	global_load_lds_dwordx4 v[200:201], off
	v_lshl_add_u64 v[200:201], v[224:225], 0, s[88:89]
	s_mov_b32 m0, s39
	s_nop 0
	global_load_lds_dwordx4 v[200:201], off
	s_waitcnt vmcnt(8)
	s_waitcnt lgkmcnt(0)
	s_setprio 1
	s_barrier
	v_mfma_f32_16x16x32_bf16 v[60:63], v[146:149], v[184:187], v[60:63]
	v_mfma_f32_16x16x32_bf16 v[56:59], v[154:157], v[184:187], v[56:59]
	v_mfma_f32_16x16x32_bf16 v[52:55], v[146:149], v[192:195], v[52:55]
	v_mfma_f32_16x16x32_bf16 v[48:51], v[154:157], v[192:195], v[48:51]
	v_mfma_f32_16x16x32_bf16 v[36:39], v[146:149], v[204:207], v[36:39]
	v_mfma_f32_16x16x32_bf16 v[32:35], v[154:157], v[204:207], v[32:35]
	v_mfma_f32_16x16x32_bf16 v[20:23], v[146:149], v[212:215], v[20:23]
	v_mfma_f32_16x16x32_bf16 v[16:19], v[154:157], v[212:215], v[16:19]
	v_mfma_f32_16x16x32_bf16 v[60:63], v[150:153], v[188:191], v[60:63]
	v_mfma_f32_16x16x32_bf16 v[56:59], v[158:161], v[188:191], v[56:59]
	v_mfma_f32_16x16x32_bf16 v[52:55], v[150:153], v[196:199], v[52:55]
	v_mfma_f32_16x16x32_bf16 v[48:51], v[158:161], v[196:199], v[48:51]
	v_mfma_f32_16x16x32_bf16 v[36:39], v[150:153], v[208:211], v[36:39]
	v_mfma_f32_16x16x32_bf16 v[32:35], v[158:161], v[208:211], v[32:35]
	v_mfma_f32_16x16x32_bf16 v[20:23], v[150:153], v[216:219], v[20:23]
	v_mfma_f32_16x16x32_bf16 v[16:19], v[158:161], v[216:219], v[16:19]
	s_setprio 0
	s_setprio 1
	v_mfma_f32_16x16x32_bf16 v[44:47], v[162:165], v[184:187], v[44:47]
	v_mfma_f32_16x16x32_bf16 v[40:43], v[176:179], v[184:187], v[40:43]
	v_mfma_f32_16x16x32_bf16 v[28:31], v[162:165], v[192:195], v[28:31]
	v_mfma_f32_16x16x32_bf16 v[24:27], v[176:179], v[192:195], v[24:27]
	v_mfma_f32_16x16x32_bf16 v[12:15], v[162:165], v[204:207], v[12:15]
	v_mfma_f32_16x16x32_bf16 v[8:11], v[176:179], v[204:207], v[8:11]
	v_mfma_f32_16x16x32_bf16 v[4:7], v[162:165], v[212:215], v[4:7]
	v_mfma_f32_16x16x32_bf16 v[0:3], v[176:179], v[212:215], v[0:3]
	v_mfma_f32_16x16x32_bf16 v[44:47], v[172:175], v[188:191], v[44:47]
	v_mfma_f32_16x16x32_bf16 v[40:43], v[180:183], v[188:191], v[40:43]
	v_mfma_f32_16x16x32_bf16 v[28:31], v[172:175], v[196:199], v[28:31]
	v_mfma_f32_16x16x32_bf16 v[24:27], v[180:183], v[196:199], v[24:27]
	v_mfma_f32_16x16x32_bf16 v[12:15], v[172:175], v[208:211], v[12:15]
	v_mfma_f32_16x16x32_bf16 v[8:11], v[180:183], v[208:211], v[8:11]
	v_mfma_f32_16x16x32_bf16 v[4:7], v[172:175], v[216:219], v[4:7]
	v_mfma_f32_16x16x32_bf16 v[0:3], v[180:183], v[216:219], v[0:3]
	s_barrier
	s_setprio 0
	s_add_i32 s47, s47, 2
	s_add_u32 s45, s45, 0x100
	s_addc_u32 s46, s46, 0
	s_cmpk_gt_u32 s47, 0x55
	s_mov_b64 s[18:19], s[20:21]
	s_cbranch_scc0 .LBB0_1100
	s_and_b64 vcc, exec, s[14:15]
	s_cbranch_vccz .LBB0_1103
	s_barrier
